# PEER pass U: rows consumed in pairs behind counted vmcnt, refills issued right after use (no vmcnt(0) per token-slice)
# baseline (speedup 1.0000x reference)
; #define LAS __attribute__((address_space(3)))
; __device__ __forceinline__ void p8_peer_gather(Frame& F) {
;     ...
;     int acc[9][16];
; #pragma unroll
;     for (int q = 0; q < 9; ++q)
; #pragma unroll
;         for (int i = 0; i < 16; ++i) acc[q][i] = 0;
;     ...
;     { const int tsl = lane >> 4, pc = lane & 15;
; #pragma unroll
;       for (int r = 0; r < 3; ++r) { const int q = 4 * r + tsl; const int j = q < 8 ? wave + 8 * q : 64;
;           __builtin_amdgcn_global_load_lds((const unsigned*)(X1Q + ((size_t)F.bid + 256 * j) * DM + 16 * pc), (LAS unsigned*)(xs_base + 1024 * r), 16, 0, 0); } }
;     v4u d[16];
;     { const unsigned uo0 = sub * 16;
; #pragma unroll
;       for (int g = 0; g < 4; ++g) { const v4u iv = *(const v4u*)(idx_s + wave * 128 + pg * 16 + 4 * g);
;           d[4 * g] = *(const v4u*)(UQ + (size_t)(iv.x + uo0)); d[4 * g + 1] = *(const v4u*)(UQ + (size_t)(iv.y + uo0)); d[4 * g + 2] = *(const v4u*)(UQ + (size_t)(iv.z + uo0)); d[4 * g + 3] = *(const v4u*)(UQ + (size_t)(iv.w + uo0)); } }
.LBB0_1752:
	s_or_b64 exec, exec, s[4:5]
	v_readlane_b32 s8, v253, 32
	v_readlane_b32 s10, v253, 34
	s_mul_i32 s2, s74, 0x1800
	v_readlane_b32 s11, v253, 35
	s_add_u32 s4, s10, 0x37600000
	v_and_b32_e32 v80, 0xf0, v4
	v_mov_b32_e32 v81, 0
	s_addc_u32 s5, s11, 0
	s_add_i32 s6, s2, 0
	s_waitcnt vmcnt(0)
	v_lshl_add_u64 v[0:1], s[10:11], 0, v[80:81]
	s_mov_b64 s[2:3], 0x12e00000
	v_lshl_add_u64 v[82:83], v[0:1], 0, s[2:3]
	v_lshlrev_b32_e32 v0, 7, v88
	v_and_b32_e32 v0, 0x1800, v0
	s_lshl_b32 s34, s74, 8
	v_add_u32_e32 v0, s34, v0
	v_ashrrev_i32_e32 v1, 31, v0
	v_lshl_add_u64 v[2:3], v[0:1], 0, s[72:73]
	v_add_u32_e32 v0, 0x2000, v0
	v_ashrrev_i32_e32 v1, 31, v0
	s_add_i32 s33, s6, 0x11400
	v_lshlrev_b64 v[84:85], 12, v[2:3]
	v_lshl_add_u64 v[0:1], v[0:1], 0, s[72:73]
	v_readlane_b32 s9, v253, 33
	v_lshl_add_u64 v[2:3], v[82:83], 0, v[84:85]
	s_mov_b32 m0, s33
	v_lshlrev_b64 v[86:87], 12, v[0:1]
	s_waitcnt lgkmcnt(0)
	s_barrier
	global_load_lds_dwordx4 v[2:3], off
	v_lshl_add_u64 v[0:1], v[82:83], 0, v[86:87]
	s_add_i32 m0, s6, 0x11800
	s_lshl_b64 s[8:9], s[72:73], 12
	v_bfe_u32 v5, v88, 3, 3
	global_load_lds_dwordx4 v[0:1], off
	v_lshl_add_u64 v[0:1], v[82:83], 0, s[8:9]
	s_mov_b64 s[10:11], 0x4000000
	s_lshl_b32 s2, s74, 9
	v_lshl_add_u64 v[0:1], v[0:1], 0, s[10:11]
	s_add_i32 m0, s6, 0x11c00
	s_add_i32 s3, s2, 0
	v_lshlrev_b32_e32 v64, 6, v5
	global_load_lds_dwordx4 v[0:1], off
	v_add_u32_e32 v80, s3, v64
	ds_read_b128 v[0:3], v80
	ds_read_b128 v[6:9], v80 offset:16
	ds_read_b128 v[14:17], v80 offset:32
	ds_read_b128 v[22:25], v80 offset:48
	v_and_b32_e32 v234, 7, v88
	v_lshlrev_b32_e32 v93, 4, v234
	v_lshlrev_b32_e32 v235, 4, v5
	s_waitcnt lgkmcnt(0)
	v_add_u32_e32 v0, v0, v93
	v_add_u32_e32 v1, v1, v93
	v_add_u32_e32 v4, v2, v93
	v_add_u32_e32 v5, v3, v93
	v_add_u32_e32 v10, v6, v93
	v_add_u32_e32 v11, v7, v93
	v_add_u32_e32 v12, v8, v93
	v_add_u32_e32 v13, v9, v93
	v_add_u32_e32 v18, v14, v93
	v_add_u32_e32 v19, v15, v93
	v_add_u32_e32 v20, v16, v93
	v_add_u32_e32 v21, v17, v93
	v_add_u32_e32 v26, v22, v93
	v_add_u32_e32 v27, v23, v93
	v_add_u32_e32 v65, v24, v93
	global_load_dwordx4 v[44:47], v0, s[4:5]
	global_load_dwordx4 v[28:31], v1, s[4:5]
	global_load_dwordx4 v[32:35], v4, s[4:5]
	s_nop 0
	global_load_dwordx4 v[0:3], v5, s[4:5]
	global_load_dwordx4 v[36:39], v10, s[4:5]
	s_nop 0
	global_load_dwordx4 v[4:7], v11, s[4:5]
	global_load_dwordx4 v[40:43], v12, s[4:5]
	s_nop 0
	global_load_dwordx4 v[8:11], v13, s[4:5]
	global_load_dwordx4 v[48:51], v18, s[4:5]
	s_nop 0
	global_load_dwordx4 v[12:15], v19, s[4:5]
	global_load_dwordx4 v[52:55], v20, s[4:5]
	s_nop 0
	global_load_dwordx4 v[16:19], v21, s[4:5]
	global_load_dwordx4 v[56:59], v26, s[4:5]
	s_nop 0
	global_load_dwordx4 v[20:23], v27, s[4:5]
	v_add_u32_e32 v66, v25, v93
	global_load_dwordx4 v[60:63], v65, s[4:5]
	global_load_dwordx4 v[24:27], v66, s[4:5]
	s_lshl_b32 s35, s74, 7
	s_cmpk_lt_u32 s75, 0x1040
	s_cselect_b64 s[12:13], -1, 0
	s_cmpk_lt_u32 s75, 0xe40
	s_cselect_b64 s[14:15], -1, 0
	s_cmpk_lt_u32 s75, 0xc40
	s_cselect_b64 s[16:17], -1, 0
	s_cmpk_lt_u32 s75, 0xa40
	s_cselect_b64 s[18:19], -1, 0
	s_cmpk_lt_u32 s75, 0x840
	s_cselect_b64 s[20:21], -1, 0
	s_cmpk_lt_u32 s75, 0x640
	s_cselect_b64 s[22:23], -1, 0
	s_cmpk_lt_u32 s75, 0x440
	s_cselect_b64 s[24:25], -1, 0
	s_add_i32 s36, s35, 0x1c00
	v_lshlrev_b32_e32 v90, 5, v234
	v_add_u32_e32 v94, 0, v64
	s_cmpk_lt_u32 s75, 0x240
	v_and_b32_e32 v92, 63, v88
	s_mov_b32 s7, 0
	v_add_u32_e32 v237, s33, v90
	v_add_u32_e32 v238, s2, v94
	s_movk_i32 s37, 0x100
	s_cselect_b64 s[26:27], -1, 0
	s_mov_b32 s39, 0
	v_mov_b32_e32 v91, v81
	v_mov_b32_e32 v95, v81
	v_mov_b32_e32 v96, v81
	v_mov_b32_e32 v97, v81
	v_mov_b32_e32 v98, v81
	v_mov_b32_e32 v99, v81
	v_mov_b32_e32 v100, v81
	v_mov_b32_e32 v101, v81
	v_mov_b32_e32 v102, v81
	v_mov_b32_e32 v103, v81
	v_mov_b32_e32 v104, v81
	v_mov_b32_e32 v105, v81
	v_mov_b32_e32 v106, v81
	v_mov_b32_e32 v107, v81
	v_mov_b32_e32 v108, v81
	v_mov_b32_e32 v109, v81
	v_mov_b32_e32 v110, v81
	v_mov_b32_e32 v111, v81
	v_mov_b32_e32 v112, v81
	v_mov_b32_e32 v113, v81
	v_mov_b32_e32 v114, v81
	v_mov_b32_e32 v115, v81
	v_mov_b32_e32 v116, v81
	v_mov_b32_e32 v117, v81
	v_mov_b32_e32 v118, v81
	v_mov_b32_e32 v119, v81
	v_mov_b32_e32 v120, v81
	v_mov_b32_e32 v121, v81
	v_mov_b32_e32 v122, v81
	v_mov_b32_e32 v123, v81
	v_mov_b32_e32 v124, v81
	v_mov_b32_e32 v125, v81
	v_mov_b32_e32 v126, v81
	v_mov_b32_e32 v127, v81
	v_mov_b32_e32 v128, v81
	v_mov_b32_e32 v129, v81
	v_mov_b32_e32 v130, v81
	v_mov_b32_e32 v131, v81
	v_mov_b32_e32 v132, v81
	v_mov_b32_e32 v133, v81
	v_mov_b32_e32 v134, v81
	v_mov_b32_e32 v135, v81
	v_mov_b32_e32 v136, v81
	v_mov_b32_e32 v137, v81
	v_mov_b32_e32 v138, v81
	v_mov_b32_e32 v139, v81
	v_mov_b32_e32 v140, v81
	v_mov_b32_e32 v141, v81
	v_mov_b32_e32 v142, v81
	v_mov_b32_e32 v143, v81
	v_mov_b32_e32 v144, v81
	v_mov_b32_e32 v145, v81
	v_mov_b32_e32 v146, v81
	v_mov_b32_e32 v147, v81
	v_mov_b32_e32 v148, v81
	v_mov_b32_e32 v149, v81
	v_mov_b32_e32 v150, v81
	v_mov_b32_e32 v151, v81
	v_mov_b32_e32 v152, v81
	v_mov_b32_e32 v153, v81
	v_mov_b32_e32 v154, v81
	v_mov_b32_e32 v155, v81
	v_mov_b32_e32 v156, v81
	v_mov_b32_e32 v157, v81
	v_mov_b32_e32 v158, v81
	v_mov_b32_e32 v159, v81
	v_mov_b32_e32 v160, v81
	v_mov_b32_e32 v161, v81
	v_mov_b32_e32 v162, v81
	v_mov_b32_e32 v163, v81
	v_mov_b32_e32 v164, v81
	v_mov_b32_e32 v165, v81
	v_mov_b32_e32 v166, v81
	v_mov_b32_e32 v167, v81
	v_mov_b32_e32 v168, v81
	v_mov_b32_e32 v169, v81
	v_mov_b32_e32 v170, v81
	v_mov_b32_e32 v171, v81
	v_mov_b32_e32 v172, v81
	v_mov_b32_e32 v173, v81
	v_mov_b32_e32 v174, v81
	v_mov_b32_e32 v175, v81
	v_mov_b32_e32 v176, v81
; #define LAS __attribute__((address_space(3)))
; __device__ __forceinline__ void p8_peer_gather(Frame& F) {
;     ...
;     for (int s_ = 0; s_ < 16 * NREP_U; ++s_) { const int s = s_ & 15;
;         if (NREP_U > 1 && s_ == 16) {
; #pragma unroll
;             for (int q = 0; q < 9; ++q)
; #pragma unroll
;                 for (int i = 0; i < 16; ++i) acc[q][i] = 0;
;         }
;         asm volatile("s_waitcnt vmcnt(0) lgkmcnt(0)" ::: "memory");
;         if (s_ + 1 < 16 * NREP_U) { const int tsl = lane >> 4, pc = lane & 15;
; #pragma unroll
;           for (int r = 0; r < 3; ++r) { const int q = 4 * r + tsl; const int j = q < 8 ? wave + 8 * q : 64;
;               __builtin_amdgcn_global_load_lds((const unsigned*)(X1Q + ((size_t)F.bid + 256 * j) * DM + 256 * ((s + 1) & 15) + 16 * pc), (LAS unsigned*)(xs_base + ((s_ + 1) & 1) * 3072 + 1024 * r), 16, 0, 0); } }
;         const unsigned char* xs_w = xs_base + (s_ & 1) * 3072;
;         const unsigned uoff = s * 128 + sub * 16;
; #pragma unroll
;         for (int q = 0; q < 9; ++q) { const int j = q < 8 ? wave + 8 * q : 64;
;             if (q < 8 ? (wave + 8 * q < 65) : ((s & 7) == wave)) {
;                 const bool v8 = (s & 7) == wave, nsame = (q < 7) || (q == 7 && v8), nlast = !nsame && !(s_ + 1 < 16 * NREP_U);
;                 const int nj = nsame ? (q + 1 < 8 ? wave + 8 * (q + 1) : 64) : (nlast ? j : wave);
;                 const unsigned noff = (nsame || nlast) ? uoff : ((s + 1) & 15) * 128 + sub * 16;
;                 const v4u xr0 = *(const v4u*)(xs_w + q * 256 + 32 * sub), xr1 = *(const v4u*)(xs_w + q * 256 + 32 * sub + 16);
;                 const int xg[8] = {(int)xr0.x, (int)xr0.y, (int)xr0.z, (int)xr0.w, (int)xr1.x, (int)xr1.y, (int)xr1.z, (int)xr1.w};
; #pragma unroll
;                 for (int i = 0; i < 16; ++i) { int a = acc[q][i];
; #pragma unroll
;                     for (int g = 0; g < 4; ++g) { const unsigned w = d[i][g];
;                         a = __builtin_amdgcn_sdot4((int)((w << 4) & 0xf0f0f0f0u), xg[2 * g], a, false);
;                         a = __builtin_amdgcn_sdot4((int)(w & 0xf0f0f0f0u), xg[2 * g + 1], a, false); }
;                     acc[q][i] = a;
;                     d[i] = *(const v4u*)(UQ + (size_t)(idx_s[nj * 128 + pg * 16 + i] + noff)); }
	v_mov_b32_e32 v177, v81
	v_mov_b32_e32 v178, v81
	v_mov_b32_e32 v179, v81
	v_mov_b32_e32 v180, v81
	v_mov_b32_e32 v181, v81
	v_mov_b32_e32 v182, v81
	v_mov_b32_e32 v183, v81
	v_mov_b32_e32 v184, v81
	v_mov_b32_e32 v185, v81
	v_mov_b32_e32 v186, v81
	v_mov_b32_e32 v187, v81
	v_mov_b32_e32 v188, v81
	v_mov_b32_e32 v189, v81
	v_mov_b32_e32 v190, v81
	v_mov_b32_e32 v191, v81
	v_mov_b32_e32 v192, v81
	v_mov_b32_e32 v193, v81
	v_mov_b32_e32 v194, v81
	v_mov_b32_e32 v195, v81
	v_mov_b32_e32 v196, v81
	v_mov_b32_e32 v197, v81
	v_mov_b32_e32 v198, v81
	v_mov_b32_e32 v199, v81
	v_mov_b32_e32 v200, v81
	v_mov_b32_e32 v201, v81
	v_mov_b32_e32 v202, v81
	v_mov_b32_e32 v203, v81
	v_mov_b32_e32 v204, v81
	v_mov_b32_e32 v205, v81
	v_mov_b32_e32 v206, v81
	v_mov_b32_e32 v207, v81
	v_mov_b32_e32 v208, v81
	v_mov_b32_e32 v209, v81
	v_mov_b32_e32 v210, v81
	v_mov_b32_e32 v211, v81
	v_mov_b32_e32 v212, v81
	v_mov_b32_e32 v213, v81
	v_mov_b32_e32 v214, v81
	v_mov_b32_e32 v215, v81
	v_mov_b32_e32 v216, v81
	v_mov_b32_e32 v217, v81
	v_mov_b32_e32 v218, v81
	v_mov_b32_e32 v219, v81
	v_mov_b32_e32 v220, v81
	v_mov_b32_e32 v221, v81
	v_mov_b32_e32 v222, v81
	v_mov_b32_e32 v223, v81
	v_mov_b32_e32 v224, v81
	v_mov_b32_e32 v225, v81
	v_mov_b32_e32 v226, v81
	v_mov_b32_e32 v227, v81
	v_mov_b32_e32 v228, v81
	v_mov_b32_e32 v229, v81
	v_mov_b32_e32 v230, v81
	v_mov_b32_e32 v231, v81
	v_mov_b32_e32 v232, v81
	v_mov_b32_e32 v233, v81
	v_mov_b32_e32 v236, v81
	v_mov_b32_e32 v239, v81
	v_mov_b32_e32 v240, v81
	s_mov_b32 s30, 0
	s_mov_b32 s42, 0xf0f0f0f0
	s_waitcnt vmcnt(0) lgkmcnt(0)
.Lu_loop:
	s_add_i32 s38, s30, 1
	s_cmpk_eq_i32 s39, 0x780
	s_cselect_b64 s[28:29], -1, 0
	s_and_b32 s6, s37, 0xf00
	s_bitcmp1_b32 s38, 0
	s_cselect_b32 s2, 0xc00, 0
	v_lshl_add_u64 v[64:65], v[82:83], 0, s[6:7]
	s_add_i32 s2, s33, s2
	v_lshl_add_u64 v[66:67], v[64:65], 0, v[84:85]
	s_mov_b32 m0, s2
	s_nop 0
	global_load_lds_dwordx4 v[66:67], off
	v_lshl_add_u64 v[66:67], v[64:65], 0, v[86:87]
	s_add_i32 m0, s2, 0x400
	v_lshl_add_u64 v[64:65], v[64:65], 0, s[8:9]
	global_load_lds_dwordx4 v[66:67], off
	v_lshl_add_u64 v[64:65], v[64:65], 0, s[10:11]
	s_add_i32 m0, s2, 0x800
	s_nop 0
	global_load_lds_dwordx4 v[64:65], off
	s_bitcmp1_b32 s30, 0
	s_cselect_b32 s2, 0xc00, 0
	v_add_u32_e32 v242, s39, v93
	v_add_u32_e32 v241, s2, v237
	ds_read_b128 v[68:71], v241
	ds_read_b128 v[64:67], v241 offset:16
	ds_read_b128 v[244:247], v238 offset:4096
	ds_read_b128 v[248:251], v238 offset:4112
	ds_read_b128 v[76:79], v238 offset:4128
	ds_read_b128 v[72:75], v238 offset:4144
	s_waitcnt vmcnt(17) lgkmcnt(4)
	v_lshlrev_b32_e32 v243, 4, v44
	v_lshlrev_b32_e32 v254, 4, v28
	v_and_b32_e32 v243, s42, v243
	v_and_b32_e32 v254, s42, v254
	v_dot4c_i32_i8_e32 v240, v243, v68
	v_dot4c_i32_i8_e32 v239, v254, v68
	v_and_b32_e32 v44, s42, v44
	v_and_b32_e32 v28, s42, v28
	v_dot4c_i32_i8_e32 v240, v44, v69
	v_dot4c_i32_i8_e32 v239, v28, v69
	v_lshlrev_b32_e32 v243, 4, v45
	v_lshlrev_b32_e32 v254, 4, v29
	v_and_b32_e32 v243, s42, v243
	v_and_b32_e32 v254, s42, v254
	v_dot4c_i32_i8_e32 v240, v243, v70
	v_dot4c_i32_i8_e32 v239, v254, v70
	v_and_b32_e32 v45, s42, v45
	v_and_b32_e32 v29, s42, v29
	v_dot4c_i32_i8_e32 v240, v45, v71
	v_dot4c_i32_i8_e32 v239, v29, v71
	v_lshlrev_b32_e32 v243, 4, v46
	v_lshlrev_b32_e32 v254, 4, v30
	v_and_b32_e32 v243, s42, v243
	v_and_b32_e32 v254, s42, v254
	v_dot4c_i32_i8_e32 v240, v243, v64
	v_dot4c_i32_i8_e32 v239, v254, v64
	v_and_b32_e32 v46, s42, v46
	v_and_b32_e32 v30, s42, v30
	v_dot4c_i32_i8_e32 v240, v46, v65
	v_dot4c_i32_i8_e32 v239, v30, v65
	v_lshlrev_b32_e32 v243, 4, v47
	v_lshlrev_b32_e32 v254, 4, v31
	v_and_b32_e32 v243, s42, v243
	v_and_b32_e32 v254, s42, v254
	v_dot4c_i32_i8_e32 v240, v243, v66
	v_dot4c_i32_i8_e32 v239, v254, v66
	v_and_b32_e32 v47, s42, v47
	v_and_b32_e32 v31, s42, v31
	v_dot4c_i32_i8_e32 v240, v47, v67
	v_dot4c_i32_i8_e32 v239, v31, v67
	s_waitcnt lgkmcnt(3)
	v_add_u32_e32 v44, v244, v242
	v_add_u32_e32 v28, v245, v242
	global_load_dwordx4 v[44:47], v44, s[4:5]
	global_load_dwordx4 v[28:31], v28, s[4:5]
	s_waitcnt vmcnt(17)
	v_lshlrev_b32_e32 v243, 4, v32
	v_lshlrev_b32_e32 v254, 4, v0
	v_and_b32_e32 v243, s42, v243
	v_and_b32_e32 v254, s42, v254
	v_dot4c_i32_i8_e32 v236, v243, v68
	v_dot4c_i32_i8_e32 v233, v254, v68
	v_and_b32_e32 v32, s42, v32
	v_and_b32_e32 v0, s42, v0
	v_dot4c_i32_i8_e32 v236, v32, v69
	v_dot4c_i32_i8_e32 v233, v0, v69
	v_lshlrev_b32_e32 v243, 4, v33
	v_lshlrev_b32_e32 v254, 4, v1
	v_and_b32_e32 v243, s42, v243
	v_and_b32_e32 v254, s42, v254
	v_dot4c_i32_i8_e32 v236, v243, v70
	v_dot4c_i32_i8_e32 v233, v254, v70
	v_and_b32_e32 v33, s42, v33
	v_and_b32_e32 v1, s42, v1
	v_dot4c_i32_i8_e32 v236, v33, v71
	v_dot4c_i32_i8_e32 v233, v1, v71
	v_lshlrev_b32_e32 v243, 4, v34
	v_lshlrev_b32_e32 v254, 4, v2
	v_and_b32_e32 v243, s42, v243
	v_and_b32_e32 v254, s42, v254
	v_dot4c_i32_i8_e32 v236, v243, v64
	v_dot4c_i32_i8_e32 v233, v254, v64
	v_and_b32_e32 v34, s42, v34
	v_and_b32_e32 v2, s42, v2
	v_dot4c_i32_i8_e32 v236, v34, v65
	v_dot4c_i32_i8_e32 v233, v2, v65
	v_lshlrev_b32_e32 v243, 4, v35
	v_lshlrev_b32_e32 v254, 4, v3
	v_and_b32_e32 v243, s42, v243
	v_and_b32_e32 v254, s42, v254
	v_dot4c_i32_i8_e32 v236, v243, v66
	v_dot4c_i32_i8_e32 v233, v254, v66
	v_and_b32_e32 v35, s42, v35
	v_and_b32_e32 v3, s42, v3
	v_dot4c_i32_i8_e32 v236, v35, v67
	v_dot4c_i32_i8_e32 v233, v3, v67
	v_add_u32_e32 v32, v246, v242
	v_add_u32_e32 v0, v247, v242
	global_load_dwordx4 v[32:35], v32, s[4:5]
	global_load_dwordx4 v[0:3], v0, s[4:5]
	s_waitcnt vmcnt(17)
; __device__ __forceinline__ void p8_peer_gather(Frame& F) {
;     ...
;                 const v4u xr0 = *(const v4u*)(xs_w + q * 256 + 32 * sub), xr1 = *(const v4u*)(xs_w + q * 256 + 32 * sub + 16);
;                 const int xg[8] = {(int)xr0.x, (int)xr0.y, (int)xr0.z, (int)xr0.w, (int)xr1.x, (int)xr1.y, (int)xr1.z, (int)xr1.w};
; #pragma unroll
;                 for (int i = 0; i < 16; ++i) { int a = acc[q][i];
; #pragma unroll
;                     for (int g = 0; g < 4; ++g) { const unsigned w = d[i][g];
;                         a = __builtin_amdgcn_sdot4((int)((w << 4) & 0xf0f0f0f0u), xg[2 * g], a, false);
;                         a = __builtin_amdgcn_sdot4((int)(w & 0xf0f0f0f0u), xg[2 * g + 1], a, false); }
;                     acc[q][i] = a;
;                     d[i] = *(const v4u*)(UQ + (size_t)(idx_s[nj * 128 + pg * 16 + i] + noff)); }
	v_lshlrev_b32_e32 v243, 4, v36
	v_lshlrev_b32_e32 v254, 4, v4
	v_and_b32_e32 v243, s42, v243
	v_and_b32_e32 v254, s42, v254
	v_dot4c_i32_i8_e32 v232, v243, v68
	v_dot4c_i32_i8_e32 v231, v254, v68
	v_and_b32_e32 v36, s42, v36
	v_and_b32_e32 v4, s42, v4
	v_dot4c_i32_i8_e32 v232, v36, v69
	v_dot4c_i32_i8_e32 v231, v4, v69
	v_lshlrev_b32_e32 v243, 4, v37
	v_lshlrev_b32_e32 v254, 4, v5
	v_and_b32_e32 v243, s42, v243
	v_and_b32_e32 v254, s42, v254
	v_dot4c_i32_i8_e32 v232, v243, v70
	v_dot4c_i32_i8_e32 v231, v254, v70
	v_and_b32_e32 v37, s42, v37
	v_and_b32_e32 v5, s42, v5
	v_dot4c_i32_i8_e32 v232, v37, v71
	v_dot4c_i32_i8_e32 v231, v5, v71
	v_lshlrev_b32_e32 v243, 4, v38
	v_lshlrev_b32_e32 v254, 4, v6
	v_and_b32_e32 v243, s42, v243
	v_and_b32_e32 v254, s42, v254
	v_dot4c_i32_i8_e32 v232, v243, v64
	v_dot4c_i32_i8_e32 v231, v254, v64
	v_and_b32_e32 v38, s42, v38
	v_and_b32_e32 v6, s42, v6
	v_dot4c_i32_i8_e32 v232, v38, v65
	v_dot4c_i32_i8_e32 v231, v6, v65
	v_lshlrev_b32_e32 v243, 4, v39
	v_lshlrev_b32_e32 v254, 4, v7
	v_and_b32_e32 v243, s42, v243
	v_and_b32_e32 v254, s42, v254
	v_dot4c_i32_i8_e32 v232, v243, v66
	v_dot4c_i32_i8_e32 v231, v254, v66
	v_and_b32_e32 v39, s42, v39
	v_and_b32_e32 v7, s42, v7
	v_dot4c_i32_i8_e32 v232, v39, v67
	v_dot4c_i32_i8_e32 v231, v7, v67
	s_waitcnt lgkmcnt(2)
	v_add_u32_e32 v36, v248, v242
	v_add_u32_e32 v4, v249, v242
	global_load_dwordx4 v[36:39], v36, s[4:5]
	global_load_dwordx4 v[4:7], v4, s[4:5]
	s_waitcnt vmcnt(17)
	v_lshlrev_b32_e32 v243, 4, v40
	v_lshlrev_b32_e32 v254, 4, v8
	v_and_b32_e32 v243, s42, v243
	v_and_b32_e32 v254, s42, v254
	v_dot4c_i32_i8_e32 v230, v243, v68
	v_dot4c_i32_i8_e32 v229, v254, v68
	v_and_b32_e32 v40, s42, v40
	v_and_b32_e32 v8, s42, v8
	v_dot4c_i32_i8_e32 v230, v40, v69
	v_dot4c_i32_i8_e32 v229, v8, v69
	v_lshlrev_b32_e32 v243, 4, v41
	v_lshlrev_b32_e32 v254, 4, v9
	v_and_b32_e32 v243, s42, v243
	v_and_b32_e32 v254, s42, v254
	v_dot4c_i32_i8_e32 v230, v243, v70
	v_dot4c_i32_i8_e32 v229, v254, v70
	v_and_b32_e32 v41, s42, v41
	v_and_b32_e32 v9, s42, v9
	v_dot4c_i32_i8_e32 v230, v41, v71
	v_dot4c_i32_i8_e32 v229, v9, v71
	v_lshlrev_b32_e32 v243, 4, v42
	v_lshlrev_b32_e32 v254, 4, v10
	v_and_b32_e32 v243, s42, v243
	v_and_b32_e32 v254, s42, v254
	v_dot4c_i32_i8_e32 v230, v243, v64
	v_dot4c_i32_i8_e32 v229, v254, v64
	v_and_b32_e32 v42, s42, v42
	v_and_b32_e32 v10, s42, v10
	v_dot4c_i32_i8_e32 v230, v42, v65
	v_dot4c_i32_i8_e32 v229, v10, v65
	v_lshlrev_b32_e32 v243, 4, v43
	v_lshlrev_b32_e32 v254, 4, v11
	v_and_b32_e32 v243, s42, v243
	v_and_b32_e32 v254, s42, v254
	v_dot4c_i32_i8_e32 v230, v243, v66
	v_dot4c_i32_i8_e32 v229, v254, v66
	v_and_b32_e32 v43, s42, v43
	v_and_b32_e32 v11, s42, v11
	v_dot4c_i32_i8_e32 v230, v43, v67
	v_dot4c_i32_i8_e32 v229, v11, v67
	v_add_u32_e32 v40, v250, v242
	v_add_u32_e32 v8, v251, v242
	global_load_dwordx4 v[40:43], v40, s[4:5]
	global_load_dwordx4 v[8:11], v8, s[4:5]
	s_waitcnt vmcnt(17)
	v_lshlrev_b32_e32 v243, 4, v48
	v_lshlrev_b32_e32 v254, 4, v12
	v_and_b32_e32 v243, s42, v243
	v_and_b32_e32 v254, s42, v254
	v_dot4c_i32_i8_e32 v228, v243, v68
	v_dot4c_i32_i8_e32 v227, v254, v68
	v_and_b32_e32 v48, s42, v48
	v_and_b32_e32 v12, s42, v12
	v_dot4c_i32_i8_e32 v228, v48, v69
	v_dot4c_i32_i8_e32 v227, v12, v69
	v_lshlrev_b32_e32 v243, 4, v49
	v_lshlrev_b32_e32 v254, 4, v13
	v_and_b32_e32 v243, s42, v243
	v_and_b32_e32 v254, s42, v254
	v_dot4c_i32_i8_e32 v228, v243, v70
	v_dot4c_i32_i8_e32 v227, v254, v70
	v_and_b32_e32 v49, s42, v49
	v_and_b32_e32 v13, s42, v13
	v_dot4c_i32_i8_e32 v228, v49, v71
	v_dot4c_i32_i8_e32 v227, v13, v71
	v_lshlrev_b32_e32 v243, 4, v50
	v_lshlrev_b32_e32 v254, 4, v14
	v_and_b32_e32 v243, s42, v243
	v_and_b32_e32 v254, s42, v254
	v_dot4c_i32_i8_e32 v228, v243, v64
	v_dot4c_i32_i8_e32 v227, v254, v64
	v_and_b32_e32 v50, s42, v50
	v_and_b32_e32 v14, s42, v14
	v_dot4c_i32_i8_e32 v228, v50, v65
	v_dot4c_i32_i8_e32 v227, v14, v65
	v_lshlrev_b32_e32 v243, 4, v51
	v_lshlrev_b32_e32 v254, 4, v15
	v_and_b32_e32 v243, s42, v243
	v_and_b32_e32 v254, s42, v254
	v_dot4c_i32_i8_e32 v228, v243, v66
	v_dot4c_i32_i8_e32 v227, v254, v66
	v_and_b32_e32 v51, s42, v51
	v_and_b32_e32 v15, s42, v15
	v_dot4c_i32_i8_e32 v228, v51, v67
	v_dot4c_i32_i8_e32 v227, v15, v67
	s_waitcnt lgkmcnt(1)
	v_add_u32_e32 v48, v76, v242
	v_add_u32_e32 v12, v77, v242
	global_load_dwordx4 v[48:51], v48, s[4:5]
	global_load_dwordx4 v[12:15], v12, s[4:5]
	s_waitcnt vmcnt(17)
	v_lshlrev_b32_e32 v243, 4, v52
	v_lshlrev_b32_e32 v254, 4, v16
	v_and_b32_e32 v243, s42, v243
	v_and_b32_e32 v254, s42, v254
	v_dot4c_i32_i8_e32 v226, v243, v68
	v_dot4c_i32_i8_e32 v225, v254, v68
	v_and_b32_e32 v52, s42, v52
	v_and_b32_e32 v16, s42, v16
	v_dot4c_i32_i8_e32 v226, v52, v69
	v_dot4c_i32_i8_e32 v225, v16, v69
	v_lshlrev_b32_e32 v243, 4, v53
	v_lshlrev_b32_e32 v254, 4, v17
	v_and_b32_e32 v243, s42, v243
	v_and_b32_e32 v254, s42, v254
	v_dot4c_i32_i8_e32 v226, v243, v70
	v_dot4c_i32_i8_e32 v225, v254, v70
	v_and_b32_e32 v53, s42, v53
	v_and_b32_e32 v17, s42, v17
	v_dot4c_i32_i8_e32 v226, v53, v71
	v_dot4c_i32_i8_e32 v225, v17, v71
	v_lshlrev_b32_e32 v243, 4, v54
	v_lshlrev_b32_e32 v254, 4, v18
	v_and_b32_e32 v243, s42, v243
	v_and_b32_e32 v254, s42, v254
	v_dot4c_i32_i8_e32 v226, v243, v64
	v_dot4c_i32_i8_e32 v225, v254, v64
	v_and_b32_e32 v54, s42, v54
	v_and_b32_e32 v18, s42, v18
	v_dot4c_i32_i8_e32 v226, v54, v65
	v_dot4c_i32_i8_e32 v225, v18, v65
	v_lshlrev_b32_e32 v243, 4, v55
	v_lshlrev_b32_e32 v254, 4, v19
	v_and_b32_e32 v243, s42, v243
	v_and_b32_e32 v254, s42, v254
	v_dot4c_i32_i8_e32 v226, v243, v66
	v_dot4c_i32_i8_e32 v225, v254, v66
	v_and_b32_e32 v55, s42, v55
	v_and_b32_e32 v19, s42, v19
	v_dot4c_i32_i8_e32 v226, v55, v67
	v_dot4c_i32_i8_e32 v225, v19, v67
	v_add_u32_e32 v52, v78, v242
	v_add_u32_e32 v16, v79, v242
	global_load_dwordx4 v[52:55], v52, s[4:5]
	global_load_dwordx4 v[16:19], v16, s[4:5]
	s_waitcnt vmcnt(17)
; __device__ __forceinline__ void p8_peer_gather(Frame& F) {
;     ...
;                 const v4u xr0 = *(const v4u*)(xs_w + q * 256 + 32 * sub), xr1 = *(const v4u*)(xs_w + q * 256 + 32 * sub + 16);
;                 const int xg[8] = {(int)xr0.x, (int)xr0.y, (int)xr0.z, (int)xr0.w, (int)xr1.x, (int)xr1.y, (int)xr1.z, (int)xr1.w};
; #pragma unroll
;                 for (int i = 0; i < 16; ++i) { int a = acc[q][i];
; #pragma unroll
;                     for (int g = 0; g < 4; ++g) { const unsigned w = d[i][g];
;                         a = __builtin_amdgcn_sdot4((int)((w << 4) & 0xf0f0f0f0u), xg[2 * g], a, false);
;                         a = __builtin_amdgcn_sdot4((int)(w & 0xf0f0f0f0u), xg[2 * g + 1], a, false); }
;                     acc[q][i] = a;
;                     d[i] = *(const v4u*)(UQ + (size_t)(idx_s[nj * 128 + pg * 16 + i] + noff)); }
	v_lshlrev_b32_e32 v243, 4, v56
	v_lshlrev_b32_e32 v254, 4, v20
	v_and_b32_e32 v243, s42, v243
	v_and_b32_e32 v254, s42, v254
	v_dot4c_i32_i8_e32 v224, v243, v68
	v_dot4c_i32_i8_e32 v223, v254, v68
	v_and_b32_e32 v56, s42, v56
	v_and_b32_e32 v20, s42, v20
	v_dot4c_i32_i8_e32 v224, v56, v69
	v_dot4c_i32_i8_e32 v223, v20, v69
	v_lshlrev_b32_e32 v243, 4, v57
	v_lshlrev_b32_e32 v254, 4, v21
	v_and_b32_e32 v243, s42, v243
	v_and_b32_e32 v254, s42, v254
	v_dot4c_i32_i8_e32 v224, v243, v70
	v_dot4c_i32_i8_e32 v223, v254, v70
	v_and_b32_e32 v57, s42, v57
	v_and_b32_e32 v21, s42, v21
	v_dot4c_i32_i8_e32 v224, v57, v71
	v_dot4c_i32_i8_e32 v223, v21, v71
	v_lshlrev_b32_e32 v243, 4, v58
	v_lshlrev_b32_e32 v254, 4, v22
	v_and_b32_e32 v243, s42, v243
	v_and_b32_e32 v254, s42, v254
	v_dot4c_i32_i8_e32 v224, v243, v64
	v_dot4c_i32_i8_e32 v223, v254, v64
	v_and_b32_e32 v58, s42, v58
	v_and_b32_e32 v22, s42, v22
	v_dot4c_i32_i8_e32 v224, v58, v65
	v_dot4c_i32_i8_e32 v223, v22, v65
	v_lshlrev_b32_e32 v243, 4, v59
	v_lshlrev_b32_e32 v254, 4, v23
	v_and_b32_e32 v243, s42, v243
	v_and_b32_e32 v254, s42, v254
	v_dot4c_i32_i8_e32 v224, v243, v66
	v_dot4c_i32_i8_e32 v223, v254, v66
	v_and_b32_e32 v59, s42, v59
	v_and_b32_e32 v23, s42, v23
	v_dot4c_i32_i8_e32 v224, v59, v67
	v_dot4c_i32_i8_e32 v223, v23, v67
	s_waitcnt lgkmcnt(0)
	v_add_u32_e32 v56, v72, v242
	v_add_u32_e32 v20, v73, v242
	global_load_dwordx4 v[56:59], v56, s[4:5]
	global_load_dwordx4 v[20:23], v20, s[4:5]
	s_waitcnt vmcnt(17)
	v_lshlrev_b32_e32 v243, 4, v60
	v_lshlrev_b32_e32 v254, 4, v24
	v_and_b32_e32 v243, s42, v243
	v_and_b32_e32 v254, s42, v254
	v_dot4c_i32_i8_e32 v222, v243, v68
	v_dot4c_i32_i8_e32 v221, v254, v68
	v_and_b32_e32 v60, s42, v60
	v_and_b32_e32 v24, s42, v24
	v_dot4c_i32_i8_e32 v222, v60, v69
	v_dot4c_i32_i8_e32 v221, v24, v69
	v_lshlrev_b32_e32 v243, 4, v61
	v_lshlrev_b32_e32 v254, 4, v25
	v_and_b32_e32 v243, s42, v243
	v_and_b32_e32 v254, s42, v254
	v_dot4c_i32_i8_e32 v222, v243, v70
	v_dot4c_i32_i8_e32 v221, v254, v70
	v_and_b32_e32 v61, s42, v61
	v_and_b32_e32 v25, s42, v25
	v_dot4c_i32_i8_e32 v222, v61, v71
	v_dot4c_i32_i8_e32 v221, v25, v71
	v_lshlrev_b32_e32 v243, 4, v62
	v_lshlrev_b32_e32 v254, 4, v26
	v_and_b32_e32 v243, s42, v243
	v_and_b32_e32 v254, s42, v254
	v_dot4c_i32_i8_e32 v222, v243, v64
	v_dot4c_i32_i8_e32 v221, v254, v64
	v_and_b32_e32 v62, s42, v62
	v_and_b32_e32 v26, s42, v26
	v_dot4c_i32_i8_e32 v222, v62, v65
	v_dot4c_i32_i8_e32 v221, v26, v65
	v_lshlrev_b32_e32 v243, 4, v63
	v_lshlrev_b32_e32 v254, 4, v27
	v_and_b32_e32 v243, s42, v243
	v_and_b32_e32 v254, s42, v254
	v_dot4c_i32_i8_e32 v222, v243, v66
	v_dot4c_i32_i8_e32 v221, v254, v66
	v_and_b32_e32 v63, s42, v63
	v_and_b32_e32 v27, s42, v27
	v_dot4c_i32_i8_e32 v222, v63, v67
	v_dot4c_i32_i8_e32 v221, v27, v67
	v_add_u32_e32 v60, v74, v242
	v_add_u32_e32 v24, v75, v242
	global_load_dwordx4 v[60:63], v60, s[4:5]
	global_load_dwordx4 v[24:27], v24, s[4:5]
	ds_read_b128 v[68:71], v241 offset:256
	ds_read_b128 v[64:67], v241 offset:272
	ds_read_b128 v[244:247], v238 offset:8192
	ds_read_b128 v[248:251], v238 offset:8208
	ds_read_b128 v[76:79], v238 offset:8224
	ds_read_b128 v[72:75], v238 offset:8240
	s_waitcnt vmcnt(14) lgkmcnt(4)
	v_lshlrev_b32_e32 v243, 4, v44
	v_lshlrev_b32_e32 v254, 4, v28
	v_and_b32_e32 v243, s42, v243
	v_and_b32_e32 v254, s42, v254
	v_dot4c_i32_i8_e32 v220, v243, v68
	v_dot4c_i32_i8_e32 v219, v254, v68
	v_and_b32_e32 v44, s42, v44
	v_and_b32_e32 v28, s42, v28
	v_dot4c_i32_i8_e32 v220, v44, v69
	v_dot4c_i32_i8_e32 v219, v28, v69
	v_lshlrev_b32_e32 v243, 4, v45
	v_lshlrev_b32_e32 v254, 4, v29
	v_and_b32_e32 v243, s42, v243
	v_and_b32_e32 v254, s42, v254
	v_dot4c_i32_i8_e32 v220, v243, v70
	v_dot4c_i32_i8_e32 v219, v254, v70
	v_and_b32_e32 v45, s42, v45
	v_and_b32_e32 v29, s42, v29
	v_dot4c_i32_i8_e32 v220, v45, v71
	v_dot4c_i32_i8_e32 v219, v29, v71
	v_lshlrev_b32_e32 v243, 4, v46
	v_lshlrev_b32_e32 v254, 4, v30
	v_and_b32_e32 v243, s42, v243
	v_and_b32_e32 v254, s42, v254
	v_dot4c_i32_i8_e32 v220, v243, v64
	v_dot4c_i32_i8_e32 v219, v254, v64
	v_and_b32_e32 v46, s42, v46
	v_and_b32_e32 v30, s42, v30
	v_dot4c_i32_i8_e32 v220, v46, v65
	v_dot4c_i32_i8_e32 v219, v30, v65
	v_lshlrev_b32_e32 v243, 4, v47
	v_lshlrev_b32_e32 v254, 4, v31
	v_and_b32_e32 v243, s42, v243
	v_and_b32_e32 v254, s42, v254
	v_dot4c_i32_i8_e32 v220, v243, v66
	v_dot4c_i32_i8_e32 v219, v254, v66
	v_and_b32_e32 v47, s42, v47
	v_and_b32_e32 v31, s42, v31
	v_dot4c_i32_i8_e32 v220, v47, v67
	v_dot4c_i32_i8_e32 v219, v31, v67
	s_waitcnt lgkmcnt(3)
	v_add_u32_e32 v44, v244, v242
	v_add_u32_e32 v28, v245, v242
	global_load_dwordx4 v[44:47], v44, s[4:5]
	global_load_dwordx4 v[28:31], v28, s[4:5]
	s_waitcnt vmcnt(14)
	v_lshlrev_b32_e32 v243, 4, v32
	v_lshlrev_b32_e32 v254, 4, v0
	v_and_b32_e32 v243, s42, v243
	v_and_b32_e32 v254, s42, v254
	v_dot4c_i32_i8_e32 v218, v243, v68
	v_dot4c_i32_i8_e32 v217, v254, v68
	v_and_b32_e32 v32, s42, v32
	v_and_b32_e32 v0, s42, v0
	v_dot4c_i32_i8_e32 v218, v32, v69
	v_dot4c_i32_i8_e32 v217, v0, v69
	v_lshlrev_b32_e32 v243, 4, v33
	v_lshlrev_b32_e32 v254, 4, v1
	v_and_b32_e32 v243, s42, v243
	v_and_b32_e32 v254, s42, v254
	v_dot4c_i32_i8_e32 v218, v243, v70
	v_dot4c_i32_i8_e32 v217, v254, v70
	v_and_b32_e32 v33, s42, v33
	v_and_b32_e32 v1, s42, v1
	v_dot4c_i32_i8_e32 v218, v33, v71
	v_dot4c_i32_i8_e32 v217, v1, v71
	v_lshlrev_b32_e32 v243, 4, v34
	v_lshlrev_b32_e32 v254, 4, v2
	v_and_b32_e32 v243, s42, v243
	v_and_b32_e32 v254, s42, v254
	v_dot4c_i32_i8_e32 v218, v243, v64
	v_dot4c_i32_i8_e32 v217, v254, v64
	v_and_b32_e32 v34, s42, v34
	v_and_b32_e32 v2, s42, v2
	v_dot4c_i32_i8_e32 v218, v34, v65
	v_dot4c_i32_i8_e32 v217, v2, v65
	v_lshlrev_b32_e32 v243, 4, v35
	v_lshlrev_b32_e32 v254, 4, v3
	v_and_b32_e32 v243, s42, v243
	v_and_b32_e32 v254, s42, v254
	v_dot4c_i32_i8_e32 v218, v243, v66
	v_dot4c_i32_i8_e32 v217, v254, v66
	v_and_b32_e32 v35, s42, v35
	v_and_b32_e32 v3, s42, v3
	v_dot4c_i32_i8_e32 v218, v35, v67
	v_dot4c_i32_i8_e32 v217, v3, v67
	v_add_u32_e32 v32, v246, v242
	v_add_u32_e32 v0, v247, v242
	global_load_dwordx4 v[32:35], v32, s[4:5]
	global_load_dwordx4 v[0:3], v0, s[4:5]
	s_waitcnt vmcnt(14)
; __device__ __forceinline__ void p8_peer_gather(Frame& F) {
;     ...
;                 const v4u xr0 = *(const v4u*)(xs_w + q * 256 + 32 * sub), xr1 = *(const v4u*)(xs_w + q * 256 + 32 * sub + 16);
;                 const int xg[8] = {(int)xr0.x, (int)xr0.y, (int)xr0.z, (int)xr0.w, (int)xr1.x, (int)xr1.y, (int)xr1.z, (int)xr1.w};
; #pragma unroll
;                 for (int i = 0; i < 16; ++i) { int a = acc[q][i];
; #pragma unroll
;                     for (int g = 0; g < 4; ++g) { const unsigned w = d[i][g];
;                         a = __builtin_amdgcn_sdot4((int)((w << 4) & 0xf0f0f0f0u), xg[2 * g], a, false);
;                         a = __builtin_amdgcn_sdot4((int)(w & 0xf0f0f0f0u), xg[2 * g + 1], a, false); }
;                     acc[q][i] = a;
;                     d[i] = *(const v4u*)(UQ + (size_t)(idx_s[nj * 128 + pg * 16 + i] + noff)); }
	v_lshlrev_b32_e32 v243, 4, v36
	v_lshlrev_b32_e32 v254, 4, v4
	v_and_b32_e32 v243, s42, v243
	v_and_b32_e32 v254, s42, v254
	v_dot4c_i32_i8_e32 v216, v243, v68
	v_dot4c_i32_i8_e32 v215, v254, v68
	v_and_b32_e32 v36, s42, v36
	v_and_b32_e32 v4, s42, v4
	v_dot4c_i32_i8_e32 v216, v36, v69
	v_dot4c_i32_i8_e32 v215, v4, v69
	v_lshlrev_b32_e32 v243, 4, v37
	v_lshlrev_b32_e32 v254, 4, v5
	v_and_b32_e32 v243, s42, v243
	v_and_b32_e32 v254, s42, v254
	v_dot4c_i32_i8_e32 v216, v243, v70
	v_dot4c_i32_i8_e32 v215, v254, v70
	v_and_b32_e32 v37, s42, v37
	v_and_b32_e32 v5, s42, v5
	v_dot4c_i32_i8_e32 v216, v37, v71
	v_dot4c_i32_i8_e32 v215, v5, v71
	v_lshlrev_b32_e32 v243, 4, v38
	v_lshlrev_b32_e32 v254, 4, v6
	v_and_b32_e32 v243, s42, v243
	v_and_b32_e32 v254, s42, v254
	v_dot4c_i32_i8_e32 v216, v243, v64
	v_dot4c_i32_i8_e32 v215, v254, v64
	v_and_b32_e32 v38, s42, v38
	v_and_b32_e32 v6, s42, v6
	v_dot4c_i32_i8_e32 v216, v38, v65
	v_dot4c_i32_i8_e32 v215, v6, v65
	v_lshlrev_b32_e32 v243, 4, v39
	v_lshlrev_b32_e32 v254, 4, v7
	v_and_b32_e32 v243, s42, v243
	v_and_b32_e32 v254, s42, v254
	v_dot4c_i32_i8_e32 v216, v243, v66
	v_dot4c_i32_i8_e32 v215, v254, v66
	v_and_b32_e32 v39, s42, v39
	v_and_b32_e32 v7, s42, v7
	v_dot4c_i32_i8_e32 v216, v39, v67
	v_dot4c_i32_i8_e32 v215, v7, v67
	s_waitcnt lgkmcnt(2)
	v_add_u32_e32 v36, v248, v242
	v_add_u32_e32 v4, v249, v242
	global_load_dwordx4 v[36:39], v36, s[4:5]
	global_load_dwordx4 v[4:7], v4, s[4:5]
	s_waitcnt vmcnt(14)
	v_lshlrev_b32_e32 v243, 4, v40
	v_lshlrev_b32_e32 v254, 4, v8
	v_and_b32_e32 v243, s42, v243
	v_and_b32_e32 v254, s42, v254
	v_dot4c_i32_i8_e32 v214, v243, v68
	v_dot4c_i32_i8_e32 v213, v254, v68
	v_and_b32_e32 v40, s42, v40
	v_and_b32_e32 v8, s42, v8
	v_dot4c_i32_i8_e32 v214, v40, v69
	v_dot4c_i32_i8_e32 v213, v8, v69
	v_lshlrev_b32_e32 v243, 4, v41
	v_lshlrev_b32_e32 v254, 4, v9
	v_and_b32_e32 v243, s42, v243
	v_and_b32_e32 v254, s42, v254
	v_dot4c_i32_i8_e32 v214, v243, v70
	v_dot4c_i32_i8_e32 v213, v254, v70
	v_and_b32_e32 v41, s42, v41
	v_and_b32_e32 v9, s42, v9
	v_dot4c_i32_i8_e32 v214, v41, v71
	v_dot4c_i32_i8_e32 v213, v9, v71
	v_lshlrev_b32_e32 v243, 4, v42
	v_lshlrev_b32_e32 v254, 4, v10
	v_and_b32_e32 v243, s42, v243
	v_and_b32_e32 v254, s42, v254
	v_dot4c_i32_i8_e32 v214, v243, v64
	v_dot4c_i32_i8_e32 v213, v254, v64
	v_and_b32_e32 v42, s42, v42
	v_and_b32_e32 v10, s42, v10
	v_dot4c_i32_i8_e32 v214, v42, v65
	v_dot4c_i32_i8_e32 v213, v10, v65
	v_lshlrev_b32_e32 v243, 4, v43
	v_lshlrev_b32_e32 v254, 4, v11
	v_and_b32_e32 v243, s42, v243
	v_and_b32_e32 v254, s42, v254
	v_dot4c_i32_i8_e32 v214, v243, v66
	v_dot4c_i32_i8_e32 v213, v254, v66
	v_and_b32_e32 v43, s42, v43
	v_and_b32_e32 v11, s42, v11
	v_dot4c_i32_i8_e32 v214, v43, v67
	v_dot4c_i32_i8_e32 v213, v11, v67
	v_add_u32_e32 v40, v250, v242
	v_add_u32_e32 v8, v251, v242
	global_load_dwordx4 v[40:43], v40, s[4:5]
	global_load_dwordx4 v[8:11], v8, s[4:5]
	s_waitcnt vmcnt(14)
	v_lshlrev_b32_e32 v243, 4, v48
	v_lshlrev_b32_e32 v254, 4, v12
	v_and_b32_e32 v243, s42, v243
	v_and_b32_e32 v254, s42, v254
	v_dot4c_i32_i8_e32 v212, v243, v68
	v_dot4c_i32_i8_e32 v211, v254, v68
	v_and_b32_e32 v48, s42, v48
	v_and_b32_e32 v12, s42, v12
	v_dot4c_i32_i8_e32 v212, v48, v69
	v_dot4c_i32_i8_e32 v211, v12, v69
	v_lshlrev_b32_e32 v243, 4, v49
	v_lshlrev_b32_e32 v254, 4, v13
	v_and_b32_e32 v243, s42, v243
	v_and_b32_e32 v254, s42, v254
	v_dot4c_i32_i8_e32 v212, v243, v70
	v_dot4c_i32_i8_e32 v211, v254, v70
	v_and_b32_e32 v49, s42, v49
	v_and_b32_e32 v13, s42, v13
	v_dot4c_i32_i8_e32 v212, v49, v71
	v_dot4c_i32_i8_e32 v211, v13, v71
	v_lshlrev_b32_e32 v243, 4, v50
	v_lshlrev_b32_e32 v254, 4, v14
	v_and_b32_e32 v243, s42, v243
	v_and_b32_e32 v254, s42, v254
	v_dot4c_i32_i8_e32 v212, v243, v64
	v_dot4c_i32_i8_e32 v211, v254, v64
	v_and_b32_e32 v50, s42, v50
	v_and_b32_e32 v14, s42, v14
	v_dot4c_i32_i8_e32 v212, v50, v65
	v_dot4c_i32_i8_e32 v211, v14, v65
	v_lshlrev_b32_e32 v243, 4, v51
	v_lshlrev_b32_e32 v254, 4, v15
	v_and_b32_e32 v243, s42, v243
	v_and_b32_e32 v254, s42, v254
	v_dot4c_i32_i8_e32 v212, v243, v66
	v_dot4c_i32_i8_e32 v211, v254, v66
	v_and_b32_e32 v51, s42, v51
	v_and_b32_e32 v15, s42, v15
	v_dot4c_i32_i8_e32 v212, v51, v67
	v_dot4c_i32_i8_e32 v211, v15, v67
	s_waitcnt lgkmcnt(1)
	v_add_u32_e32 v48, v76, v242
	v_add_u32_e32 v12, v77, v242
	global_load_dwordx4 v[48:51], v48, s[4:5]
	global_load_dwordx4 v[12:15], v12, s[4:5]
	s_waitcnt vmcnt(14)
	v_lshlrev_b32_e32 v243, 4, v52
	v_lshlrev_b32_e32 v254, 4, v16
	v_and_b32_e32 v243, s42, v243
	v_and_b32_e32 v254, s42, v254
	v_dot4c_i32_i8_e32 v210, v243, v68
	v_dot4c_i32_i8_e32 v209, v254, v68
	v_and_b32_e32 v52, s42, v52
	v_and_b32_e32 v16, s42, v16
	v_dot4c_i32_i8_e32 v210, v52, v69
	v_dot4c_i32_i8_e32 v209, v16, v69
	v_lshlrev_b32_e32 v243, 4, v53
	v_lshlrev_b32_e32 v254, 4, v17
	v_and_b32_e32 v243, s42, v243
	v_and_b32_e32 v254, s42, v254
	v_dot4c_i32_i8_e32 v210, v243, v70
	v_dot4c_i32_i8_e32 v209, v254, v70
	v_and_b32_e32 v53, s42, v53
	v_and_b32_e32 v17, s42, v17
	v_dot4c_i32_i8_e32 v210, v53, v71
	v_dot4c_i32_i8_e32 v209, v17, v71
	v_lshlrev_b32_e32 v243, 4, v54
	v_lshlrev_b32_e32 v254, 4, v18
	v_and_b32_e32 v243, s42, v243
	v_and_b32_e32 v254, s42, v254
	v_dot4c_i32_i8_e32 v210, v243, v64
	v_dot4c_i32_i8_e32 v209, v254, v64
	v_and_b32_e32 v54, s42, v54
	v_and_b32_e32 v18, s42, v18
	v_dot4c_i32_i8_e32 v210, v54, v65
	v_dot4c_i32_i8_e32 v209, v18, v65
	v_lshlrev_b32_e32 v243, 4, v55
	v_lshlrev_b32_e32 v254, 4, v19
	v_and_b32_e32 v243, s42, v243
	v_and_b32_e32 v254, s42, v254
	v_dot4c_i32_i8_e32 v210, v243, v66
	v_dot4c_i32_i8_e32 v209, v254, v66
	v_and_b32_e32 v55, s42, v55
	v_and_b32_e32 v19, s42, v19
	v_dot4c_i32_i8_e32 v210, v55, v67
	v_dot4c_i32_i8_e32 v209, v19, v67
	v_add_u32_e32 v52, v78, v242
	v_add_u32_e32 v16, v79, v242
	global_load_dwordx4 v[52:55], v52, s[4:5]
	global_load_dwordx4 v[16:19], v16, s[4:5]
	s_waitcnt vmcnt(14)
; __device__ __forceinline__ void p8_peer_gather(Frame& F) {
;     ...
;                 const v4u xr0 = *(const v4u*)(xs_w + q * 256 + 32 * sub), xr1 = *(const v4u*)(xs_w + q * 256 + 32 * sub + 16);
;                 const int xg[8] = {(int)xr0.x, (int)xr0.y, (int)xr0.z, (int)xr0.w, (int)xr1.x, (int)xr1.y, (int)xr1.z, (int)xr1.w};
; #pragma unroll
;                 for (int i = 0; i < 16; ++i) { int a = acc[q][i];
; #pragma unroll
;                     for (int g = 0; g < 4; ++g) { const unsigned w = d[i][g];
;                         a = __builtin_amdgcn_sdot4((int)((w << 4) & 0xf0f0f0f0u), xg[2 * g], a, false);
;                         a = __builtin_amdgcn_sdot4((int)(w & 0xf0f0f0f0u), xg[2 * g + 1], a, false); }
;                     acc[q][i] = a;
;                     d[i] = *(const v4u*)(UQ + (size_t)(idx_s[nj * 128 + pg * 16 + i] + noff)); }
	v_lshlrev_b32_e32 v243, 4, v56
	v_lshlrev_b32_e32 v254, 4, v20
	v_and_b32_e32 v243, s42, v243
	v_and_b32_e32 v254, s42, v254
	v_dot4c_i32_i8_e32 v208, v243, v68
	v_dot4c_i32_i8_e32 v207, v254, v68
	v_and_b32_e32 v56, s42, v56
	v_and_b32_e32 v20, s42, v20
	v_dot4c_i32_i8_e32 v208, v56, v69
	v_dot4c_i32_i8_e32 v207, v20, v69
	v_lshlrev_b32_e32 v243, 4, v57
	v_lshlrev_b32_e32 v254, 4, v21
	v_and_b32_e32 v243, s42, v243
	v_and_b32_e32 v254, s42, v254
	v_dot4c_i32_i8_e32 v208, v243, v70
	v_dot4c_i32_i8_e32 v207, v254, v70
	v_and_b32_e32 v57, s42, v57
	v_and_b32_e32 v21, s42, v21
	v_dot4c_i32_i8_e32 v208, v57, v71
	v_dot4c_i32_i8_e32 v207, v21, v71
	v_lshlrev_b32_e32 v243, 4, v58
	v_lshlrev_b32_e32 v254, 4, v22
	v_and_b32_e32 v243, s42, v243
	v_and_b32_e32 v254, s42, v254
	v_dot4c_i32_i8_e32 v208, v243, v64
	v_dot4c_i32_i8_e32 v207, v254, v64
	v_and_b32_e32 v58, s42, v58
	v_and_b32_e32 v22, s42, v22
	v_dot4c_i32_i8_e32 v208, v58, v65
	v_dot4c_i32_i8_e32 v207, v22, v65
	v_lshlrev_b32_e32 v243, 4, v59
	v_lshlrev_b32_e32 v254, 4, v23
	v_and_b32_e32 v243, s42, v243
	v_and_b32_e32 v254, s42, v254
	v_dot4c_i32_i8_e32 v208, v243, v66
	v_dot4c_i32_i8_e32 v207, v254, v66
	v_and_b32_e32 v59, s42, v59
	v_and_b32_e32 v23, s42, v23
	v_dot4c_i32_i8_e32 v208, v59, v67
	v_dot4c_i32_i8_e32 v207, v23, v67
	s_waitcnt lgkmcnt(0)
	v_add_u32_e32 v56, v72, v242
	v_add_u32_e32 v20, v73, v242
	global_load_dwordx4 v[56:59], v56, s[4:5]
	global_load_dwordx4 v[20:23], v20, s[4:5]
	s_waitcnt vmcnt(14)
	v_lshlrev_b32_e32 v243, 4, v60
	v_lshlrev_b32_e32 v254, 4, v24
	v_and_b32_e32 v243, s42, v243
	v_and_b32_e32 v254, s42, v254
	v_dot4c_i32_i8_e32 v206, v243, v68
	v_dot4c_i32_i8_e32 v205, v254, v68
	v_and_b32_e32 v60, s42, v60
	v_and_b32_e32 v24, s42, v24
	v_dot4c_i32_i8_e32 v206, v60, v69
	v_dot4c_i32_i8_e32 v205, v24, v69
	v_lshlrev_b32_e32 v243, 4, v61
	v_lshlrev_b32_e32 v254, 4, v25
	v_and_b32_e32 v243, s42, v243
	v_and_b32_e32 v254, s42, v254
	v_dot4c_i32_i8_e32 v206, v243, v70
	v_dot4c_i32_i8_e32 v205, v254, v70
	v_and_b32_e32 v61, s42, v61
	v_and_b32_e32 v25, s42, v25
	v_dot4c_i32_i8_e32 v206, v61, v71
	v_dot4c_i32_i8_e32 v205, v25, v71
	v_lshlrev_b32_e32 v243, 4, v62
	v_lshlrev_b32_e32 v254, 4, v26
	v_and_b32_e32 v243, s42, v243
	v_and_b32_e32 v254, s42, v254
	v_dot4c_i32_i8_e32 v206, v243, v64
	v_dot4c_i32_i8_e32 v205, v254, v64
	v_and_b32_e32 v62, s42, v62
	v_and_b32_e32 v26, s42, v26
	v_dot4c_i32_i8_e32 v206, v62, v65
	v_dot4c_i32_i8_e32 v205, v26, v65
	v_lshlrev_b32_e32 v243, 4, v63
	v_lshlrev_b32_e32 v254, 4, v27
	v_and_b32_e32 v243, s42, v243
	v_and_b32_e32 v254, s42, v254
	v_dot4c_i32_i8_e32 v206, v243, v66
	v_dot4c_i32_i8_e32 v205, v254, v66
	v_and_b32_e32 v63, s42, v63
	v_and_b32_e32 v27, s42, v27
	v_dot4c_i32_i8_e32 v206, v63, v67
	v_dot4c_i32_i8_e32 v205, v27, v67
	v_add_u32_e32 v60, v74, v242
	v_add_u32_e32 v24, v75, v242
	global_load_dwordx4 v[60:63], v60, s[4:5]
	global_load_dwordx4 v[24:27], v24, s[4:5]
	ds_read_b128 v[68:71], v241 offset:512
	ds_read_b128 v[64:67], v241 offset:528
	ds_read_b128 v[244:247], v238 offset:12288
	ds_read_b128 v[248:251], v238 offset:12304
	ds_read_b128 v[76:79], v238 offset:12320
	ds_read_b128 v[72:75], v238 offset:12336
	s_waitcnt vmcnt(14) lgkmcnt(4)
	v_lshlrev_b32_e32 v243, 4, v44
	v_lshlrev_b32_e32 v254, 4, v28
	v_and_b32_e32 v243, s42, v243
	v_and_b32_e32 v254, s42, v254
	v_dot4c_i32_i8_e32 v204, v243, v68
	v_dot4c_i32_i8_e32 v203, v254, v68
	v_and_b32_e32 v44, s42, v44
	v_and_b32_e32 v28, s42, v28
	v_dot4c_i32_i8_e32 v204, v44, v69
	v_dot4c_i32_i8_e32 v203, v28, v69
	v_lshlrev_b32_e32 v243, 4, v45
	v_lshlrev_b32_e32 v254, 4, v29
	v_and_b32_e32 v243, s42, v243
	v_and_b32_e32 v254, s42, v254
	v_dot4c_i32_i8_e32 v204, v243, v70
	v_dot4c_i32_i8_e32 v203, v254, v70
	v_and_b32_e32 v45, s42, v45
	v_and_b32_e32 v29, s42, v29
	v_dot4c_i32_i8_e32 v204, v45, v71
	v_dot4c_i32_i8_e32 v203, v29, v71
	v_lshlrev_b32_e32 v243, 4, v46
	v_lshlrev_b32_e32 v254, 4, v30
	v_and_b32_e32 v243, s42, v243
	v_and_b32_e32 v254, s42, v254
	v_dot4c_i32_i8_e32 v204, v243, v64
	v_dot4c_i32_i8_e32 v203, v254, v64
	v_and_b32_e32 v46, s42, v46
	v_and_b32_e32 v30, s42, v30
	v_dot4c_i32_i8_e32 v204, v46, v65
	v_dot4c_i32_i8_e32 v203, v30, v65
	v_lshlrev_b32_e32 v243, 4, v47
	v_lshlrev_b32_e32 v254, 4, v31
	v_and_b32_e32 v243, s42, v243
	v_and_b32_e32 v254, s42, v254
	v_dot4c_i32_i8_e32 v204, v243, v66
	v_dot4c_i32_i8_e32 v203, v254, v66
	v_and_b32_e32 v47, s42, v47
	v_and_b32_e32 v31, s42, v31
	v_dot4c_i32_i8_e32 v204, v47, v67
	v_dot4c_i32_i8_e32 v203, v31, v67
	s_waitcnt lgkmcnt(3)
	v_add_u32_e32 v44, v244, v242
	v_add_u32_e32 v28, v245, v242
	global_load_dwordx4 v[44:47], v44, s[4:5]
	global_load_dwordx4 v[28:31], v28, s[4:5]
	s_waitcnt vmcnt(14)
	v_lshlrev_b32_e32 v243, 4, v32
	v_lshlrev_b32_e32 v254, 4, v0
	v_and_b32_e32 v243, s42, v243
	v_and_b32_e32 v254, s42, v254
	v_dot4c_i32_i8_e32 v202, v243, v68
	v_dot4c_i32_i8_e32 v201, v254, v68
	v_and_b32_e32 v32, s42, v32
	v_and_b32_e32 v0, s42, v0
	v_dot4c_i32_i8_e32 v202, v32, v69
	v_dot4c_i32_i8_e32 v201, v0, v69
	v_lshlrev_b32_e32 v243, 4, v33
	v_lshlrev_b32_e32 v254, 4, v1
	v_and_b32_e32 v243, s42, v243
	v_and_b32_e32 v254, s42, v254
	v_dot4c_i32_i8_e32 v202, v243, v70
	v_dot4c_i32_i8_e32 v201, v254, v70
	v_and_b32_e32 v33, s42, v33
	v_and_b32_e32 v1, s42, v1
	v_dot4c_i32_i8_e32 v202, v33, v71
	v_dot4c_i32_i8_e32 v201, v1, v71
	v_lshlrev_b32_e32 v243, 4, v34
	v_lshlrev_b32_e32 v254, 4, v2
	v_and_b32_e32 v243, s42, v243
	v_and_b32_e32 v254, s42, v254
	v_dot4c_i32_i8_e32 v202, v243, v64
	v_dot4c_i32_i8_e32 v201, v254, v64
	v_and_b32_e32 v34, s42, v34
	v_and_b32_e32 v2, s42, v2
	v_dot4c_i32_i8_e32 v202, v34, v65
	v_dot4c_i32_i8_e32 v201, v2, v65
	v_lshlrev_b32_e32 v243, 4, v35
	v_lshlrev_b32_e32 v254, 4, v3
	v_and_b32_e32 v243, s42, v243
	v_and_b32_e32 v254, s42, v254
	v_dot4c_i32_i8_e32 v202, v243, v66
	v_dot4c_i32_i8_e32 v201, v254, v66
	v_and_b32_e32 v35, s42, v35
	v_and_b32_e32 v3, s42, v3
	v_dot4c_i32_i8_e32 v202, v35, v67
	v_dot4c_i32_i8_e32 v201, v3, v67
	v_add_u32_e32 v32, v246, v242
	v_add_u32_e32 v0, v247, v242
	global_load_dwordx4 v[32:35], v32, s[4:5]
	global_load_dwordx4 v[0:3], v0, s[4:5]
	s_waitcnt vmcnt(14)
; __device__ __forceinline__ void p8_peer_gather(Frame& F) {
;     ...
;                 const v4u xr0 = *(const v4u*)(xs_w + q * 256 + 32 * sub), xr1 = *(const v4u*)(xs_w + q * 256 + 32 * sub + 16);
;                 const int xg[8] = {(int)xr0.x, (int)xr0.y, (int)xr0.z, (int)xr0.w, (int)xr1.x, (int)xr1.y, (int)xr1.z, (int)xr1.w};
; #pragma unroll
;                 for (int i = 0; i < 16; ++i) { int a = acc[q][i];
; #pragma unroll
;                     for (int g = 0; g < 4; ++g) { const unsigned w = d[i][g];
;                         a = __builtin_amdgcn_sdot4((int)((w << 4) & 0xf0f0f0f0u), xg[2 * g], a, false);
;                         a = __builtin_amdgcn_sdot4((int)(w & 0xf0f0f0f0u), xg[2 * g + 1], a, false); }
;                     acc[q][i] = a;
;                     d[i] = *(const v4u*)(UQ + (size_t)(idx_s[nj * 128 + pg * 16 + i] + noff)); }
	v_lshlrev_b32_e32 v243, 4, v36
	v_lshlrev_b32_e32 v254, 4, v4
	v_and_b32_e32 v243, s42, v243
	v_and_b32_e32 v254, s42, v254
	v_dot4c_i32_i8_e32 v200, v243, v68
	v_dot4c_i32_i8_e32 v199, v254, v68
	v_and_b32_e32 v36, s42, v36
	v_and_b32_e32 v4, s42, v4
	v_dot4c_i32_i8_e32 v200, v36, v69
	v_dot4c_i32_i8_e32 v199, v4, v69
	v_lshlrev_b32_e32 v243, 4, v37
	v_lshlrev_b32_e32 v254, 4, v5
	v_and_b32_e32 v243, s42, v243
	v_and_b32_e32 v254, s42, v254
	v_dot4c_i32_i8_e32 v200, v243, v70
	v_dot4c_i32_i8_e32 v199, v254, v70
	v_and_b32_e32 v37, s42, v37
	v_and_b32_e32 v5, s42, v5
	v_dot4c_i32_i8_e32 v200, v37, v71
	v_dot4c_i32_i8_e32 v199, v5, v71
	v_lshlrev_b32_e32 v243, 4, v38
	v_lshlrev_b32_e32 v254, 4, v6
	v_and_b32_e32 v243, s42, v243
	v_and_b32_e32 v254, s42, v254
	v_dot4c_i32_i8_e32 v200, v243, v64
	v_dot4c_i32_i8_e32 v199, v254, v64
	v_and_b32_e32 v38, s42, v38
	v_and_b32_e32 v6, s42, v6
	v_dot4c_i32_i8_e32 v200, v38, v65
	v_dot4c_i32_i8_e32 v199, v6, v65
	v_lshlrev_b32_e32 v243, 4, v39
	v_lshlrev_b32_e32 v254, 4, v7
	v_and_b32_e32 v243, s42, v243
	v_and_b32_e32 v254, s42, v254
	v_dot4c_i32_i8_e32 v200, v243, v66
	v_dot4c_i32_i8_e32 v199, v254, v66
	v_and_b32_e32 v39, s42, v39
	v_and_b32_e32 v7, s42, v7
	v_dot4c_i32_i8_e32 v200, v39, v67
	v_dot4c_i32_i8_e32 v199, v7, v67
	s_waitcnt lgkmcnt(2)
	v_add_u32_e32 v36, v248, v242
	v_add_u32_e32 v4, v249, v242
	global_load_dwordx4 v[36:39], v36, s[4:5]
	global_load_dwordx4 v[4:7], v4, s[4:5]
	s_waitcnt vmcnt(14)
	v_lshlrev_b32_e32 v243, 4, v40
	v_lshlrev_b32_e32 v254, 4, v8
	v_and_b32_e32 v243, s42, v243
	v_and_b32_e32 v254, s42, v254
	v_dot4c_i32_i8_e32 v198, v243, v68
	v_dot4c_i32_i8_e32 v197, v254, v68
	v_and_b32_e32 v40, s42, v40
	v_and_b32_e32 v8, s42, v8
	v_dot4c_i32_i8_e32 v198, v40, v69
	v_dot4c_i32_i8_e32 v197, v8, v69
	v_lshlrev_b32_e32 v243, 4, v41
	v_lshlrev_b32_e32 v254, 4, v9
	v_and_b32_e32 v243, s42, v243
	v_and_b32_e32 v254, s42, v254
	v_dot4c_i32_i8_e32 v198, v243, v70
	v_dot4c_i32_i8_e32 v197, v254, v70
	v_and_b32_e32 v41, s42, v41
	v_and_b32_e32 v9, s42, v9
	v_dot4c_i32_i8_e32 v198, v41, v71
	v_dot4c_i32_i8_e32 v197, v9, v71
	v_lshlrev_b32_e32 v243, 4, v42
	v_lshlrev_b32_e32 v254, 4, v10
	v_and_b32_e32 v243, s42, v243
	v_and_b32_e32 v254, s42, v254
	v_dot4c_i32_i8_e32 v198, v243, v64
	v_dot4c_i32_i8_e32 v197, v254, v64
	v_and_b32_e32 v42, s42, v42
	v_and_b32_e32 v10, s42, v10
	v_dot4c_i32_i8_e32 v198, v42, v65
	v_dot4c_i32_i8_e32 v197, v10, v65
	v_lshlrev_b32_e32 v243, 4, v43
	v_lshlrev_b32_e32 v254, 4, v11
	v_and_b32_e32 v243, s42, v243
	v_and_b32_e32 v254, s42, v254
	v_dot4c_i32_i8_e32 v198, v243, v66
	v_dot4c_i32_i8_e32 v197, v254, v66
	v_and_b32_e32 v43, s42, v43
	v_and_b32_e32 v11, s42, v11
	v_dot4c_i32_i8_e32 v198, v43, v67
	v_dot4c_i32_i8_e32 v197, v11, v67
	v_add_u32_e32 v40, v250, v242
	v_add_u32_e32 v8, v251, v242
	global_load_dwordx4 v[40:43], v40, s[4:5]
	global_load_dwordx4 v[8:11], v8, s[4:5]
	s_waitcnt vmcnt(14)
	v_lshlrev_b32_e32 v243, 4, v48
	v_lshlrev_b32_e32 v254, 4, v12
	v_and_b32_e32 v243, s42, v243
	v_and_b32_e32 v254, s42, v254
	v_dot4c_i32_i8_e32 v196, v243, v68
	v_dot4c_i32_i8_e32 v195, v254, v68
	v_and_b32_e32 v48, s42, v48
	v_and_b32_e32 v12, s42, v12
	v_dot4c_i32_i8_e32 v196, v48, v69
	v_dot4c_i32_i8_e32 v195, v12, v69
	v_lshlrev_b32_e32 v243, 4, v49
	v_lshlrev_b32_e32 v254, 4, v13
	v_and_b32_e32 v243, s42, v243
	v_and_b32_e32 v254, s42, v254
	v_dot4c_i32_i8_e32 v196, v243, v70
	v_dot4c_i32_i8_e32 v195, v254, v70
	v_and_b32_e32 v49, s42, v49
	v_and_b32_e32 v13, s42, v13
	v_dot4c_i32_i8_e32 v196, v49, v71
	v_dot4c_i32_i8_e32 v195, v13, v71
	v_lshlrev_b32_e32 v243, 4, v50
	v_lshlrev_b32_e32 v254, 4, v14
	v_and_b32_e32 v243, s42, v243
	v_and_b32_e32 v254, s42, v254
	v_dot4c_i32_i8_e32 v196, v243, v64
	v_dot4c_i32_i8_e32 v195, v254, v64
	v_and_b32_e32 v50, s42, v50
	v_and_b32_e32 v14, s42, v14
	v_dot4c_i32_i8_e32 v196, v50, v65
	v_dot4c_i32_i8_e32 v195, v14, v65
	v_lshlrev_b32_e32 v243, 4, v51
	v_lshlrev_b32_e32 v254, 4, v15
	v_and_b32_e32 v243, s42, v243
	v_and_b32_e32 v254, s42, v254
	v_dot4c_i32_i8_e32 v196, v243, v66
	v_dot4c_i32_i8_e32 v195, v254, v66
	v_and_b32_e32 v51, s42, v51
	v_and_b32_e32 v15, s42, v15
	v_dot4c_i32_i8_e32 v196, v51, v67
	v_dot4c_i32_i8_e32 v195, v15, v67
	s_waitcnt lgkmcnt(1)
	v_add_u32_e32 v48, v76, v242
	v_add_u32_e32 v12, v77, v242
	global_load_dwordx4 v[48:51], v48, s[4:5]
	global_load_dwordx4 v[12:15], v12, s[4:5]
	s_waitcnt vmcnt(14)
	v_lshlrev_b32_e32 v243, 4, v52
	v_lshlrev_b32_e32 v254, 4, v16
	v_and_b32_e32 v243, s42, v243
	v_and_b32_e32 v254, s42, v254
	v_dot4c_i32_i8_e32 v194, v243, v68
	v_dot4c_i32_i8_e32 v193, v254, v68
	v_and_b32_e32 v52, s42, v52
	v_and_b32_e32 v16, s42, v16
	v_dot4c_i32_i8_e32 v194, v52, v69
	v_dot4c_i32_i8_e32 v193, v16, v69
	v_lshlrev_b32_e32 v243, 4, v53
	v_lshlrev_b32_e32 v254, 4, v17
	v_and_b32_e32 v243, s42, v243
	v_and_b32_e32 v254, s42, v254
	v_dot4c_i32_i8_e32 v194, v243, v70
	v_dot4c_i32_i8_e32 v193, v254, v70
	v_and_b32_e32 v53, s42, v53
	v_and_b32_e32 v17, s42, v17
	v_dot4c_i32_i8_e32 v194, v53, v71
	v_dot4c_i32_i8_e32 v193, v17, v71
	v_lshlrev_b32_e32 v243, 4, v54
	v_lshlrev_b32_e32 v254, 4, v18
	v_and_b32_e32 v243, s42, v243
	v_and_b32_e32 v254, s42, v254
	v_dot4c_i32_i8_e32 v194, v243, v64
	v_dot4c_i32_i8_e32 v193, v254, v64
	v_and_b32_e32 v54, s42, v54
	v_and_b32_e32 v18, s42, v18
	v_dot4c_i32_i8_e32 v194, v54, v65
	v_dot4c_i32_i8_e32 v193, v18, v65
	v_lshlrev_b32_e32 v243, 4, v55
	v_lshlrev_b32_e32 v254, 4, v19
	v_and_b32_e32 v243, s42, v243
	v_and_b32_e32 v254, s42, v254
	v_dot4c_i32_i8_e32 v194, v243, v66
	v_dot4c_i32_i8_e32 v193, v254, v66
	v_and_b32_e32 v55, s42, v55
	v_and_b32_e32 v19, s42, v19
	v_dot4c_i32_i8_e32 v194, v55, v67
	v_dot4c_i32_i8_e32 v193, v19, v67
	v_add_u32_e32 v52, v78, v242
	v_add_u32_e32 v16, v79, v242
	global_load_dwordx4 v[52:55], v52, s[4:5]
	global_load_dwordx4 v[16:19], v16, s[4:5]
	s_waitcnt vmcnt(14)
; __device__ __forceinline__ void p8_peer_gather(Frame& F) {
;     ...
;                 const v4u xr0 = *(const v4u*)(xs_w + q * 256 + 32 * sub), xr1 = *(const v4u*)(xs_w + q * 256 + 32 * sub + 16);
;                 const int xg[8] = {(int)xr0.x, (int)xr0.y, (int)xr0.z, (int)xr0.w, (int)xr1.x, (int)xr1.y, (int)xr1.z, (int)xr1.w};
; #pragma unroll
;                 for (int i = 0; i < 16; ++i) { int a = acc[q][i];
; #pragma unroll
;                     for (int g = 0; g < 4; ++g) { const unsigned w = d[i][g];
;                         a = __builtin_amdgcn_sdot4((int)((w << 4) & 0xf0f0f0f0u), xg[2 * g], a, false);
;                         a = __builtin_amdgcn_sdot4((int)(w & 0xf0f0f0f0u), xg[2 * g + 1], a, false); }
;                     acc[q][i] = a;
;                     d[i] = *(const v4u*)(UQ + (size_t)(idx_s[nj * 128 + pg * 16 + i] + noff)); }
	v_lshlrev_b32_e32 v243, 4, v56
	v_lshlrev_b32_e32 v254, 4, v20
	v_and_b32_e32 v243, s42, v243
	v_and_b32_e32 v254, s42, v254
	v_dot4c_i32_i8_e32 v192, v243, v68
	v_dot4c_i32_i8_e32 v191, v254, v68
	v_and_b32_e32 v56, s42, v56
	v_and_b32_e32 v20, s42, v20
	v_dot4c_i32_i8_e32 v192, v56, v69
	v_dot4c_i32_i8_e32 v191, v20, v69
	v_lshlrev_b32_e32 v243, 4, v57
	v_lshlrev_b32_e32 v254, 4, v21
	v_and_b32_e32 v243, s42, v243
	v_and_b32_e32 v254, s42, v254
	v_dot4c_i32_i8_e32 v192, v243, v70
	v_dot4c_i32_i8_e32 v191, v254, v70
	v_and_b32_e32 v57, s42, v57
	v_and_b32_e32 v21, s42, v21
	v_dot4c_i32_i8_e32 v192, v57, v71
	v_dot4c_i32_i8_e32 v191, v21, v71
	v_lshlrev_b32_e32 v243, 4, v58
	v_lshlrev_b32_e32 v254, 4, v22
	v_and_b32_e32 v243, s42, v243
	v_and_b32_e32 v254, s42, v254
	v_dot4c_i32_i8_e32 v192, v243, v64
	v_dot4c_i32_i8_e32 v191, v254, v64
	v_and_b32_e32 v58, s42, v58
	v_and_b32_e32 v22, s42, v22
	v_dot4c_i32_i8_e32 v192, v58, v65
	v_dot4c_i32_i8_e32 v191, v22, v65
	v_lshlrev_b32_e32 v243, 4, v59
	v_lshlrev_b32_e32 v254, 4, v23
	v_and_b32_e32 v243, s42, v243
	v_and_b32_e32 v254, s42, v254
	v_dot4c_i32_i8_e32 v192, v243, v66
	v_dot4c_i32_i8_e32 v191, v254, v66
	v_and_b32_e32 v59, s42, v59
	v_and_b32_e32 v23, s42, v23
	v_dot4c_i32_i8_e32 v192, v59, v67
	v_dot4c_i32_i8_e32 v191, v23, v67
	s_waitcnt lgkmcnt(0)
	v_add_u32_e32 v56, v72, v242
	v_add_u32_e32 v20, v73, v242
	global_load_dwordx4 v[56:59], v56, s[4:5]
	global_load_dwordx4 v[20:23], v20, s[4:5]
	s_waitcnt vmcnt(14)
	v_lshlrev_b32_e32 v243, 4, v60
	v_lshlrev_b32_e32 v254, 4, v24
	v_and_b32_e32 v243, s42, v243
	v_and_b32_e32 v254, s42, v254
	v_dot4c_i32_i8_e32 v190, v243, v68
	v_dot4c_i32_i8_e32 v189, v254, v68
	v_and_b32_e32 v60, s42, v60
	v_and_b32_e32 v24, s42, v24
	v_dot4c_i32_i8_e32 v190, v60, v69
	v_dot4c_i32_i8_e32 v189, v24, v69
	v_lshlrev_b32_e32 v243, 4, v61
	v_lshlrev_b32_e32 v254, 4, v25
	v_and_b32_e32 v243, s42, v243
	v_and_b32_e32 v254, s42, v254
	v_dot4c_i32_i8_e32 v190, v243, v70
	v_dot4c_i32_i8_e32 v189, v254, v70
	v_and_b32_e32 v61, s42, v61
	v_and_b32_e32 v25, s42, v25
	v_dot4c_i32_i8_e32 v190, v61, v71
	v_dot4c_i32_i8_e32 v189, v25, v71
	v_lshlrev_b32_e32 v243, 4, v62
	v_lshlrev_b32_e32 v254, 4, v26
	v_and_b32_e32 v243, s42, v243
	v_and_b32_e32 v254, s42, v254
	v_dot4c_i32_i8_e32 v190, v243, v64
	v_dot4c_i32_i8_e32 v189, v254, v64
	v_and_b32_e32 v62, s42, v62
	v_and_b32_e32 v26, s42, v26
	v_dot4c_i32_i8_e32 v190, v62, v65
	v_dot4c_i32_i8_e32 v189, v26, v65
	v_lshlrev_b32_e32 v243, 4, v63
	v_lshlrev_b32_e32 v254, 4, v27
	v_and_b32_e32 v243, s42, v243
	v_and_b32_e32 v254, s42, v254
	v_dot4c_i32_i8_e32 v190, v243, v66
	v_dot4c_i32_i8_e32 v189, v254, v66
	v_and_b32_e32 v63, s42, v63
	v_and_b32_e32 v27, s42, v27
	v_dot4c_i32_i8_e32 v190, v63, v67
	v_dot4c_i32_i8_e32 v189, v27, v67
	v_add_u32_e32 v60, v74, v242
	v_add_u32_e32 v24, v75, v242
	global_load_dwordx4 v[60:63], v60, s[4:5]
	global_load_dwordx4 v[24:27], v24, s[4:5]
	ds_read_b128 v[68:71], v241 offset:768
	ds_read_b128 v[64:67], v241 offset:784
	ds_read_b128 v[244:247], v238 offset:16384
	ds_read_b128 v[248:251], v238 offset:16400
	ds_read_b128 v[76:79], v238 offset:16416
	ds_read_b128 v[72:75], v238 offset:16432
	s_waitcnt vmcnt(14) lgkmcnt(4)
	v_lshlrev_b32_e32 v243, 4, v44
	v_lshlrev_b32_e32 v254, 4, v28
	v_and_b32_e32 v243, s42, v243
	v_and_b32_e32 v254, s42, v254
	v_dot4c_i32_i8_e32 v188, v243, v68
	v_dot4c_i32_i8_e32 v187, v254, v68
	v_and_b32_e32 v44, s42, v44
	v_and_b32_e32 v28, s42, v28
	v_dot4c_i32_i8_e32 v188, v44, v69
	v_dot4c_i32_i8_e32 v187, v28, v69
	v_lshlrev_b32_e32 v243, 4, v45
	v_lshlrev_b32_e32 v254, 4, v29
	v_and_b32_e32 v243, s42, v243
	v_and_b32_e32 v254, s42, v254
	v_dot4c_i32_i8_e32 v188, v243, v70
	v_dot4c_i32_i8_e32 v187, v254, v70
	v_and_b32_e32 v45, s42, v45
	v_and_b32_e32 v29, s42, v29
	v_dot4c_i32_i8_e32 v188, v45, v71
	v_dot4c_i32_i8_e32 v187, v29, v71
	v_lshlrev_b32_e32 v243, 4, v46
	v_lshlrev_b32_e32 v254, 4, v30
	v_and_b32_e32 v243, s42, v243
	v_and_b32_e32 v254, s42, v254
	v_dot4c_i32_i8_e32 v188, v243, v64
	v_dot4c_i32_i8_e32 v187, v254, v64
	v_and_b32_e32 v46, s42, v46
	v_and_b32_e32 v30, s42, v30
	v_dot4c_i32_i8_e32 v188, v46, v65
	v_dot4c_i32_i8_e32 v187, v30, v65
	v_lshlrev_b32_e32 v243, 4, v47
	v_lshlrev_b32_e32 v254, 4, v31
	v_and_b32_e32 v243, s42, v243
	v_and_b32_e32 v254, s42, v254
	v_dot4c_i32_i8_e32 v188, v243, v66
	v_dot4c_i32_i8_e32 v187, v254, v66
	v_and_b32_e32 v47, s42, v47
	v_and_b32_e32 v31, s42, v31
	v_dot4c_i32_i8_e32 v188, v47, v67
	v_dot4c_i32_i8_e32 v187, v31, v67
	s_waitcnt lgkmcnt(3)
	v_add_u32_e32 v44, v244, v242
	v_add_u32_e32 v28, v245, v242
	global_load_dwordx4 v[44:47], v44, s[4:5]
	global_load_dwordx4 v[28:31], v28, s[4:5]
	s_waitcnt vmcnt(14)
	v_lshlrev_b32_e32 v243, 4, v32
	v_lshlrev_b32_e32 v254, 4, v0
	v_and_b32_e32 v243, s42, v243
	v_and_b32_e32 v254, s42, v254
	v_dot4c_i32_i8_e32 v186, v243, v68
	v_dot4c_i32_i8_e32 v185, v254, v68
	v_and_b32_e32 v32, s42, v32
	v_and_b32_e32 v0, s42, v0
	v_dot4c_i32_i8_e32 v186, v32, v69
	v_dot4c_i32_i8_e32 v185, v0, v69
	v_lshlrev_b32_e32 v243, 4, v33
	v_lshlrev_b32_e32 v254, 4, v1
	v_and_b32_e32 v243, s42, v243
	v_and_b32_e32 v254, s42, v254
	v_dot4c_i32_i8_e32 v186, v243, v70
	v_dot4c_i32_i8_e32 v185, v254, v70
	v_and_b32_e32 v33, s42, v33
	v_and_b32_e32 v1, s42, v1
	v_dot4c_i32_i8_e32 v186, v33, v71
	v_dot4c_i32_i8_e32 v185, v1, v71
	v_lshlrev_b32_e32 v243, 4, v34
	v_lshlrev_b32_e32 v254, 4, v2
	v_and_b32_e32 v243, s42, v243
	v_and_b32_e32 v254, s42, v254
	v_dot4c_i32_i8_e32 v186, v243, v64
	v_dot4c_i32_i8_e32 v185, v254, v64
	v_and_b32_e32 v34, s42, v34
	v_and_b32_e32 v2, s42, v2
	v_dot4c_i32_i8_e32 v186, v34, v65
	v_dot4c_i32_i8_e32 v185, v2, v65
	v_lshlrev_b32_e32 v243, 4, v35
	v_lshlrev_b32_e32 v254, 4, v3
	v_and_b32_e32 v243, s42, v243
	v_and_b32_e32 v254, s42, v254
	v_dot4c_i32_i8_e32 v186, v243, v66
	v_dot4c_i32_i8_e32 v185, v254, v66
	v_and_b32_e32 v35, s42, v35
	v_and_b32_e32 v3, s42, v3
	v_dot4c_i32_i8_e32 v186, v35, v67
	v_dot4c_i32_i8_e32 v185, v3, v67
	v_add_u32_e32 v32, v246, v242
	v_add_u32_e32 v0, v247, v242
	global_load_dwordx4 v[32:35], v32, s[4:5]
	global_load_dwordx4 v[0:3], v0, s[4:5]
	s_waitcnt vmcnt(14)
; __device__ __forceinline__ void p8_peer_gather(Frame& F) {
;     ...
;                 const v4u xr0 = *(const v4u*)(xs_w + q * 256 + 32 * sub), xr1 = *(const v4u*)(xs_w + q * 256 + 32 * sub + 16);
;                 const int xg[8] = {(int)xr0.x, (int)xr0.y, (int)xr0.z, (int)xr0.w, (int)xr1.x, (int)xr1.y, (int)xr1.z, (int)xr1.w};
; #pragma unroll
;                 for (int i = 0; i < 16; ++i) { int a = acc[q][i];
; #pragma unroll
;                     for (int g = 0; g < 4; ++g) { const unsigned w = d[i][g];
;                         a = __builtin_amdgcn_sdot4((int)((w << 4) & 0xf0f0f0f0u), xg[2 * g], a, false);
;                         a = __builtin_amdgcn_sdot4((int)(w & 0xf0f0f0f0u), xg[2 * g + 1], a, false); }
;                     acc[q][i] = a;
;                     d[i] = *(const v4u*)(UQ + (size_t)(idx_s[nj * 128 + pg * 16 + i] + noff)); }
	v_lshlrev_b32_e32 v243, 4, v36
	v_lshlrev_b32_e32 v254, 4, v4
	v_and_b32_e32 v243, s42, v243
	v_and_b32_e32 v254, s42, v254
	v_dot4c_i32_i8_e32 v184, v243, v68
	v_dot4c_i32_i8_e32 v183, v254, v68
	v_and_b32_e32 v36, s42, v36
	v_and_b32_e32 v4, s42, v4
	v_dot4c_i32_i8_e32 v184, v36, v69
	v_dot4c_i32_i8_e32 v183, v4, v69
	v_lshlrev_b32_e32 v243, 4, v37
	v_lshlrev_b32_e32 v254, 4, v5
	v_and_b32_e32 v243, s42, v243
	v_and_b32_e32 v254, s42, v254
	v_dot4c_i32_i8_e32 v184, v243, v70
	v_dot4c_i32_i8_e32 v183, v254, v70
	v_and_b32_e32 v37, s42, v37
	v_and_b32_e32 v5, s42, v5
	v_dot4c_i32_i8_e32 v184, v37, v71
	v_dot4c_i32_i8_e32 v183, v5, v71
	v_lshlrev_b32_e32 v243, 4, v38
	v_lshlrev_b32_e32 v254, 4, v6
	v_and_b32_e32 v243, s42, v243
	v_and_b32_e32 v254, s42, v254
	v_dot4c_i32_i8_e32 v184, v243, v64
	v_dot4c_i32_i8_e32 v183, v254, v64
	v_and_b32_e32 v38, s42, v38
	v_and_b32_e32 v6, s42, v6
	v_dot4c_i32_i8_e32 v184, v38, v65
	v_dot4c_i32_i8_e32 v183, v6, v65
	v_lshlrev_b32_e32 v243, 4, v39
	v_lshlrev_b32_e32 v254, 4, v7
	v_and_b32_e32 v243, s42, v243
	v_and_b32_e32 v254, s42, v254
	v_dot4c_i32_i8_e32 v184, v243, v66
	v_dot4c_i32_i8_e32 v183, v254, v66
	v_and_b32_e32 v39, s42, v39
	v_and_b32_e32 v7, s42, v7
	v_dot4c_i32_i8_e32 v184, v39, v67
	v_dot4c_i32_i8_e32 v183, v7, v67
	s_waitcnt lgkmcnt(2)
	v_add_u32_e32 v36, v248, v242
	v_add_u32_e32 v4, v249, v242
	global_load_dwordx4 v[36:39], v36, s[4:5]
	global_load_dwordx4 v[4:7], v4, s[4:5]
	s_waitcnt vmcnt(14)
	v_lshlrev_b32_e32 v243, 4, v40
	v_lshlrev_b32_e32 v254, 4, v8
	v_and_b32_e32 v243, s42, v243
	v_and_b32_e32 v254, s42, v254
	v_dot4c_i32_i8_e32 v182, v243, v68
	v_dot4c_i32_i8_e32 v181, v254, v68
	v_and_b32_e32 v40, s42, v40
	v_and_b32_e32 v8, s42, v8
	v_dot4c_i32_i8_e32 v182, v40, v69
	v_dot4c_i32_i8_e32 v181, v8, v69
	v_lshlrev_b32_e32 v243, 4, v41
	v_lshlrev_b32_e32 v254, 4, v9
	v_and_b32_e32 v243, s42, v243
	v_and_b32_e32 v254, s42, v254
	v_dot4c_i32_i8_e32 v182, v243, v70
	v_dot4c_i32_i8_e32 v181, v254, v70
	v_and_b32_e32 v41, s42, v41
	v_and_b32_e32 v9, s42, v9
	v_dot4c_i32_i8_e32 v182, v41, v71
	v_dot4c_i32_i8_e32 v181, v9, v71
	v_lshlrev_b32_e32 v243, 4, v42
	v_lshlrev_b32_e32 v254, 4, v10
	v_and_b32_e32 v243, s42, v243
	v_and_b32_e32 v254, s42, v254
	v_dot4c_i32_i8_e32 v182, v243, v64
	v_dot4c_i32_i8_e32 v181, v254, v64
	v_and_b32_e32 v42, s42, v42
	v_and_b32_e32 v10, s42, v10
	v_dot4c_i32_i8_e32 v182, v42, v65
	v_dot4c_i32_i8_e32 v181, v10, v65
	v_lshlrev_b32_e32 v243, 4, v43
	v_lshlrev_b32_e32 v254, 4, v11
	v_and_b32_e32 v243, s42, v243
	v_and_b32_e32 v254, s42, v254
	v_dot4c_i32_i8_e32 v182, v243, v66
	v_dot4c_i32_i8_e32 v181, v254, v66
	v_and_b32_e32 v43, s42, v43
	v_and_b32_e32 v11, s42, v11
	v_dot4c_i32_i8_e32 v182, v43, v67
	v_dot4c_i32_i8_e32 v181, v11, v67
	v_add_u32_e32 v40, v250, v242
	v_add_u32_e32 v8, v251, v242
	global_load_dwordx4 v[40:43], v40, s[4:5]
	global_load_dwordx4 v[8:11], v8, s[4:5]
	s_waitcnt vmcnt(14)
	v_lshlrev_b32_e32 v243, 4, v48
	v_lshlrev_b32_e32 v254, 4, v12
	v_and_b32_e32 v243, s42, v243
	v_and_b32_e32 v254, s42, v254
	v_dot4c_i32_i8_e32 v180, v243, v68
	v_dot4c_i32_i8_e32 v179, v254, v68
	v_and_b32_e32 v48, s42, v48
	v_and_b32_e32 v12, s42, v12
	v_dot4c_i32_i8_e32 v180, v48, v69
	v_dot4c_i32_i8_e32 v179, v12, v69
	v_lshlrev_b32_e32 v243, 4, v49
	v_lshlrev_b32_e32 v254, 4, v13
	v_and_b32_e32 v243, s42, v243
	v_and_b32_e32 v254, s42, v254
	v_dot4c_i32_i8_e32 v180, v243, v70
	v_dot4c_i32_i8_e32 v179, v254, v70
	v_and_b32_e32 v49, s42, v49
	v_and_b32_e32 v13, s42, v13
	v_dot4c_i32_i8_e32 v180, v49, v71
	v_dot4c_i32_i8_e32 v179, v13, v71
	v_lshlrev_b32_e32 v243, 4, v50
	v_lshlrev_b32_e32 v254, 4, v14
	v_and_b32_e32 v243, s42, v243
	v_and_b32_e32 v254, s42, v254
	v_dot4c_i32_i8_e32 v180, v243, v64
	v_dot4c_i32_i8_e32 v179, v254, v64
	v_and_b32_e32 v50, s42, v50
	v_and_b32_e32 v14, s42, v14
	v_dot4c_i32_i8_e32 v180, v50, v65
	v_dot4c_i32_i8_e32 v179, v14, v65
	v_lshlrev_b32_e32 v243, 4, v51
	v_lshlrev_b32_e32 v254, 4, v15
	v_and_b32_e32 v243, s42, v243
	v_and_b32_e32 v254, s42, v254
	v_dot4c_i32_i8_e32 v180, v243, v66
	v_dot4c_i32_i8_e32 v179, v254, v66
	v_and_b32_e32 v51, s42, v51
	v_and_b32_e32 v15, s42, v15
	v_dot4c_i32_i8_e32 v180, v51, v67
	v_dot4c_i32_i8_e32 v179, v15, v67
	s_waitcnt lgkmcnt(1)
	v_add_u32_e32 v48, v76, v242
	v_add_u32_e32 v12, v77, v242
	global_load_dwordx4 v[48:51], v48, s[4:5]
	global_load_dwordx4 v[12:15], v12, s[4:5]
	s_waitcnt vmcnt(14)
	v_lshlrev_b32_e32 v243, 4, v52
	v_lshlrev_b32_e32 v254, 4, v16
	v_and_b32_e32 v243, s42, v243
	v_and_b32_e32 v254, s42, v254
	v_dot4c_i32_i8_e32 v178, v243, v68
	v_dot4c_i32_i8_e32 v177, v254, v68
	v_and_b32_e32 v52, s42, v52
	v_and_b32_e32 v16, s42, v16
	v_dot4c_i32_i8_e32 v178, v52, v69
	v_dot4c_i32_i8_e32 v177, v16, v69
	v_lshlrev_b32_e32 v243, 4, v53
	v_lshlrev_b32_e32 v254, 4, v17
	v_and_b32_e32 v243, s42, v243
	v_and_b32_e32 v254, s42, v254
	v_dot4c_i32_i8_e32 v178, v243, v70
	v_dot4c_i32_i8_e32 v177, v254, v70
	v_and_b32_e32 v53, s42, v53
	v_and_b32_e32 v17, s42, v17
	v_dot4c_i32_i8_e32 v178, v53, v71
	v_dot4c_i32_i8_e32 v177, v17, v71
	v_lshlrev_b32_e32 v243, 4, v54
	v_lshlrev_b32_e32 v254, 4, v18
	v_and_b32_e32 v243, s42, v243
	v_and_b32_e32 v254, s42, v254
	v_dot4c_i32_i8_e32 v178, v243, v64
	v_dot4c_i32_i8_e32 v177, v254, v64
	v_and_b32_e32 v54, s42, v54
	v_and_b32_e32 v18, s42, v18
	v_dot4c_i32_i8_e32 v178, v54, v65
	v_dot4c_i32_i8_e32 v177, v18, v65
	v_lshlrev_b32_e32 v243, 4, v55
	v_lshlrev_b32_e32 v254, 4, v19
	v_and_b32_e32 v243, s42, v243
	v_and_b32_e32 v254, s42, v254
	v_dot4c_i32_i8_e32 v178, v243, v66
	v_dot4c_i32_i8_e32 v177, v254, v66
	v_and_b32_e32 v55, s42, v55
	v_and_b32_e32 v19, s42, v19
	v_dot4c_i32_i8_e32 v178, v55, v67
	v_dot4c_i32_i8_e32 v177, v19, v67
	v_add_u32_e32 v52, v78, v242
	v_add_u32_e32 v16, v79, v242
	global_load_dwordx4 v[52:55], v52, s[4:5]
	global_load_dwordx4 v[16:19], v16, s[4:5]
	s_waitcnt vmcnt(14)
; __device__ __forceinline__ void p8_peer_gather(Frame& F) {
;     ...
;                 const v4u xr0 = *(const v4u*)(xs_w + q * 256 + 32 * sub), xr1 = *(const v4u*)(xs_w + q * 256 + 32 * sub + 16);
;                 const int xg[8] = {(int)xr0.x, (int)xr0.y, (int)xr0.z, (int)xr0.w, (int)xr1.x, (int)xr1.y, (int)xr1.z, (int)xr1.w};
; #pragma unroll
;                 for (int i = 0; i < 16; ++i) { int a = acc[q][i];
; #pragma unroll
;                     for (int g = 0; g < 4; ++g) { const unsigned w = d[i][g];
;                         a = __builtin_amdgcn_sdot4((int)((w << 4) & 0xf0f0f0f0u), xg[2 * g], a, false);
;                         a = __builtin_amdgcn_sdot4((int)(w & 0xf0f0f0f0u), xg[2 * g + 1], a, false); }
;                     acc[q][i] = a;
;                     d[i] = *(const v4u*)(UQ + (size_t)(idx_s[nj * 128 + pg * 16 + i] + noff)); }
	v_lshlrev_b32_e32 v243, 4, v56
	v_lshlrev_b32_e32 v254, 4, v20
	v_and_b32_e32 v243, s42, v243
	v_and_b32_e32 v254, s42, v254
	v_dot4c_i32_i8_e32 v176, v243, v68
	v_dot4c_i32_i8_e32 v175, v254, v68
	v_and_b32_e32 v56, s42, v56
	v_and_b32_e32 v20, s42, v20
	v_dot4c_i32_i8_e32 v176, v56, v69
	v_dot4c_i32_i8_e32 v175, v20, v69
	v_lshlrev_b32_e32 v243, 4, v57
	v_lshlrev_b32_e32 v254, 4, v21
	v_and_b32_e32 v243, s42, v243
	v_and_b32_e32 v254, s42, v254
	v_dot4c_i32_i8_e32 v176, v243, v70
	v_dot4c_i32_i8_e32 v175, v254, v70
	v_and_b32_e32 v57, s42, v57
	v_and_b32_e32 v21, s42, v21
	v_dot4c_i32_i8_e32 v176, v57, v71
	v_dot4c_i32_i8_e32 v175, v21, v71
	v_lshlrev_b32_e32 v243, 4, v58
	v_lshlrev_b32_e32 v254, 4, v22
	v_and_b32_e32 v243, s42, v243
	v_and_b32_e32 v254, s42, v254
	v_dot4c_i32_i8_e32 v176, v243, v64
	v_dot4c_i32_i8_e32 v175, v254, v64
	v_and_b32_e32 v58, s42, v58
	v_and_b32_e32 v22, s42, v22
	v_dot4c_i32_i8_e32 v176, v58, v65
	v_dot4c_i32_i8_e32 v175, v22, v65
	v_lshlrev_b32_e32 v243, 4, v59
	v_lshlrev_b32_e32 v254, 4, v23
	v_and_b32_e32 v243, s42, v243
	v_and_b32_e32 v254, s42, v254
	v_dot4c_i32_i8_e32 v176, v243, v66
	v_dot4c_i32_i8_e32 v175, v254, v66
	v_and_b32_e32 v59, s42, v59
	v_and_b32_e32 v23, s42, v23
	v_dot4c_i32_i8_e32 v176, v59, v67
	v_dot4c_i32_i8_e32 v175, v23, v67
	s_waitcnt lgkmcnt(0)
	v_add_u32_e32 v56, v72, v242
	v_add_u32_e32 v20, v73, v242
	global_load_dwordx4 v[56:59], v56, s[4:5]
	global_load_dwordx4 v[20:23], v20, s[4:5]
	s_waitcnt vmcnt(14)
	v_lshlrev_b32_e32 v243, 4, v60
	v_lshlrev_b32_e32 v254, 4, v24
	v_and_b32_e32 v243, s42, v243
	v_and_b32_e32 v254, s42, v254
	v_dot4c_i32_i8_e32 v174, v243, v68
	v_dot4c_i32_i8_e32 v173, v254, v68
	v_and_b32_e32 v60, s42, v60
	v_and_b32_e32 v24, s42, v24
	v_dot4c_i32_i8_e32 v174, v60, v69
	v_dot4c_i32_i8_e32 v173, v24, v69
	v_lshlrev_b32_e32 v243, 4, v61
	v_lshlrev_b32_e32 v254, 4, v25
	v_and_b32_e32 v243, s42, v243
	v_and_b32_e32 v254, s42, v254
	v_dot4c_i32_i8_e32 v174, v243, v70
	v_dot4c_i32_i8_e32 v173, v254, v70
	v_and_b32_e32 v61, s42, v61
	v_and_b32_e32 v25, s42, v25
	v_dot4c_i32_i8_e32 v174, v61, v71
	v_dot4c_i32_i8_e32 v173, v25, v71
	v_lshlrev_b32_e32 v243, 4, v62
	v_lshlrev_b32_e32 v254, 4, v26
	v_and_b32_e32 v243, s42, v243
	v_and_b32_e32 v254, s42, v254
	v_dot4c_i32_i8_e32 v174, v243, v64
	v_dot4c_i32_i8_e32 v173, v254, v64
	v_and_b32_e32 v62, s42, v62
	v_and_b32_e32 v26, s42, v26
	v_dot4c_i32_i8_e32 v174, v62, v65
	v_dot4c_i32_i8_e32 v173, v26, v65
	v_lshlrev_b32_e32 v243, 4, v63
	v_lshlrev_b32_e32 v254, 4, v27
	v_and_b32_e32 v243, s42, v243
	v_and_b32_e32 v254, s42, v254
	v_dot4c_i32_i8_e32 v174, v243, v66
	v_dot4c_i32_i8_e32 v173, v254, v66
	v_and_b32_e32 v63, s42, v63
	v_and_b32_e32 v27, s42, v27
	v_dot4c_i32_i8_e32 v174, v63, v67
	v_dot4c_i32_i8_e32 v173, v27, v67
	v_add_u32_e32 v60, v74, v242
	v_add_u32_e32 v24, v75, v242
	global_load_dwordx4 v[60:63], v60, s[4:5]
	global_load_dwordx4 v[24:27], v24, s[4:5]
	ds_read_b128 v[68:71], v241 offset:1024
	ds_read_b128 v[64:67], v241 offset:1040
	ds_read_b128 v[244:247], v238 offset:20480
	ds_read_b128 v[248:251], v238 offset:20496
	ds_read_b128 v[76:79], v238 offset:20512
	ds_read_b128 v[72:75], v238 offset:20528
	s_waitcnt vmcnt(14) lgkmcnt(4)
	v_lshlrev_b32_e32 v243, 4, v44
	v_lshlrev_b32_e32 v254, 4, v28
	v_and_b32_e32 v243, s42, v243
	v_and_b32_e32 v254, s42, v254
	v_dot4c_i32_i8_e32 v172, v243, v68
	v_dot4c_i32_i8_e32 v171, v254, v68
	v_and_b32_e32 v44, s42, v44
	v_and_b32_e32 v28, s42, v28
	v_dot4c_i32_i8_e32 v172, v44, v69
	v_dot4c_i32_i8_e32 v171, v28, v69
	v_lshlrev_b32_e32 v243, 4, v45
	v_lshlrev_b32_e32 v254, 4, v29
	v_and_b32_e32 v243, s42, v243
	v_and_b32_e32 v254, s42, v254
	v_dot4c_i32_i8_e32 v172, v243, v70
	v_dot4c_i32_i8_e32 v171, v254, v70
	v_and_b32_e32 v45, s42, v45
	v_and_b32_e32 v29, s42, v29
	v_dot4c_i32_i8_e32 v172, v45, v71
	v_dot4c_i32_i8_e32 v171, v29, v71
	v_lshlrev_b32_e32 v243, 4, v46
	v_lshlrev_b32_e32 v254, 4, v30
	v_and_b32_e32 v243, s42, v243
	v_and_b32_e32 v254, s42, v254
	v_dot4c_i32_i8_e32 v172, v243, v64
	v_dot4c_i32_i8_e32 v171, v254, v64
	v_and_b32_e32 v46, s42, v46
	v_and_b32_e32 v30, s42, v30
	v_dot4c_i32_i8_e32 v172, v46, v65
	v_dot4c_i32_i8_e32 v171, v30, v65
	v_lshlrev_b32_e32 v243, 4, v47
	v_lshlrev_b32_e32 v254, 4, v31
	v_and_b32_e32 v243, s42, v243
	v_and_b32_e32 v254, s42, v254
	v_dot4c_i32_i8_e32 v172, v243, v66
	v_dot4c_i32_i8_e32 v171, v254, v66
	v_and_b32_e32 v47, s42, v47
	v_and_b32_e32 v31, s42, v31
	v_dot4c_i32_i8_e32 v172, v47, v67
	v_dot4c_i32_i8_e32 v171, v31, v67
	s_waitcnt lgkmcnt(3)
	v_add_u32_e32 v44, v244, v242
	v_add_u32_e32 v28, v245, v242
	global_load_dwordx4 v[44:47], v44, s[4:5]
	global_load_dwordx4 v[28:31], v28, s[4:5]
	s_waitcnt vmcnt(14)
	v_lshlrev_b32_e32 v243, 4, v32
	v_lshlrev_b32_e32 v254, 4, v0
	v_and_b32_e32 v243, s42, v243
	v_and_b32_e32 v254, s42, v254
	v_dot4c_i32_i8_e32 v170, v243, v68
	v_dot4c_i32_i8_e32 v169, v254, v68
	v_and_b32_e32 v32, s42, v32
	v_and_b32_e32 v0, s42, v0
	v_dot4c_i32_i8_e32 v170, v32, v69
	v_dot4c_i32_i8_e32 v169, v0, v69
	v_lshlrev_b32_e32 v243, 4, v33
	v_lshlrev_b32_e32 v254, 4, v1
	v_and_b32_e32 v243, s42, v243
	v_and_b32_e32 v254, s42, v254
	v_dot4c_i32_i8_e32 v170, v243, v70
	v_dot4c_i32_i8_e32 v169, v254, v70
	v_and_b32_e32 v33, s42, v33
	v_and_b32_e32 v1, s42, v1
	v_dot4c_i32_i8_e32 v170, v33, v71
	v_dot4c_i32_i8_e32 v169, v1, v71
	v_lshlrev_b32_e32 v243, 4, v34
	v_lshlrev_b32_e32 v254, 4, v2
	v_and_b32_e32 v243, s42, v243
	v_and_b32_e32 v254, s42, v254
	v_dot4c_i32_i8_e32 v170, v243, v64
	v_dot4c_i32_i8_e32 v169, v254, v64
	v_and_b32_e32 v34, s42, v34
	v_and_b32_e32 v2, s42, v2
	v_dot4c_i32_i8_e32 v170, v34, v65
	v_dot4c_i32_i8_e32 v169, v2, v65
	v_lshlrev_b32_e32 v243, 4, v35
	v_lshlrev_b32_e32 v254, 4, v3
	v_and_b32_e32 v243, s42, v243
	v_and_b32_e32 v254, s42, v254
	v_dot4c_i32_i8_e32 v170, v243, v66
	v_dot4c_i32_i8_e32 v169, v254, v66
	v_and_b32_e32 v35, s42, v35
	v_and_b32_e32 v3, s42, v3
	v_dot4c_i32_i8_e32 v170, v35, v67
	v_dot4c_i32_i8_e32 v169, v3, v67
	v_add_u32_e32 v32, v246, v242
	v_add_u32_e32 v0, v247, v242
	global_load_dwordx4 v[32:35], v32, s[4:5]
	global_load_dwordx4 v[0:3], v0, s[4:5]
	s_waitcnt vmcnt(14)
; __device__ __forceinline__ void p8_peer_gather(Frame& F) {
;     ...
;                 const v4u xr0 = *(const v4u*)(xs_w + q * 256 + 32 * sub), xr1 = *(const v4u*)(xs_w + q * 256 + 32 * sub + 16);
;                 const int xg[8] = {(int)xr0.x, (int)xr0.y, (int)xr0.z, (int)xr0.w, (int)xr1.x, (int)xr1.y, (int)xr1.z, (int)xr1.w};
; #pragma unroll
;                 for (int i = 0; i < 16; ++i) { int a = acc[q][i];
; #pragma unroll
;                     for (int g = 0; g < 4; ++g) { const unsigned w = d[i][g];
;                         a = __builtin_amdgcn_sdot4((int)((w << 4) & 0xf0f0f0f0u), xg[2 * g], a, false);
;                         a = __builtin_amdgcn_sdot4((int)(w & 0xf0f0f0f0u), xg[2 * g + 1], a, false); }
;                     acc[q][i] = a;
;                     d[i] = *(const v4u*)(UQ + (size_t)(idx_s[nj * 128 + pg * 16 + i] + noff)); }
	v_lshlrev_b32_e32 v243, 4, v36
	v_lshlrev_b32_e32 v254, 4, v4
	v_and_b32_e32 v243, s42, v243
	v_and_b32_e32 v254, s42, v254
	v_dot4c_i32_i8_e32 v168, v243, v68
	v_dot4c_i32_i8_e32 v167, v254, v68
	v_and_b32_e32 v36, s42, v36
	v_and_b32_e32 v4, s42, v4
	v_dot4c_i32_i8_e32 v168, v36, v69
	v_dot4c_i32_i8_e32 v167, v4, v69
	v_lshlrev_b32_e32 v243, 4, v37
	v_lshlrev_b32_e32 v254, 4, v5
	v_and_b32_e32 v243, s42, v243
	v_and_b32_e32 v254, s42, v254
	v_dot4c_i32_i8_e32 v168, v243, v70
	v_dot4c_i32_i8_e32 v167, v254, v70
	v_and_b32_e32 v37, s42, v37
	v_and_b32_e32 v5, s42, v5
	v_dot4c_i32_i8_e32 v168, v37, v71
	v_dot4c_i32_i8_e32 v167, v5, v71
	v_lshlrev_b32_e32 v243, 4, v38
	v_lshlrev_b32_e32 v254, 4, v6
	v_and_b32_e32 v243, s42, v243
	v_and_b32_e32 v254, s42, v254
	v_dot4c_i32_i8_e32 v168, v243, v64
	v_dot4c_i32_i8_e32 v167, v254, v64
	v_and_b32_e32 v38, s42, v38
	v_and_b32_e32 v6, s42, v6
	v_dot4c_i32_i8_e32 v168, v38, v65
	v_dot4c_i32_i8_e32 v167, v6, v65
	v_lshlrev_b32_e32 v243, 4, v39
	v_lshlrev_b32_e32 v254, 4, v7
	v_and_b32_e32 v243, s42, v243
	v_and_b32_e32 v254, s42, v254
	v_dot4c_i32_i8_e32 v168, v243, v66
	v_dot4c_i32_i8_e32 v167, v254, v66
	v_and_b32_e32 v39, s42, v39
	v_and_b32_e32 v7, s42, v7
	v_dot4c_i32_i8_e32 v168, v39, v67
	v_dot4c_i32_i8_e32 v167, v7, v67
	s_waitcnt lgkmcnt(2)
	v_add_u32_e32 v36, v248, v242
	v_add_u32_e32 v4, v249, v242
	global_load_dwordx4 v[36:39], v36, s[4:5]
	global_load_dwordx4 v[4:7], v4, s[4:5]
	s_waitcnt vmcnt(14)
	v_lshlrev_b32_e32 v243, 4, v40
	v_lshlrev_b32_e32 v254, 4, v8
	v_and_b32_e32 v243, s42, v243
	v_and_b32_e32 v254, s42, v254
	v_dot4c_i32_i8_e32 v166, v243, v68
	v_dot4c_i32_i8_e32 v165, v254, v68
	v_and_b32_e32 v40, s42, v40
	v_and_b32_e32 v8, s42, v8
	v_dot4c_i32_i8_e32 v166, v40, v69
	v_dot4c_i32_i8_e32 v165, v8, v69
	v_lshlrev_b32_e32 v243, 4, v41
	v_lshlrev_b32_e32 v254, 4, v9
	v_and_b32_e32 v243, s42, v243
	v_and_b32_e32 v254, s42, v254
	v_dot4c_i32_i8_e32 v166, v243, v70
	v_dot4c_i32_i8_e32 v165, v254, v70
	v_and_b32_e32 v41, s42, v41
	v_and_b32_e32 v9, s42, v9
	v_dot4c_i32_i8_e32 v166, v41, v71
	v_dot4c_i32_i8_e32 v165, v9, v71
	v_lshlrev_b32_e32 v243, 4, v42
	v_lshlrev_b32_e32 v254, 4, v10
	v_and_b32_e32 v243, s42, v243
	v_and_b32_e32 v254, s42, v254
	v_dot4c_i32_i8_e32 v166, v243, v64
	v_dot4c_i32_i8_e32 v165, v254, v64
	v_and_b32_e32 v42, s42, v42
	v_and_b32_e32 v10, s42, v10
	v_dot4c_i32_i8_e32 v166, v42, v65
	v_dot4c_i32_i8_e32 v165, v10, v65
	v_lshlrev_b32_e32 v243, 4, v43
	v_lshlrev_b32_e32 v254, 4, v11
	v_and_b32_e32 v243, s42, v243
	v_and_b32_e32 v254, s42, v254
	v_dot4c_i32_i8_e32 v166, v243, v66
	v_dot4c_i32_i8_e32 v165, v254, v66
	v_and_b32_e32 v43, s42, v43
	v_and_b32_e32 v11, s42, v11
	v_dot4c_i32_i8_e32 v166, v43, v67
	v_dot4c_i32_i8_e32 v165, v11, v67
	v_add_u32_e32 v40, v250, v242
	v_add_u32_e32 v8, v251, v242
	global_load_dwordx4 v[40:43], v40, s[4:5]
	global_load_dwordx4 v[8:11], v8, s[4:5]
	s_waitcnt vmcnt(14)
	v_lshlrev_b32_e32 v243, 4, v48
	v_lshlrev_b32_e32 v254, 4, v12
	v_and_b32_e32 v243, s42, v243
	v_and_b32_e32 v254, s42, v254
	v_dot4c_i32_i8_e32 v164, v243, v68
	v_dot4c_i32_i8_e32 v163, v254, v68
	v_and_b32_e32 v48, s42, v48
	v_and_b32_e32 v12, s42, v12
	v_dot4c_i32_i8_e32 v164, v48, v69
	v_dot4c_i32_i8_e32 v163, v12, v69
	v_lshlrev_b32_e32 v243, 4, v49
	v_lshlrev_b32_e32 v254, 4, v13
	v_and_b32_e32 v243, s42, v243
	v_and_b32_e32 v254, s42, v254
	v_dot4c_i32_i8_e32 v164, v243, v70
	v_dot4c_i32_i8_e32 v163, v254, v70
	v_and_b32_e32 v49, s42, v49
	v_and_b32_e32 v13, s42, v13
	v_dot4c_i32_i8_e32 v164, v49, v71
	v_dot4c_i32_i8_e32 v163, v13, v71
	v_lshlrev_b32_e32 v243, 4, v50
	v_lshlrev_b32_e32 v254, 4, v14
	v_and_b32_e32 v243, s42, v243
	v_and_b32_e32 v254, s42, v254
	v_dot4c_i32_i8_e32 v164, v243, v64
	v_dot4c_i32_i8_e32 v163, v254, v64
	v_and_b32_e32 v50, s42, v50
	v_and_b32_e32 v14, s42, v14
	v_dot4c_i32_i8_e32 v164, v50, v65
	v_dot4c_i32_i8_e32 v163, v14, v65
	v_lshlrev_b32_e32 v243, 4, v51
	v_lshlrev_b32_e32 v254, 4, v15
	v_and_b32_e32 v243, s42, v243
	v_and_b32_e32 v254, s42, v254
	v_dot4c_i32_i8_e32 v164, v243, v66
	v_dot4c_i32_i8_e32 v163, v254, v66
	v_and_b32_e32 v51, s42, v51
	v_and_b32_e32 v15, s42, v15
	v_dot4c_i32_i8_e32 v164, v51, v67
	v_dot4c_i32_i8_e32 v163, v15, v67
	s_waitcnt lgkmcnt(1)
	v_add_u32_e32 v48, v76, v242
	v_add_u32_e32 v12, v77, v242
	global_load_dwordx4 v[48:51], v48, s[4:5]
	global_load_dwordx4 v[12:15], v12, s[4:5]
	s_waitcnt vmcnt(14)
	v_lshlrev_b32_e32 v243, 4, v52
	v_lshlrev_b32_e32 v254, 4, v16
	v_and_b32_e32 v243, s42, v243
	v_and_b32_e32 v254, s42, v254
	v_dot4c_i32_i8_e32 v162, v243, v68
	v_dot4c_i32_i8_e32 v161, v254, v68
	v_and_b32_e32 v52, s42, v52
	v_and_b32_e32 v16, s42, v16
	v_dot4c_i32_i8_e32 v162, v52, v69
	v_dot4c_i32_i8_e32 v161, v16, v69
	v_lshlrev_b32_e32 v243, 4, v53
	v_lshlrev_b32_e32 v254, 4, v17
	v_and_b32_e32 v243, s42, v243
	v_and_b32_e32 v254, s42, v254
	v_dot4c_i32_i8_e32 v162, v243, v70
	v_dot4c_i32_i8_e32 v161, v254, v70
	v_and_b32_e32 v53, s42, v53
	v_and_b32_e32 v17, s42, v17
	v_dot4c_i32_i8_e32 v162, v53, v71
	v_dot4c_i32_i8_e32 v161, v17, v71
	v_lshlrev_b32_e32 v243, 4, v54
	v_lshlrev_b32_e32 v254, 4, v18
	v_and_b32_e32 v243, s42, v243
	v_and_b32_e32 v254, s42, v254
	v_dot4c_i32_i8_e32 v162, v243, v64
	v_dot4c_i32_i8_e32 v161, v254, v64
	v_and_b32_e32 v54, s42, v54
	v_and_b32_e32 v18, s42, v18
	v_dot4c_i32_i8_e32 v162, v54, v65
	v_dot4c_i32_i8_e32 v161, v18, v65
	v_lshlrev_b32_e32 v243, 4, v55
	v_lshlrev_b32_e32 v254, 4, v19
	v_and_b32_e32 v243, s42, v243
	v_and_b32_e32 v254, s42, v254
	v_dot4c_i32_i8_e32 v162, v243, v66
	v_dot4c_i32_i8_e32 v161, v254, v66
	v_and_b32_e32 v55, s42, v55
	v_and_b32_e32 v19, s42, v19
	v_dot4c_i32_i8_e32 v162, v55, v67
	v_dot4c_i32_i8_e32 v161, v19, v67
	v_add_u32_e32 v52, v78, v242
	v_add_u32_e32 v16, v79, v242
	global_load_dwordx4 v[52:55], v52, s[4:5]
	global_load_dwordx4 v[16:19], v16, s[4:5]
	s_waitcnt vmcnt(14)
; __device__ __forceinline__ void p8_peer_gather(Frame& F) {
;     ...
;                 const v4u xr0 = *(const v4u*)(xs_w + q * 256 + 32 * sub), xr1 = *(const v4u*)(xs_w + q * 256 + 32 * sub + 16);
;                 const int xg[8] = {(int)xr0.x, (int)xr0.y, (int)xr0.z, (int)xr0.w, (int)xr1.x, (int)xr1.y, (int)xr1.z, (int)xr1.w};
; #pragma unroll
;                 for (int i = 0; i < 16; ++i) { int a = acc[q][i];
; #pragma unroll
;                     for (int g = 0; g < 4; ++g) { const unsigned w = d[i][g];
;                         a = __builtin_amdgcn_sdot4((int)((w << 4) & 0xf0f0f0f0u), xg[2 * g], a, false);
;                         a = __builtin_amdgcn_sdot4((int)(w & 0xf0f0f0f0u), xg[2 * g + 1], a, false); }
;                     acc[q][i] = a;
;                     d[i] = *(const v4u*)(UQ + (size_t)(idx_s[nj * 128 + pg * 16 + i] + noff)); }
	v_lshlrev_b32_e32 v243, 4, v56
	v_lshlrev_b32_e32 v254, 4, v20
	v_and_b32_e32 v243, s42, v243
	v_and_b32_e32 v254, s42, v254
	v_dot4c_i32_i8_e32 v160, v243, v68
	v_dot4c_i32_i8_e32 v159, v254, v68
	v_and_b32_e32 v56, s42, v56
	v_and_b32_e32 v20, s42, v20
	v_dot4c_i32_i8_e32 v160, v56, v69
	v_dot4c_i32_i8_e32 v159, v20, v69
	v_lshlrev_b32_e32 v243, 4, v57
	v_lshlrev_b32_e32 v254, 4, v21
	v_and_b32_e32 v243, s42, v243
	v_and_b32_e32 v254, s42, v254
	v_dot4c_i32_i8_e32 v160, v243, v70
	v_dot4c_i32_i8_e32 v159, v254, v70
	v_and_b32_e32 v57, s42, v57
	v_and_b32_e32 v21, s42, v21
	v_dot4c_i32_i8_e32 v160, v57, v71
	v_dot4c_i32_i8_e32 v159, v21, v71
	v_lshlrev_b32_e32 v243, 4, v58
	v_lshlrev_b32_e32 v254, 4, v22
	v_and_b32_e32 v243, s42, v243
	v_and_b32_e32 v254, s42, v254
	v_dot4c_i32_i8_e32 v160, v243, v64
	v_dot4c_i32_i8_e32 v159, v254, v64
	v_and_b32_e32 v58, s42, v58
	v_and_b32_e32 v22, s42, v22
	v_dot4c_i32_i8_e32 v160, v58, v65
	v_dot4c_i32_i8_e32 v159, v22, v65
	v_lshlrev_b32_e32 v243, 4, v59
	v_lshlrev_b32_e32 v254, 4, v23
	v_and_b32_e32 v243, s42, v243
	v_and_b32_e32 v254, s42, v254
	v_dot4c_i32_i8_e32 v160, v243, v66
	v_dot4c_i32_i8_e32 v159, v254, v66
	v_and_b32_e32 v59, s42, v59
	v_and_b32_e32 v23, s42, v23
	v_dot4c_i32_i8_e32 v160, v59, v67
	v_dot4c_i32_i8_e32 v159, v23, v67
	s_waitcnt lgkmcnt(0)
	v_add_u32_e32 v56, v72, v242
	v_add_u32_e32 v20, v73, v242
	global_load_dwordx4 v[56:59], v56, s[4:5]
	global_load_dwordx4 v[20:23], v20, s[4:5]
	s_waitcnt vmcnt(14)
	v_lshlrev_b32_e32 v243, 4, v60
	v_lshlrev_b32_e32 v254, 4, v24
	v_and_b32_e32 v243, s42, v243
	v_and_b32_e32 v254, s42, v254
	v_dot4c_i32_i8_e32 v158, v243, v68
	v_dot4c_i32_i8_e32 v157, v254, v68
	v_and_b32_e32 v60, s42, v60
	v_and_b32_e32 v24, s42, v24
	v_dot4c_i32_i8_e32 v158, v60, v69
	v_dot4c_i32_i8_e32 v157, v24, v69
	v_lshlrev_b32_e32 v243, 4, v61
	v_lshlrev_b32_e32 v254, 4, v25
	v_and_b32_e32 v243, s42, v243
	v_and_b32_e32 v254, s42, v254
	v_dot4c_i32_i8_e32 v158, v243, v70
	v_dot4c_i32_i8_e32 v157, v254, v70
	v_and_b32_e32 v61, s42, v61
	v_and_b32_e32 v25, s42, v25
	v_dot4c_i32_i8_e32 v158, v61, v71
	v_dot4c_i32_i8_e32 v157, v25, v71
	v_lshlrev_b32_e32 v243, 4, v62
	v_lshlrev_b32_e32 v254, 4, v26
	v_and_b32_e32 v243, s42, v243
	v_and_b32_e32 v254, s42, v254
	v_dot4c_i32_i8_e32 v158, v243, v64
	v_dot4c_i32_i8_e32 v157, v254, v64
	v_and_b32_e32 v62, s42, v62
	v_and_b32_e32 v26, s42, v26
	v_dot4c_i32_i8_e32 v158, v62, v65
	v_dot4c_i32_i8_e32 v157, v26, v65
	v_lshlrev_b32_e32 v243, 4, v63
	v_lshlrev_b32_e32 v254, 4, v27
	v_and_b32_e32 v243, s42, v243
	v_and_b32_e32 v254, s42, v254
	v_dot4c_i32_i8_e32 v158, v243, v66
	v_dot4c_i32_i8_e32 v157, v254, v66
	v_and_b32_e32 v63, s42, v63
	v_and_b32_e32 v27, s42, v27
	v_dot4c_i32_i8_e32 v158, v63, v67
	v_dot4c_i32_i8_e32 v157, v27, v67
	v_add_u32_e32 v60, v74, v242
	v_add_u32_e32 v24, v75, v242
	global_load_dwordx4 v[60:63], v60, s[4:5]
	global_load_dwordx4 v[24:27], v24, s[4:5]
	ds_read_b128 v[68:71], v241 offset:1280
	ds_read_b128 v[64:67], v241 offset:1296
	ds_read_b128 v[244:247], v238 offset:24576
	ds_read_b128 v[248:251], v238 offset:24592
	ds_read_b128 v[76:79], v238 offset:24608
	ds_read_b128 v[72:75], v238 offset:24624
	s_waitcnt vmcnt(14) lgkmcnt(4)
	v_lshlrev_b32_e32 v243, 4, v44
	v_lshlrev_b32_e32 v254, 4, v28
	v_and_b32_e32 v243, s42, v243
	v_and_b32_e32 v254, s42, v254
	v_dot4c_i32_i8_e32 v156, v243, v68
	v_dot4c_i32_i8_e32 v155, v254, v68
	v_and_b32_e32 v44, s42, v44
	v_and_b32_e32 v28, s42, v28
	v_dot4c_i32_i8_e32 v156, v44, v69
	v_dot4c_i32_i8_e32 v155, v28, v69
	v_lshlrev_b32_e32 v243, 4, v45
	v_lshlrev_b32_e32 v254, 4, v29
	v_and_b32_e32 v243, s42, v243
	v_and_b32_e32 v254, s42, v254
	v_dot4c_i32_i8_e32 v156, v243, v70
	v_dot4c_i32_i8_e32 v155, v254, v70
	v_and_b32_e32 v45, s42, v45
	v_and_b32_e32 v29, s42, v29
	v_dot4c_i32_i8_e32 v156, v45, v71
	v_dot4c_i32_i8_e32 v155, v29, v71
	v_lshlrev_b32_e32 v243, 4, v46
	v_lshlrev_b32_e32 v254, 4, v30
	v_and_b32_e32 v243, s42, v243
	v_and_b32_e32 v254, s42, v254
	v_dot4c_i32_i8_e32 v156, v243, v64
	v_dot4c_i32_i8_e32 v155, v254, v64
	v_and_b32_e32 v46, s42, v46
	v_and_b32_e32 v30, s42, v30
	v_dot4c_i32_i8_e32 v156, v46, v65
	v_dot4c_i32_i8_e32 v155, v30, v65
	v_lshlrev_b32_e32 v243, 4, v47
	v_lshlrev_b32_e32 v254, 4, v31
	v_and_b32_e32 v243, s42, v243
	v_and_b32_e32 v254, s42, v254
	v_dot4c_i32_i8_e32 v156, v243, v66
	v_dot4c_i32_i8_e32 v155, v254, v66
	v_and_b32_e32 v47, s42, v47
	v_and_b32_e32 v31, s42, v31
	v_dot4c_i32_i8_e32 v156, v47, v67
	v_dot4c_i32_i8_e32 v155, v31, v67
	s_waitcnt lgkmcnt(3)
	v_add_u32_e32 v44, v244, v242
	v_add_u32_e32 v28, v245, v242
	global_load_dwordx4 v[44:47], v44, s[4:5]
	global_load_dwordx4 v[28:31], v28, s[4:5]
	s_waitcnt vmcnt(14)
	v_lshlrev_b32_e32 v243, 4, v32
	v_lshlrev_b32_e32 v254, 4, v0
	v_and_b32_e32 v243, s42, v243
	v_and_b32_e32 v254, s42, v254
	v_dot4c_i32_i8_e32 v154, v243, v68
	v_dot4c_i32_i8_e32 v153, v254, v68
	v_and_b32_e32 v32, s42, v32
	v_and_b32_e32 v0, s42, v0
	v_dot4c_i32_i8_e32 v154, v32, v69
	v_dot4c_i32_i8_e32 v153, v0, v69
	v_lshlrev_b32_e32 v243, 4, v33
	v_lshlrev_b32_e32 v254, 4, v1
	v_and_b32_e32 v243, s42, v243
	v_and_b32_e32 v254, s42, v254
	v_dot4c_i32_i8_e32 v154, v243, v70
	v_dot4c_i32_i8_e32 v153, v254, v70
	v_and_b32_e32 v33, s42, v33
	v_and_b32_e32 v1, s42, v1
	v_dot4c_i32_i8_e32 v154, v33, v71
	v_dot4c_i32_i8_e32 v153, v1, v71
	v_lshlrev_b32_e32 v243, 4, v34
	v_lshlrev_b32_e32 v254, 4, v2
	v_and_b32_e32 v243, s42, v243
	v_and_b32_e32 v254, s42, v254
	v_dot4c_i32_i8_e32 v154, v243, v64
	v_dot4c_i32_i8_e32 v153, v254, v64
	v_and_b32_e32 v34, s42, v34
	v_and_b32_e32 v2, s42, v2
	v_dot4c_i32_i8_e32 v154, v34, v65
	v_dot4c_i32_i8_e32 v153, v2, v65
	v_lshlrev_b32_e32 v243, 4, v35
	v_lshlrev_b32_e32 v254, 4, v3
	v_and_b32_e32 v243, s42, v243
	v_and_b32_e32 v254, s42, v254
	v_dot4c_i32_i8_e32 v154, v243, v66
	v_dot4c_i32_i8_e32 v153, v254, v66
	v_and_b32_e32 v35, s42, v35
	v_and_b32_e32 v3, s42, v3
	v_dot4c_i32_i8_e32 v154, v35, v67
	v_dot4c_i32_i8_e32 v153, v3, v67
	v_add_u32_e32 v32, v246, v242
	v_add_u32_e32 v0, v247, v242
	global_load_dwordx4 v[32:35], v32, s[4:5]
	global_load_dwordx4 v[0:3], v0, s[4:5]
	s_waitcnt vmcnt(14)
; __device__ __forceinline__ void p8_peer_gather(Frame& F) {
;     ...
;                 const v4u xr0 = *(const v4u*)(xs_w + q * 256 + 32 * sub), xr1 = *(const v4u*)(xs_w + q * 256 + 32 * sub + 16);
;                 const int xg[8] = {(int)xr0.x, (int)xr0.y, (int)xr0.z, (int)xr0.w, (int)xr1.x, (int)xr1.y, (int)xr1.z, (int)xr1.w};
; #pragma unroll
;                 for (int i = 0; i < 16; ++i) { int a = acc[q][i];
; #pragma unroll
;                     for (int g = 0; g < 4; ++g) { const unsigned w = d[i][g];
;                         a = __builtin_amdgcn_sdot4((int)((w << 4) & 0xf0f0f0f0u), xg[2 * g], a, false);
;                         a = __builtin_amdgcn_sdot4((int)(w & 0xf0f0f0f0u), xg[2 * g + 1], a, false); }
;                     acc[q][i] = a;
;                     d[i] = *(const v4u*)(UQ + (size_t)(idx_s[nj * 128 + pg * 16 + i] + noff)); }
	v_lshlrev_b32_e32 v243, 4, v36
	v_lshlrev_b32_e32 v254, 4, v4
	v_and_b32_e32 v243, s42, v243
	v_and_b32_e32 v254, s42, v254
	v_dot4c_i32_i8_e32 v152, v243, v68
	v_dot4c_i32_i8_e32 v151, v254, v68
	v_and_b32_e32 v36, s42, v36
	v_and_b32_e32 v4, s42, v4
	v_dot4c_i32_i8_e32 v152, v36, v69
	v_dot4c_i32_i8_e32 v151, v4, v69
	v_lshlrev_b32_e32 v243, 4, v37
	v_lshlrev_b32_e32 v254, 4, v5
	v_and_b32_e32 v243, s42, v243
	v_and_b32_e32 v254, s42, v254
	v_dot4c_i32_i8_e32 v152, v243, v70
	v_dot4c_i32_i8_e32 v151, v254, v70
	v_and_b32_e32 v37, s42, v37
	v_and_b32_e32 v5, s42, v5
	v_dot4c_i32_i8_e32 v152, v37, v71
	v_dot4c_i32_i8_e32 v151, v5, v71
	v_lshlrev_b32_e32 v243, 4, v38
	v_lshlrev_b32_e32 v254, 4, v6
	v_and_b32_e32 v243, s42, v243
	v_and_b32_e32 v254, s42, v254
	v_dot4c_i32_i8_e32 v152, v243, v64
	v_dot4c_i32_i8_e32 v151, v254, v64
	v_and_b32_e32 v38, s42, v38
	v_and_b32_e32 v6, s42, v6
	v_dot4c_i32_i8_e32 v152, v38, v65
	v_dot4c_i32_i8_e32 v151, v6, v65
	v_lshlrev_b32_e32 v243, 4, v39
	v_lshlrev_b32_e32 v254, 4, v7
	v_and_b32_e32 v243, s42, v243
	v_and_b32_e32 v254, s42, v254
	v_dot4c_i32_i8_e32 v152, v243, v66
	v_dot4c_i32_i8_e32 v151, v254, v66
	v_and_b32_e32 v39, s42, v39
	v_and_b32_e32 v7, s42, v7
	v_dot4c_i32_i8_e32 v152, v39, v67
	v_dot4c_i32_i8_e32 v151, v7, v67
	s_waitcnt lgkmcnt(2)
	v_add_u32_e32 v36, v248, v242
	v_add_u32_e32 v4, v249, v242
	global_load_dwordx4 v[36:39], v36, s[4:5]
	global_load_dwordx4 v[4:7], v4, s[4:5]
	s_waitcnt vmcnt(14)
	v_lshlrev_b32_e32 v243, 4, v40
	v_lshlrev_b32_e32 v254, 4, v8
	v_and_b32_e32 v243, s42, v243
	v_and_b32_e32 v254, s42, v254
	v_dot4c_i32_i8_e32 v150, v243, v68
	v_dot4c_i32_i8_e32 v149, v254, v68
	v_and_b32_e32 v40, s42, v40
	v_and_b32_e32 v8, s42, v8
	v_dot4c_i32_i8_e32 v150, v40, v69
	v_dot4c_i32_i8_e32 v149, v8, v69
	v_lshlrev_b32_e32 v243, 4, v41
	v_lshlrev_b32_e32 v254, 4, v9
	v_and_b32_e32 v243, s42, v243
	v_and_b32_e32 v254, s42, v254
	v_dot4c_i32_i8_e32 v150, v243, v70
	v_dot4c_i32_i8_e32 v149, v254, v70
	v_and_b32_e32 v41, s42, v41
	v_and_b32_e32 v9, s42, v9
	v_dot4c_i32_i8_e32 v150, v41, v71
	v_dot4c_i32_i8_e32 v149, v9, v71
	v_lshlrev_b32_e32 v243, 4, v42
	v_lshlrev_b32_e32 v254, 4, v10
	v_and_b32_e32 v243, s42, v243
	v_and_b32_e32 v254, s42, v254
	v_dot4c_i32_i8_e32 v150, v243, v64
	v_dot4c_i32_i8_e32 v149, v254, v64
	v_and_b32_e32 v42, s42, v42
	v_and_b32_e32 v10, s42, v10
	v_dot4c_i32_i8_e32 v150, v42, v65
	v_dot4c_i32_i8_e32 v149, v10, v65
	v_lshlrev_b32_e32 v243, 4, v43
	v_lshlrev_b32_e32 v254, 4, v11
	v_and_b32_e32 v243, s42, v243
	v_and_b32_e32 v254, s42, v254
	v_dot4c_i32_i8_e32 v150, v243, v66
	v_dot4c_i32_i8_e32 v149, v254, v66
	v_and_b32_e32 v43, s42, v43
	v_and_b32_e32 v11, s42, v11
	v_dot4c_i32_i8_e32 v150, v43, v67
	v_dot4c_i32_i8_e32 v149, v11, v67
	v_add_u32_e32 v40, v250, v242
	v_add_u32_e32 v8, v251, v242
	global_load_dwordx4 v[40:43], v40, s[4:5]
	global_load_dwordx4 v[8:11], v8, s[4:5]
	s_waitcnt vmcnt(14)
	v_lshlrev_b32_e32 v243, 4, v48
	v_lshlrev_b32_e32 v254, 4, v12
	v_and_b32_e32 v243, s42, v243
	v_and_b32_e32 v254, s42, v254
	v_dot4c_i32_i8_e32 v148, v243, v68
	v_dot4c_i32_i8_e32 v147, v254, v68
	v_and_b32_e32 v48, s42, v48
	v_and_b32_e32 v12, s42, v12
	v_dot4c_i32_i8_e32 v148, v48, v69
	v_dot4c_i32_i8_e32 v147, v12, v69
	v_lshlrev_b32_e32 v243, 4, v49
	v_lshlrev_b32_e32 v254, 4, v13
	v_and_b32_e32 v243, s42, v243
	v_and_b32_e32 v254, s42, v254
	v_dot4c_i32_i8_e32 v148, v243, v70
	v_dot4c_i32_i8_e32 v147, v254, v70
	v_and_b32_e32 v49, s42, v49
	v_and_b32_e32 v13, s42, v13
	v_dot4c_i32_i8_e32 v148, v49, v71
	v_dot4c_i32_i8_e32 v147, v13, v71
	v_lshlrev_b32_e32 v243, 4, v50
	v_lshlrev_b32_e32 v254, 4, v14
	v_and_b32_e32 v243, s42, v243
	v_and_b32_e32 v254, s42, v254
	v_dot4c_i32_i8_e32 v148, v243, v64
	v_dot4c_i32_i8_e32 v147, v254, v64
	v_and_b32_e32 v50, s42, v50
	v_and_b32_e32 v14, s42, v14
	v_dot4c_i32_i8_e32 v148, v50, v65
	v_dot4c_i32_i8_e32 v147, v14, v65
	v_lshlrev_b32_e32 v243, 4, v51
	v_lshlrev_b32_e32 v254, 4, v15
	v_and_b32_e32 v243, s42, v243
	v_and_b32_e32 v254, s42, v254
	v_dot4c_i32_i8_e32 v148, v243, v66
	v_dot4c_i32_i8_e32 v147, v254, v66
	v_and_b32_e32 v51, s42, v51
	v_and_b32_e32 v15, s42, v15
	v_dot4c_i32_i8_e32 v148, v51, v67
	v_dot4c_i32_i8_e32 v147, v15, v67
	s_waitcnt lgkmcnt(1)
	v_add_u32_e32 v48, v76, v242
	v_add_u32_e32 v12, v77, v242
	global_load_dwordx4 v[48:51], v48, s[4:5]
	global_load_dwordx4 v[12:15], v12, s[4:5]
	s_waitcnt vmcnt(14)
	v_lshlrev_b32_e32 v243, 4, v52
	v_lshlrev_b32_e32 v254, 4, v16
	v_and_b32_e32 v243, s42, v243
	v_and_b32_e32 v254, s42, v254
	v_dot4c_i32_i8_e32 v146, v243, v68
	v_dot4c_i32_i8_e32 v145, v254, v68
	v_and_b32_e32 v52, s42, v52
	v_and_b32_e32 v16, s42, v16
	v_dot4c_i32_i8_e32 v146, v52, v69
	v_dot4c_i32_i8_e32 v145, v16, v69
	v_lshlrev_b32_e32 v243, 4, v53
	v_lshlrev_b32_e32 v254, 4, v17
	v_and_b32_e32 v243, s42, v243
	v_and_b32_e32 v254, s42, v254
	v_dot4c_i32_i8_e32 v146, v243, v70
	v_dot4c_i32_i8_e32 v145, v254, v70
	v_and_b32_e32 v53, s42, v53
	v_and_b32_e32 v17, s42, v17
	v_dot4c_i32_i8_e32 v146, v53, v71
	v_dot4c_i32_i8_e32 v145, v17, v71
	v_lshlrev_b32_e32 v243, 4, v54
	v_lshlrev_b32_e32 v254, 4, v18
	v_and_b32_e32 v243, s42, v243
	v_and_b32_e32 v254, s42, v254
	v_dot4c_i32_i8_e32 v146, v243, v64
	v_dot4c_i32_i8_e32 v145, v254, v64
	v_and_b32_e32 v54, s42, v54
	v_and_b32_e32 v18, s42, v18
	v_dot4c_i32_i8_e32 v146, v54, v65
	v_dot4c_i32_i8_e32 v145, v18, v65
	v_lshlrev_b32_e32 v243, 4, v55
	v_lshlrev_b32_e32 v254, 4, v19
	v_and_b32_e32 v243, s42, v243
	v_and_b32_e32 v254, s42, v254
	v_dot4c_i32_i8_e32 v146, v243, v66
	v_dot4c_i32_i8_e32 v145, v254, v66
	v_and_b32_e32 v55, s42, v55
	v_and_b32_e32 v19, s42, v19
	v_dot4c_i32_i8_e32 v146, v55, v67
	v_dot4c_i32_i8_e32 v145, v19, v67
	v_add_u32_e32 v52, v78, v242
	v_add_u32_e32 v16, v79, v242
	global_load_dwordx4 v[52:55], v52, s[4:5]
	global_load_dwordx4 v[16:19], v16, s[4:5]
	s_waitcnt vmcnt(14)
; __device__ __forceinline__ void p8_peer_gather(Frame& F) {
;     ...
;                 const v4u xr0 = *(const v4u*)(xs_w + q * 256 + 32 * sub), xr1 = *(const v4u*)(xs_w + q * 256 + 32 * sub + 16);
;                 const int xg[8] = {(int)xr0.x, (int)xr0.y, (int)xr0.z, (int)xr0.w, (int)xr1.x, (int)xr1.y, (int)xr1.z, (int)xr1.w};
; #pragma unroll
;                 for (int i = 0; i < 16; ++i) { int a = acc[q][i];
; #pragma unroll
;                     for (int g = 0; g < 4; ++g) { const unsigned w = d[i][g];
;                         a = __builtin_amdgcn_sdot4((int)((w << 4) & 0xf0f0f0f0u), xg[2 * g], a, false);
;                         a = __builtin_amdgcn_sdot4((int)(w & 0xf0f0f0f0u), xg[2 * g + 1], a, false); }
;                     acc[q][i] = a;
;                     d[i] = *(const v4u*)(UQ + (size_t)(idx_s[nj * 128 + pg * 16 + i] + noff)); }
	v_lshlrev_b32_e32 v243, 4, v56
	v_lshlrev_b32_e32 v254, 4, v20
	v_and_b32_e32 v243, s42, v243
	v_and_b32_e32 v254, s42, v254
	v_dot4c_i32_i8_e32 v144, v243, v68
	v_dot4c_i32_i8_e32 v143, v254, v68
	v_and_b32_e32 v56, s42, v56
	v_and_b32_e32 v20, s42, v20
	v_dot4c_i32_i8_e32 v144, v56, v69
	v_dot4c_i32_i8_e32 v143, v20, v69
	v_lshlrev_b32_e32 v243, 4, v57
	v_lshlrev_b32_e32 v254, 4, v21
	v_and_b32_e32 v243, s42, v243
	v_and_b32_e32 v254, s42, v254
	v_dot4c_i32_i8_e32 v144, v243, v70
	v_dot4c_i32_i8_e32 v143, v254, v70
	v_and_b32_e32 v57, s42, v57
	v_and_b32_e32 v21, s42, v21
	v_dot4c_i32_i8_e32 v144, v57, v71
	v_dot4c_i32_i8_e32 v143, v21, v71
	v_lshlrev_b32_e32 v243, 4, v58
	v_lshlrev_b32_e32 v254, 4, v22
	v_and_b32_e32 v243, s42, v243
	v_and_b32_e32 v254, s42, v254
	v_dot4c_i32_i8_e32 v144, v243, v64
	v_dot4c_i32_i8_e32 v143, v254, v64
	v_and_b32_e32 v58, s42, v58
	v_and_b32_e32 v22, s42, v22
	v_dot4c_i32_i8_e32 v144, v58, v65
	v_dot4c_i32_i8_e32 v143, v22, v65
	v_lshlrev_b32_e32 v243, 4, v59
	v_lshlrev_b32_e32 v254, 4, v23
	v_and_b32_e32 v243, s42, v243
	v_and_b32_e32 v254, s42, v254
	v_dot4c_i32_i8_e32 v144, v243, v66
	v_dot4c_i32_i8_e32 v143, v254, v66
	v_and_b32_e32 v59, s42, v59
	v_and_b32_e32 v23, s42, v23
	v_dot4c_i32_i8_e32 v144, v59, v67
	v_dot4c_i32_i8_e32 v143, v23, v67
	s_waitcnt lgkmcnt(0)
	v_add_u32_e32 v56, v72, v242
	v_add_u32_e32 v20, v73, v242
	global_load_dwordx4 v[56:59], v56, s[4:5]
	global_load_dwordx4 v[20:23], v20, s[4:5]
	s_waitcnt vmcnt(14)
	v_lshlrev_b32_e32 v243, 4, v60
	v_lshlrev_b32_e32 v254, 4, v24
	v_and_b32_e32 v243, s42, v243
	v_and_b32_e32 v254, s42, v254
	v_dot4c_i32_i8_e32 v142, v243, v68
	v_dot4c_i32_i8_e32 v141, v254, v68
	v_and_b32_e32 v60, s42, v60
	v_and_b32_e32 v24, s42, v24
	v_dot4c_i32_i8_e32 v142, v60, v69
	v_dot4c_i32_i8_e32 v141, v24, v69
	v_lshlrev_b32_e32 v243, 4, v61
	v_lshlrev_b32_e32 v254, 4, v25
	v_and_b32_e32 v243, s42, v243
	v_and_b32_e32 v254, s42, v254
	v_dot4c_i32_i8_e32 v142, v243, v70
	v_dot4c_i32_i8_e32 v141, v254, v70
	v_and_b32_e32 v61, s42, v61
	v_and_b32_e32 v25, s42, v25
	v_dot4c_i32_i8_e32 v142, v61, v71
	v_dot4c_i32_i8_e32 v141, v25, v71
	v_lshlrev_b32_e32 v243, 4, v62
	v_lshlrev_b32_e32 v254, 4, v26
	v_and_b32_e32 v243, s42, v243
	v_and_b32_e32 v254, s42, v254
	v_dot4c_i32_i8_e32 v142, v243, v64
	v_dot4c_i32_i8_e32 v141, v254, v64
	v_and_b32_e32 v62, s42, v62
	v_and_b32_e32 v26, s42, v26
	v_dot4c_i32_i8_e32 v142, v62, v65
	v_dot4c_i32_i8_e32 v141, v26, v65
	v_lshlrev_b32_e32 v243, 4, v63
	v_lshlrev_b32_e32 v254, 4, v27
	v_and_b32_e32 v243, s42, v243
	v_and_b32_e32 v254, s42, v254
	v_dot4c_i32_i8_e32 v142, v243, v66
	v_dot4c_i32_i8_e32 v141, v254, v66
	v_and_b32_e32 v63, s42, v63
	v_and_b32_e32 v27, s42, v27
	v_dot4c_i32_i8_e32 v142, v63, v67
	v_dot4c_i32_i8_e32 v141, v27, v67
	v_add_u32_e32 v60, v74, v242
	v_add_u32_e32 v24, v75, v242
	global_load_dwordx4 v[60:63], v60, s[4:5]
	global_load_dwordx4 v[24:27], v24, s[4:5]
	ds_read_b128 v[68:71], v241 offset:1536
	ds_read_b128 v[64:67], v241 offset:1552
	ds_read_b128 v[244:247], v238 offset:28672
	ds_read_b128 v[248:251], v238 offset:28688
	ds_read_b128 v[76:79], v238 offset:28704
	ds_read_b128 v[72:75], v238 offset:28720
	s_waitcnt vmcnt(14) lgkmcnt(4)
	v_lshlrev_b32_e32 v243, 4, v44
	v_lshlrev_b32_e32 v254, 4, v28
	v_and_b32_e32 v243, s42, v243
	v_and_b32_e32 v254, s42, v254
	v_dot4c_i32_i8_e32 v140, v243, v68
	v_dot4c_i32_i8_e32 v139, v254, v68
	v_and_b32_e32 v44, s42, v44
	v_and_b32_e32 v28, s42, v28
	v_dot4c_i32_i8_e32 v140, v44, v69
	v_dot4c_i32_i8_e32 v139, v28, v69
	v_lshlrev_b32_e32 v243, 4, v45
	v_lshlrev_b32_e32 v254, 4, v29
	v_and_b32_e32 v243, s42, v243
	v_and_b32_e32 v254, s42, v254
	v_dot4c_i32_i8_e32 v140, v243, v70
	v_dot4c_i32_i8_e32 v139, v254, v70
	v_and_b32_e32 v45, s42, v45
	v_and_b32_e32 v29, s42, v29
	v_dot4c_i32_i8_e32 v140, v45, v71
	v_dot4c_i32_i8_e32 v139, v29, v71
	v_lshlrev_b32_e32 v243, 4, v46
	v_lshlrev_b32_e32 v254, 4, v30
	v_and_b32_e32 v243, s42, v243
	v_and_b32_e32 v254, s42, v254
	v_dot4c_i32_i8_e32 v140, v243, v64
	v_dot4c_i32_i8_e32 v139, v254, v64
	v_and_b32_e32 v46, s42, v46
	v_and_b32_e32 v30, s42, v30
	v_dot4c_i32_i8_e32 v140, v46, v65
	v_dot4c_i32_i8_e32 v139, v30, v65
	v_lshlrev_b32_e32 v243, 4, v47
	v_lshlrev_b32_e32 v254, 4, v31
	v_and_b32_e32 v243, s42, v243
	v_and_b32_e32 v254, s42, v254
	v_dot4c_i32_i8_e32 v140, v243, v66
	v_dot4c_i32_i8_e32 v139, v254, v66
	v_and_b32_e32 v47, s42, v47
	v_and_b32_e32 v31, s42, v31
	v_dot4c_i32_i8_e32 v140, v47, v67
	v_dot4c_i32_i8_e32 v139, v31, v67
	s_waitcnt lgkmcnt(3)
	v_add_u32_e32 v44, v244, v242
	v_add_u32_e32 v28, v245, v242
	global_load_dwordx4 v[44:47], v44, s[4:5]
	global_load_dwordx4 v[28:31], v28, s[4:5]
	s_waitcnt vmcnt(14)
	v_lshlrev_b32_e32 v243, 4, v32
	v_lshlrev_b32_e32 v254, 4, v0
	v_and_b32_e32 v243, s42, v243
	v_and_b32_e32 v254, s42, v254
	v_dot4c_i32_i8_e32 v138, v243, v68
	v_dot4c_i32_i8_e32 v137, v254, v68
	v_and_b32_e32 v32, s42, v32
	v_and_b32_e32 v0, s42, v0
	v_dot4c_i32_i8_e32 v138, v32, v69
	v_dot4c_i32_i8_e32 v137, v0, v69
	v_lshlrev_b32_e32 v243, 4, v33
	v_lshlrev_b32_e32 v254, 4, v1
	v_and_b32_e32 v243, s42, v243
	v_and_b32_e32 v254, s42, v254
	v_dot4c_i32_i8_e32 v138, v243, v70
	v_dot4c_i32_i8_e32 v137, v254, v70
	v_and_b32_e32 v33, s42, v33
	v_and_b32_e32 v1, s42, v1
	v_dot4c_i32_i8_e32 v138, v33, v71
	v_dot4c_i32_i8_e32 v137, v1, v71
	v_lshlrev_b32_e32 v243, 4, v34
	v_lshlrev_b32_e32 v254, 4, v2
	v_and_b32_e32 v243, s42, v243
	v_and_b32_e32 v254, s42, v254
	v_dot4c_i32_i8_e32 v138, v243, v64
	v_dot4c_i32_i8_e32 v137, v254, v64
	v_and_b32_e32 v34, s42, v34
	v_and_b32_e32 v2, s42, v2
	v_dot4c_i32_i8_e32 v138, v34, v65
	v_dot4c_i32_i8_e32 v137, v2, v65
	v_lshlrev_b32_e32 v243, 4, v35
	v_lshlrev_b32_e32 v254, 4, v3
	v_and_b32_e32 v243, s42, v243
	v_and_b32_e32 v254, s42, v254
	v_dot4c_i32_i8_e32 v138, v243, v66
	v_dot4c_i32_i8_e32 v137, v254, v66
	v_and_b32_e32 v35, s42, v35
	v_and_b32_e32 v3, s42, v3
	v_dot4c_i32_i8_e32 v138, v35, v67
	v_dot4c_i32_i8_e32 v137, v3, v67
	v_add_u32_e32 v32, v246, v242
	v_add_u32_e32 v0, v247, v242
	global_load_dwordx4 v[32:35], v32, s[4:5]
	global_load_dwordx4 v[0:3], v0, s[4:5]
	s_waitcnt vmcnt(14)
; __device__ __forceinline__ void p8_peer_gather(Frame& F) {
;     ...
;                 const v4u xr0 = *(const v4u*)(xs_w + q * 256 + 32 * sub), xr1 = *(const v4u*)(xs_w + q * 256 + 32 * sub + 16);
;                 const int xg[8] = {(int)xr0.x, (int)xr0.y, (int)xr0.z, (int)xr0.w, (int)xr1.x, (int)xr1.y, (int)xr1.z, (int)xr1.w};
; #pragma unroll
;                 for (int i = 0; i < 16; ++i) { int a = acc[q][i];
; #pragma unroll
;                     for (int g = 0; g < 4; ++g) { const unsigned w = d[i][g];
;                         a = __builtin_amdgcn_sdot4((int)((w << 4) & 0xf0f0f0f0u), xg[2 * g], a, false);
;                         a = __builtin_amdgcn_sdot4((int)(w & 0xf0f0f0f0u), xg[2 * g + 1], a, false); }
;                     acc[q][i] = a;
;                     d[i] = *(const v4u*)(UQ + (size_t)(idx_s[nj * 128 + pg * 16 + i] + noff)); }
	v_lshlrev_b32_e32 v243, 4, v36
	v_lshlrev_b32_e32 v254, 4, v4
	v_and_b32_e32 v243, s42, v243
	v_and_b32_e32 v254, s42, v254
	v_dot4c_i32_i8_e32 v136, v243, v68
	v_dot4c_i32_i8_e32 v135, v254, v68
	v_and_b32_e32 v36, s42, v36
	v_and_b32_e32 v4, s42, v4
	v_dot4c_i32_i8_e32 v136, v36, v69
	v_dot4c_i32_i8_e32 v135, v4, v69
	v_lshlrev_b32_e32 v243, 4, v37
	v_lshlrev_b32_e32 v254, 4, v5
	v_and_b32_e32 v243, s42, v243
	v_and_b32_e32 v254, s42, v254
	v_dot4c_i32_i8_e32 v136, v243, v70
	v_dot4c_i32_i8_e32 v135, v254, v70
	v_and_b32_e32 v37, s42, v37
	v_and_b32_e32 v5, s42, v5
	v_dot4c_i32_i8_e32 v136, v37, v71
	v_dot4c_i32_i8_e32 v135, v5, v71
	v_lshlrev_b32_e32 v243, 4, v38
	v_lshlrev_b32_e32 v254, 4, v6
	v_and_b32_e32 v243, s42, v243
	v_and_b32_e32 v254, s42, v254
	v_dot4c_i32_i8_e32 v136, v243, v64
	v_dot4c_i32_i8_e32 v135, v254, v64
	v_and_b32_e32 v38, s42, v38
	v_and_b32_e32 v6, s42, v6
	v_dot4c_i32_i8_e32 v136, v38, v65
	v_dot4c_i32_i8_e32 v135, v6, v65
	v_lshlrev_b32_e32 v243, 4, v39
	v_lshlrev_b32_e32 v254, 4, v7
	v_and_b32_e32 v243, s42, v243
	v_and_b32_e32 v254, s42, v254
	v_dot4c_i32_i8_e32 v136, v243, v66
	v_dot4c_i32_i8_e32 v135, v254, v66
	v_and_b32_e32 v39, s42, v39
	v_and_b32_e32 v7, s42, v7
	v_dot4c_i32_i8_e32 v136, v39, v67
	v_dot4c_i32_i8_e32 v135, v7, v67
	s_waitcnt lgkmcnt(2)
	v_add_u32_e32 v36, v248, v242
	v_add_u32_e32 v4, v249, v242
	global_load_dwordx4 v[36:39], v36, s[4:5]
	global_load_dwordx4 v[4:7], v4, s[4:5]
	s_waitcnt vmcnt(14)
	v_lshlrev_b32_e32 v243, 4, v40
	v_lshlrev_b32_e32 v254, 4, v8
	v_and_b32_e32 v243, s42, v243
	v_and_b32_e32 v254, s42, v254
	v_dot4c_i32_i8_e32 v134, v243, v68
	v_dot4c_i32_i8_e32 v133, v254, v68
	v_and_b32_e32 v40, s42, v40
	v_and_b32_e32 v8, s42, v8
	v_dot4c_i32_i8_e32 v134, v40, v69
	v_dot4c_i32_i8_e32 v133, v8, v69
	v_lshlrev_b32_e32 v243, 4, v41
	v_lshlrev_b32_e32 v254, 4, v9
	v_and_b32_e32 v243, s42, v243
	v_and_b32_e32 v254, s42, v254
	v_dot4c_i32_i8_e32 v134, v243, v70
	v_dot4c_i32_i8_e32 v133, v254, v70
	v_and_b32_e32 v41, s42, v41
	v_and_b32_e32 v9, s42, v9
	v_dot4c_i32_i8_e32 v134, v41, v71
	v_dot4c_i32_i8_e32 v133, v9, v71
	v_lshlrev_b32_e32 v243, 4, v42
	v_lshlrev_b32_e32 v254, 4, v10
	v_and_b32_e32 v243, s42, v243
	v_and_b32_e32 v254, s42, v254
	v_dot4c_i32_i8_e32 v134, v243, v64
	v_dot4c_i32_i8_e32 v133, v254, v64
	v_and_b32_e32 v42, s42, v42
	v_and_b32_e32 v10, s42, v10
	v_dot4c_i32_i8_e32 v134, v42, v65
	v_dot4c_i32_i8_e32 v133, v10, v65
	v_lshlrev_b32_e32 v243, 4, v43
	v_lshlrev_b32_e32 v254, 4, v11
	v_and_b32_e32 v243, s42, v243
	v_and_b32_e32 v254, s42, v254
	v_dot4c_i32_i8_e32 v134, v243, v66
	v_dot4c_i32_i8_e32 v133, v254, v66
	v_and_b32_e32 v43, s42, v43
	v_and_b32_e32 v11, s42, v11
	v_dot4c_i32_i8_e32 v134, v43, v67
	v_dot4c_i32_i8_e32 v133, v11, v67
	v_add_u32_e32 v40, v250, v242
	v_add_u32_e32 v8, v251, v242
	global_load_dwordx4 v[40:43], v40, s[4:5]
	global_load_dwordx4 v[8:11], v8, s[4:5]
	s_waitcnt vmcnt(14)
	v_lshlrev_b32_e32 v243, 4, v48
	v_lshlrev_b32_e32 v254, 4, v12
	v_and_b32_e32 v243, s42, v243
	v_and_b32_e32 v254, s42, v254
	v_dot4c_i32_i8_e32 v132, v243, v68
	v_dot4c_i32_i8_e32 v131, v254, v68
	v_and_b32_e32 v48, s42, v48
	v_and_b32_e32 v12, s42, v12
	v_dot4c_i32_i8_e32 v132, v48, v69
	v_dot4c_i32_i8_e32 v131, v12, v69
	v_lshlrev_b32_e32 v243, 4, v49
	v_lshlrev_b32_e32 v254, 4, v13
	v_and_b32_e32 v243, s42, v243
	v_and_b32_e32 v254, s42, v254
	v_dot4c_i32_i8_e32 v132, v243, v70
	v_dot4c_i32_i8_e32 v131, v254, v70
	v_and_b32_e32 v49, s42, v49
	v_and_b32_e32 v13, s42, v13
	v_dot4c_i32_i8_e32 v132, v49, v71
	v_dot4c_i32_i8_e32 v131, v13, v71
	v_lshlrev_b32_e32 v243, 4, v50
	v_lshlrev_b32_e32 v254, 4, v14
	v_and_b32_e32 v243, s42, v243
	v_and_b32_e32 v254, s42, v254
	v_dot4c_i32_i8_e32 v132, v243, v64
	v_dot4c_i32_i8_e32 v131, v254, v64
	v_and_b32_e32 v50, s42, v50
	v_and_b32_e32 v14, s42, v14
	v_dot4c_i32_i8_e32 v132, v50, v65
	v_dot4c_i32_i8_e32 v131, v14, v65
	v_lshlrev_b32_e32 v243, 4, v51
	v_lshlrev_b32_e32 v254, 4, v15
	v_and_b32_e32 v243, s42, v243
	v_and_b32_e32 v254, s42, v254
	v_dot4c_i32_i8_e32 v132, v243, v66
	v_dot4c_i32_i8_e32 v131, v254, v66
	v_and_b32_e32 v51, s42, v51
	v_and_b32_e32 v15, s42, v15
	v_dot4c_i32_i8_e32 v132, v51, v67
	v_dot4c_i32_i8_e32 v131, v15, v67
	s_waitcnt lgkmcnt(1)
	v_add_u32_e32 v48, v76, v242
	v_add_u32_e32 v12, v77, v242
	global_load_dwordx4 v[48:51], v48, s[4:5]
	global_load_dwordx4 v[12:15], v12, s[4:5]
	s_waitcnt vmcnt(14)
	v_lshlrev_b32_e32 v243, 4, v52
	v_lshlrev_b32_e32 v254, 4, v16
	v_and_b32_e32 v243, s42, v243
	v_and_b32_e32 v254, s42, v254
	v_dot4c_i32_i8_e32 v130, v243, v68
	v_dot4c_i32_i8_e32 v129, v254, v68
	v_and_b32_e32 v52, s42, v52
	v_and_b32_e32 v16, s42, v16
	v_dot4c_i32_i8_e32 v130, v52, v69
	v_dot4c_i32_i8_e32 v129, v16, v69
	v_lshlrev_b32_e32 v243, 4, v53
	v_lshlrev_b32_e32 v254, 4, v17
	v_and_b32_e32 v243, s42, v243
	v_and_b32_e32 v254, s42, v254
	v_dot4c_i32_i8_e32 v130, v243, v70
	v_dot4c_i32_i8_e32 v129, v254, v70
	v_and_b32_e32 v53, s42, v53
	v_and_b32_e32 v17, s42, v17
	v_dot4c_i32_i8_e32 v130, v53, v71
	v_dot4c_i32_i8_e32 v129, v17, v71
	v_lshlrev_b32_e32 v243, 4, v54
	v_lshlrev_b32_e32 v254, 4, v18
	v_and_b32_e32 v243, s42, v243
	v_and_b32_e32 v254, s42, v254
	v_dot4c_i32_i8_e32 v130, v243, v64
	v_dot4c_i32_i8_e32 v129, v254, v64
	v_and_b32_e32 v54, s42, v54
	v_and_b32_e32 v18, s42, v18
	v_dot4c_i32_i8_e32 v130, v54, v65
	v_dot4c_i32_i8_e32 v129, v18, v65
	v_lshlrev_b32_e32 v243, 4, v55
	v_lshlrev_b32_e32 v254, 4, v19
	v_and_b32_e32 v243, s42, v243
	v_and_b32_e32 v254, s42, v254
	v_dot4c_i32_i8_e32 v130, v243, v66
	v_dot4c_i32_i8_e32 v129, v254, v66
	v_and_b32_e32 v55, s42, v55
	v_and_b32_e32 v19, s42, v19
	v_dot4c_i32_i8_e32 v130, v55, v67
	v_dot4c_i32_i8_e32 v129, v19, v67
	v_add_u32_e32 v52, v78, v242
	v_add_u32_e32 v16, v79, v242
	global_load_dwordx4 v[52:55], v52, s[4:5]
	global_load_dwordx4 v[16:19], v16, s[4:5]
	s_waitcnt vmcnt(14)
; __device__ __forceinline__ void p8_peer_gather(Frame& F) {
;     ...
;         for (int q = 0; q < 9; ++q) { const int j = q < 8 ? wave + 8 * q : 64;
;             if (q < 8 ? (wave + 8 * q < 65) : ((s & 7) == wave)) {
;                 const bool v8 = (s & 7) == wave, nsame = (q < 7) || (q == 7 && v8), nlast = !nsame && !(s_ + 1 < 16 * NREP_U);
;                 const int nj = nsame ? (q + 1 < 8 ? wave + 8 * (q + 1) : 64) : (nlast ? j : wave);
;                 const unsigned noff = (nsame || nlast) ? uoff : ((s + 1) & 15) * 128 + sub * 16;
;                 const v4u xr0 = *(const v4u*)(xs_w + q * 256 + 32 * sub), xr1 = *(const v4u*)(xs_w + q * 256 + 32 * sub + 16);
;                 const int xg[8] = {(int)xr0.x, (int)xr0.y, (int)xr0.z, (int)xr0.w, (int)xr1.x, (int)xr1.y, (int)xr1.z, (int)xr1.w};
; #pragma unroll
;                 for (int i = 0; i < 16; ++i) { int a = acc[q][i];
; #pragma unroll
;                     for (int g = 0; g < 4; ++g) { const unsigned w = d[i][g];
;                         a = __builtin_amdgcn_sdot4((int)((w << 4) & 0xf0f0f0f0u), xg[2 * g], a, false);
;                         a = __builtin_amdgcn_sdot4((int)(w & 0xf0f0f0f0u), xg[2 * g + 1], a, false); }
;                     acc[q][i] = a;
;                     d[i] = *(const v4u*)(UQ + (size_t)(idx_s[nj * 128 + pg * 16 + i] + noff)); }
	v_lshlrev_b32_e32 v243, 4, v56
	v_lshlrev_b32_e32 v254, 4, v20
	v_and_b32_e32 v243, s42, v243
	v_and_b32_e32 v254, s42, v254
	v_dot4c_i32_i8_e32 v128, v243, v68
	v_dot4c_i32_i8_e32 v127, v254, v68
	v_and_b32_e32 v56, s42, v56
	v_and_b32_e32 v20, s42, v20
	v_dot4c_i32_i8_e32 v128, v56, v69
	v_dot4c_i32_i8_e32 v127, v20, v69
	v_lshlrev_b32_e32 v243, 4, v57
	v_lshlrev_b32_e32 v254, 4, v21
	v_and_b32_e32 v243, s42, v243
	v_and_b32_e32 v254, s42, v254
	v_dot4c_i32_i8_e32 v128, v243, v70
	v_dot4c_i32_i8_e32 v127, v254, v70
	v_and_b32_e32 v57, s42, v57
	v_and_b32_e32 v21, s42, v21
	v_dot4c_i32_i8_e32 v128, v57, v71
	v_dot4c_i32_i8_e32 v127, v21, v71
	v_lshlrev_b32_e32 v243, 4, v58
	v_lshlrev_b32_e32 v254, 4, v22
	v_and_b32_e32 v243, s42, v243
	v_and_b32_e32 v254, s42, v254
	v_dot4c_i32_i8_e32 v128, v243, v64
	v_dot4c_i32_i8_e32 v127, v254, v64
	v_and_b32_e32 v58, s42, v58
	v_and_b32_e32 v22, s42, v22
	v_dot4c_i32_i8_e32 v128, v58, v65
	v_dot4c_i32_i8_e32 v127, v22, v65
	v_lshlrev_b32_e32 v243, 4, v59
	v_lshlrev_b32_e32 v254, 4, v23
	v_and_b32_e32 v243, s42, v243
	v_and_b32_e32 v254, s42, v254
	v_dot4c_i32_i8_e32 v128, v243, v66
	v_dot4c_i32_i8_e32 v127, v254, v66
	v_and_b32_e32 v59, s42, v59
	v_and_b32_e32 v23, s42, v23
	v_dot4c_i32_i8_e32 v128, v59, v67
	v_dot4c_i32_i8_e32 v127, v23, v67
	s_waitcnt lgkmcnt(0)
	v_add_u32_e32 v56, v72, v242
	v_add_u32_e32 v20, v73, v242
	global_load_dwordx4 v[56:59], v56, s[4:5]
	global_load_dwordx4 v[20:23], v20, s[4:5]
	s_waitcnt vmcnt(14)
	v_lshlrev_b32_e32 v243, 4, v60
	v_lshlrev_b32_e32 v254, 4, v24
	v_and_b32_e32 v243, s42, v243
	v_and_b32_e32 v254, s42, v254
	v_dot4c_i32_i8_e32 v126, v243, v68
	v_dot4c_i32_i8_e32 v125, v254, v68
	v_and_b32_e32 v60, s42, v60
	v_and_b32_e32 v24, s42, v24
	v_dot4c_i32_i8_e32 v126, v60, v69
	v_dot4c_i32_i8_e32 v125, v24, v69
	v_lshlrev_b32_e32 v243, 4, v61
	v_lshlrev_b32_e32 v254, 4, v25
	v_and_b32_e32 v243, s42, v243
	v_and_b32_e32 v254, s42, v254
	v_dot4c_i32_i8_e32 v126, v243, v70
	v_dot4c_i32_i8_e32 v125, v254, v70
	v_and_b32_e32 v61, s42, v61
	v_and_b32_e32 v25, s42, v25
	v_dot4c_i32_i8_e32 v126, v61, v71
	v_dot4c_i32_i8_e32 v125, v25, v71
	v_lshlrev_b32_e32 v243, 4, v62
	v_lshlrev_b32_e32 v254, 4, v26
	v_and_b32_e32 v243, s42, v243
	v_and_b32_e32 v254, s42, v254
	v_dot4c_i32_i8_e32 v126, v243, v64
	v_dot4c_i32_i8_e32 v125, v254, v64
	v_and_b32_e32 v62, s42, v62
	v_and_b32_e32 v26, s42, v26
	v_dot4c_i32_i8_e32 v126, v62, v65
	v_dot4c_i32_i8_e32 v125, v26, v65
	v_lshlrev_b32_e32 v243, 4, v63
	v_lshlrev_b32_e32 v254, 4, v27
	v_and_b32_e32 v243, s42, v243
	v_and_b32_e32 v254, s42, v254
	v_dot4c_i32_i8_e32 v126, v243, v66
	v_dot4c_i32_i8_e32 v125, v254, v66
	v_and_b32_e32 v63, s42, v63
	v_and_b32_e32 v27, s42, v27
	v_dot4c_i32_i8_e32 v126, v63, v67
	v_dot4c_i32_i8_e32 v125, v27, v67
	v_add_u32_e32 v60, v74, v242
	v_add_u32_e32 v24, v75, v242
	global_load_dwordx4 v[60:63], v60, s[4:5]
	global_load_dwordx4 v[24:27], v24, s[4:5]
	s_and_b32 s2, s30, 7
	s_cmp_eq_u32 s2, s74
	s_cselect_b64 s[30:31], -1, 0
	s_add_i32 s6, s39, 0x80
	s_and_b32 s2, s6, 0x780
	ds_read_b128 v[68:71], v241 offset:1792
	ds_read_b128 v[64:67], v241 offset:1808
	s_or_b64 s[40:41], s[28:29], s[30:31]
	s_and_b64 s[40:41], s[40:41], exec
	s_cselect_b32 s3, s39, s2
	s_and_b64 s[40:41], exec, s[28:29]
	v_or_b32_e32 v242, s3, v93
	s_cselect_b32 s3, s36, s35
	s_and_b64 s[40:41], s[30:31], exec
	s_cselect_b32 s3, 0x2000, s3
	v_lshl_add_u32 v252, s3, 2, v94
	ds_read_b128 v[244:247], v252
	ds_read_b128 v[248:251], v252 offset:16
	ds_read_b128 v[76:79], v252 offset:32
	ds_read_b128 v[72:75], v252 offset:48
	s_waitcnt vmcnt(14) lgkmcnt(4)
	v_lshlrev_b32_e32 v243, 4, v44
	v_lshlrev_b32_e32 v254, 4, v28
	v_and_b32_e32 v243, s42, v243
	v_and_b32_e32 v254, s42, v254
	v_dot4c_i32_i8_e32 v124, v243, v68
	v_dot4c_i32_i8_e32 v123, v254, v68
	v_and_b32_e32 v44, s42, v44
	v_and_b32_e32 v28, s42, v28
	v_dot4c_i32_i8_e32 v124, v44, v69
	v_dot4c_i32_i8_e32 v123, v28, v69
	v_lshlrev_b32_e32 v243, 4, v45
	v_lshlrev_b32_e32 v254, 4, v29
	v_and_b32_e32 v243, s42, v243
	v_and_b32_e32 v254, s42, v254
	v_dot4c_i32_i8_e32 v124, v243, v70
	v_dot4c_i32_i8_e32 v123, v254, v70
	v_and_b32_e32 v45, s42, v45
	v_and_b32_e32 v29, s42, v29
	v_dot4c_i32_i8_e32 v124, v45, v71
	v_dot4c_i32_i8_e32 v123, v29, v71
	v_lshlrev_b32_e32 v243, 4, v46
	v_lshlrev_b32_e32 v254, 4, v30
	v_and_b32_e32 v243, s42, v243
	v_and_b32_e32 v254, s42, v254
	v_dot4c_i32_i8_e32 v124, v243, v64
	v_dot4c_i32_i8_e32 v123, v254, v64
	v_and_b32_e32 v46, s42, v46
	v_and_b32_e32 v30, s42, v30
	v_dot4c_i32_i8_e32 v124, v46, v65
	v_dot4c_i32_i8_e32 v123, v30, v65
	v_lshlrev_b32_e32 v243, 4, v47
	v_lshlrev_b32_e32 v254, 4, v31
	v_and_b32_e32 v243, s42, v243
	v_and_b32_e32 v254, s42, v254
	v_dot4c_i32_i8_e32 v124, v243, v66
	v_dot4c_i32_i8_e32 v123, v254, v66
	v_and_b32_e32 v47, s42, v47
	v_and_b32_e32 v31, s42, v31
	v_dot4c_i32_i8_e32 v124, v47, v67
	v_dot4c_i32_i8_e32 v123, v31, v67
	s_waitcnt lgkmcnt(3)
	v_add_u32_e32 v44, v244, v242
	v_add_u32_e32 v28, v245, v242
	global_load_dwordx4 v[44:47], v44, s[4:5]
	global_load_dwordx4 v[28:31], v28, s[4:5]
	s_waitcnt vmcnt(14)
; __device__ __forceinline__ void p8_peer_gather(Frame& F) {
;     ...
;                 const v4u xr0 = *(const v4u*)(xs_w + q * 256 + 32 * sub), xr1 = *(const v4u*)(xs_w + q * 256 + 32 * sub + 16);
;                 const int xg[8] = {(int)xr0.x, (int)xr0.y, (int)xr0.z, (int)xr0.w, (int)xr1.x, (int)xr1.y, (int)xr1.z, (int)xr1.w};
; #pragma unroll
;                 for (int i = 0; i < 16; ++i) { int a = acc[q][i];
; #pragma unroll
;                     for (int g = 0; g < 4; ++g) { const unsigned w = d[i][g];
;                         a = __builtin_amdgcn_sdot4((int)((w << 4) & 0xf0f0f0f0u), xg[2 * g], a, false);
;                         a = __builtin_amdgcn_sdot4((int)(w & 0xf0f0f0f0u), xg[2 * g + 1], a, false); }
;                     acc[q][i] = a;
;                     d[i] = *(const v4u*)(UQ + (size_t)(idx_s[nj * 128 + pg * 16 + i] + noff)); }
	v_lshlrev_b32_e32 v243, 4, v32
	v_lshlrev_b32_e32 v254, 4, v0
	v_and_b32_e32 v243, s42, v243
	v_and_b32_e32 v254, s42, v254
	v_dot4c_i32_i8_e32 v122, v243, v68
	v_dot4c_i32_i8_e32 v121, v254, v68
	v_and_b32_e32 v32, s42, v32
	v_and_b32_e32 v0, s42, v0
	v_dot4c_i32_i8_e32 v122, v32, v69
	v_dot4c_i32_i8_e32 v121, v0, v69
	v_lshlrev_b32_e32 v243, 4, v33
	v_lshlrev_b32_e32 v254, 4, v1
	v_and_b32_e32 v243, s42, v243
	v_and_b32_e32 v254, s42, v254
	v_dot4c_i32_i8_e32 v122, v243, v70
	v_dot4c_i32_i8_e32 v121, v254, v70
	v_and_b32_e32 v33, s42, v33
	v_and_b32_e32 v1, s42, v1
	v_dot4c_i32_i8_e32 v122, v33, v71
	v_dot4c_i32_i8_e32 v121, v1, v71
	v_lshlrev_b32_e32 v243, 4, v34
	v_lshlrev_b32_e32 v254, 4, v2
	v_and_b32_e32 v243, s42, v243
	v_and_b32_e32 v254, s42, v254
	v_dot4c_i32_i8_e32 v122, v243, v64
	v_dot4c_i32_i8_e32 v121, v254, v64
	v_and_b32_e32 v34, s42, v34
	v_and_b32_e32 v2, s42, v2
	v_dot4c_i32_i8_e32 v122, v34, v65
	v_dot4c_i32_i8_e32 v121, v2, v65
	v_lshlrev_b32_e32 v243, 4, v35
	v_lshlrev_b32_e32 v254, 4, v3
	v_and_b32_e32 v243, s42, v243
	v_and_b32_e32 v254, s42, v254
	v_dot4c_i32_i8_e32 v122, v243, v66
	v_dot4c_i32_i8_e32 v121, v254, v66
	v_and_b32_e32 v35, s42, v35
	v_and_b32_e32 v3, s42, v3
	v_dot4c_i32_i8_e32 v122, v35, v67
	v_dot4c_i32_i8_e32 v121, v3, v67
	v_add_u32_e32 v32, v246, v242
	v_add_u32_e32 v0, v247, v242
	global_load_dwordx4 v[32:35], v32, s[4:5]
	global_load_dwordx4 v[0:3], v0, s[4:5]
	s_waitcnt vmcnt(14)
	v_lshlrev_b32_e32 v243, 4, v36
	v_lshlrev_b32_e32 v254, 4, v4
	v_and_b32_e32 v243, s42, v243
	v_and_b32_e32 v254, s42, v254
	v_dot4c_i32_i8_e32 v120, v243, v68
	v_dot4c_i32_i8_e32 v119, v254, v68
	v_and_b32_e32 v36, s42, v36
	v_and_b32_e32 v4, s42, v4
	v_dot4c_i32_i8_e32 v120, v36, v69
	v_dot4c_i32_i8_e32 v119, v4, v69
	v_lshlrev_b32_e32 v243, 4, v37
	v_lshlrev_b32_e32 v254, 4, v5
	v_and_b32_e32 v243, s42, v243
	v_and_b32_e32 v254, s42, v254
	v_dot4c_i32_i8_e32 v120, v243, v70
	v_dot4c_i32_i8_e32 v119, v254, v70
	v_and_b32_e32 v37, s42, v37
	v_and_b32_e32 v5, s42, v5
	v_dot4c_i32_i8_e32 v120, v37, v71
	v_dot4c_i32_i8_e32 v119, v5, v71
	v_lshlrev_b32_e32 v243, 4, v38
	v_lshlrev_b32_e32 v254, 4, v6
	v_and_b32_e32 v243, s42, v243
	v_and_b32_e32 v254, s42, v254
	v_dot4c_i32_i8_e32 v120, v243, v64
	v_dot4c_i32_i8_e32 v119, v254, v64
	v_and_b32_e32 v38, s42, v38
	v_and_b32_e32 v6, s42, v6
	v_dot4c_i32_i8_e32 v120, v38, v65
	v_dot4c_i32_i8_e32 v119, v6, v65
	v_lshlrev_b32_e32 v243, 4, v39
	v_lshlrev_b32_e32 v254, 4, v7
	v_and_b32_e32 v243, s42, v243
	v_and_b32_e32 v254, s42, v254
	v_dot4c_i32_i8_e32 v120, v243, v66
	v_dot4c_i32_i8_e32 v119, v254, v66
	v_and_b32_e32 v39, s42, v39
	v_and_b32_e32 v7, s42, v7
	v_dot4c_i32_i8_e32 v120, v39, v67
	v_dot4c_i32_i8_e32 v119, v7, v67
	s_waitcnt lgkmcnt(2)
	v_add_u32_e32 v36, v248, v242
	v_add_u32_e32 v4, v249, v242
	global_load_dwordx4 v[36:39], v36, s[4:5]
	global_load_dwordx4 v[4:7], v4, s[4:5]
	s_waitcnt vmcnt(14)
	v_lshlrev_b32_e32 v243, 4, v40
	v_lshlrev_b32_e32 v254, 4, v8
	v_and_b32_e32 v243, s42, v243
	v_and_b32_e32 v254, s42, v254
	v_dot4c_i32_i8_e32 v118, v243, v68
	v_dot4c_i32_i8_e32 v117, v254, v68
	v_and_b32_e32 v40, s42, v40
	v_and_b32_e32 v8, s42, v8
	v_dot4c_i32_i8_e32 v118, v40, v69
	v_dot4c_i32_i8_e32 v117, v8, v69
	v_lshlrev_b32_e32 v243, 4, v41
	v_lshlrev_b32_e32 v254, 4, v9
	v_and_b32_e32 v243, s42, v243
	v_and_b32_e32 v254, s42, v254
	v_dot4c_i32_i8_e32 v118, v243, v70
	v_dot4c_i32_i8_e32 v117, v254, v70
	v_and_b32_e32 v41, s42, v41
	v_and_b32_e32 v9, s42, v9
	v_dot4c_i32_i8_e32 v118, v41, v71
	v_dot4c_i32_i8_e32 v117, v9, v71
	v_lshlrev_b32_e32 v243, 4, v42
	v_lshlrev_b32_e32 v254, 4, v10
	v_and_b32_e32 v243, s42, v243
	v_and_b32_e32 v254, s42, v254
	v_dot4c_i32_i8_e32 v118, v243, v64
	v_dot4c_i32_i8_e32 v117, v254, v64
	v_and_b32_e32 v42, s42, v42
	v_and_b32_e32 v10, s42, v10
	v_dot4c_i32_i8_e32 v118, v42, v65
	v_dot4c_i32_i8_e32 v117, v10, v65
	v_lshlrev_b32_e32 v243, 4, v43
	v_lshlrev_b32_e32 v254, 4, v11
	v_and_b32_e32 v243, s42, v243
	v_and_b32_e32 v254, s42, v254
	v_dot4c_i32_i8_e32 v118, v243, v66
	v_dot4c_i32_i8_e32 v117, v254, v66
	v_and_b32_e32 v43, s42, v43
	v_and_b32_e32 v11, s42, v11
	v_dot4c_i32_i8_e32 v118, v43, v67
	v_dot4c_i32_i8_e32 v117, v11, v67
	v_add_u32_e32 v40, v250, v242
	v_add_u32_e32 v8, v251, v242
	global_load_dwordx4 v[40:43], v40, s[4:5]
	global_load_dwordx4 v[8:11], v8, s[4:5]
	s_waitcnt vmcnt(14)
	v_lshlrev_b32_e32 v243, 4, v48
	v_lshlrev_b32_e32 v254, 4, v12
	v_and_b32_e32 v243, s42, v243
	v_and_b32_e32 v254, s42, v254
	v_dot4c_i32_i8_e32 v116, v243, v68
	v_dot4c_i32_i8_e32 v115, v254, v68
	v_and_b32_e32 v48, s42, v48
	v_and_b32_e32 v12, s42, v12
	v_dot4c_i32_i8_e32 v116, v48, v69
	v_dot4c_i32_i8_e32 v115, v12, v69
	v_lshlrev_b32_e32 v243, 4, v49
	v_lshlrev_b32_e32 v254, 4, v13
	v_and_b32_e32 v243, s42, v243
	v_and_b32_e32 v254, s42, v254
	v_dot4c_i32_i8_e32 v116, v243, v70
	v_dot4c_i32_i8_e32 v115, v254, v70
	v_and_b32_e32 v49, s42, v49
	v_and_b32_e32 v13, s42, v13
	v_dot4c_i32_i8_e32 v116, v49, v71
	v_dot4c_i32_i8_e32 v115, v13, v71
	v_lshlrev_b32_e32 v243, 4, v50
	v_lshlrev_b32_e32 v254, 4, v14
	v_and_b32_e32 v243, s42, v243
	v_and_b32_e32 v254, s42, v254
	v_dot4c_i32_i8_e32 v116, v243, v64
	v_dot4c_i32_i8_e32 v115, v254, v64
	v_and_b32_e32 v50, s42, v50
	v_and_b32_e32 v14, s42, v14
	v_dot4c_i32_i8_e32 v116, v50, v65
	v_dot4c_i32_i8_e32 v115, v14, v65
	v_lshlrev_b32_e32 v243, 4, v51
	v_lshlrev_b32_e32 v254, 4, v15
	v_and_b32_e32 v243, s42, v243
	v_and_b32_e32 v254, s42, v254
	v_dot4c_i32_i8_e32 v116, v243, v66
	v_dot4c_i32_i8_e32 v115, v254, v66
	v_and_b32_e32 v51, s42, v51
	v_and_b32_e32 v15, s42, v15
	v_dot4c_i32_i8_e32 v116, v51, v67
	v_dot4c_i32_i8_e32 v115, v15, v67
	s_waitcnt lgkmcnt(1)
; __device__ __forceinline__ void p8_peer_gather(Frame& F) {
;     ...
;         for (int q = 0; q < 9; ++q) { const int j = q < 8 ? wave + 8 * q : 64;
;             if (q < 8 ? (wave + 8 * q < 65) : ((s & 7) == wave)) {
;                 const bool v8 = (s & 7) == wave, nsame = (q < 7) || (q == 7 && v8), nlast = !nsame && !(s_ + 1 < 16 * NREP_U);
;                 const int nj = nsame ? (q + 1 < 8 ? wave + 8 * (q + 1) : 64) : (nlast ? j : wave);
;                 const unsigned noff = (nsame || nlast) ? uoff : ((s + 1) & 15) * 128 + sub * 16;
;                 const v4u xr0 = *(const v4u*)(xs_w + q * 256 + 32 * sub), xr1 = *(const v4u*)(xs_w + q * 256 + 32 * sub + 16);
;                 const int xg[8] = {(int)xr0.x, (int)xr0.y, (int)xr0.z, (int)xr0.w, (int)xr1.x, (int)xr1.y, (int)xr1.z, (int)xr1.w};
; #pragma unroll
;                 for (int i = 0; i < 16; ++i) { int a = acc[q][i];
; #pragma unroll
;                     for (int g = 0; g < 4; ++g) { const unsigned w = d[i][g];
;                         a = __builtin_amdgcn_sdot4((int)((w << 4) & 0xf0f0f0f0u), xg[2 * g], a, false);
;                         a = __builtin_amdgcn_sdot4((int)(w & 0xf0f0f0f0u), xg[2 * g + 1], a, false); }
;                     acc[q][i] = a;
;                     d[i] = *(const v4u*)(UQ + (size_t)(idx_s[nj * 128 + pg * 16 + i] + noff)); }
	v_add_u32_e32 v48, v76, v242
	v_add_u32_e32 v12, v77, v242
	global_load_dwordx4 v[48:51], v48, s[4:5]
	global_load_dwordx4 v[12:15], v12, s[4:5]
	s_waitcnt vmcnt(14)
	v_lshlrev_b32_e32 v243, 4, v52
	v_lshlrev_b32_e32 v254, 4, v16
	v_and_b32_e32 v243, s42, v243
	v_and_b32_e32 v254, s42, v254
	v_dot4c_i32_i8_e32 v114, v243, v68
	v_dot4c_i32_i8_e32 v113, v254, v68
	v_and_b32_e32 v52, s42, v52
	v_and_b32_e32 v16, s42, v16
	v_dot4c_i32_i8_e32 v114, v52, v69
	v_dot4c_i32_i8_e32 v113, v16, v69
	v_lshlrev_b32_e32 v243, 4, v53
	v_lshlrev_b32_e32 v254, 4, v17
	v_and_b32_e32 v243, s42, v243
	v_and_b32_e32 v254, s42, v254
	v_dot4c_i32_i8_e32 v114, v243, v70
	v_dot4c_i32_i8_e32 v113, v254, v70
	v_and_b32_e32 v53, s42, v53
	v_and_b32_e32 v17, s42, v17
	v_dot4c_i32_i8_e32 v114, v53, v71
	v_dot4c_i32_i8_e32 v113, v17, v71
	v_lshlrev_b32_e32 v243, 4, v54
	v_lshlrev_b32_e32 v254, 4, v18
	v_and_b32_e32 v243, s42, v243
	v_and_b32_e32 v254, s42, v254
	v_dot4c_i32_i8_e32 v114, v243, v64
	v_dot4c_i32_i8_e32 v113, v254, v64
	v_and_b32_e32 v54, s42, v54
	v_and_b32_e32 v18, s42, v18
	v_dot4c_i32_i8_e32 v114, v54, v65
	v_dot4c_i32_i8_e32 v113, v18, v65
	v_lshlrev_b32_e32 v243, 4, v55
	v_lshlrev_b32_e32 v254, 4, v19
	v_and_b32_e32 v243, s42, v243
	v_and_b32_e32 v254, s42, v254
	v_dot4c_i32_i8_e32 v114, v243, v66
	v_dot4c_i32_i8_e32 v113, v254, v66
	v_and_b32_e32 v55, s42, v55
	v_and_b32_e32 v19, s42, v19
	v_dot4c_i32_i8_e32 v114, v55, v67
	v_dot4c_i32_i8_e32 v113, v19, v67
	v_add_u32_e32 v52, v78, v242
	v_add_u32_e32 v16, v79, v242
	global_load_dwordx4 v[52:55], v52, s[4:5]
	global_load_dwordx4 v[16:19], v16, s[4:5]
	s_waitcnt vmcnt(14)
	v_lshlrev_b32_e32 v243, 4, v56
	v_lshlrev_b32_e32 v254, 4, v20
	v_and_b32_e32 v243, s42, v243
	v_and_b32_e32 v254, s42, v254
	v_dot4c_i32_i8_e32 v112, v243, v68
	v_dot4c_i32_i8_e32 v111, v254, v68
	v_and_b32_e32 v56, s42, v56
	v_and_b32_e32 v20, s42, v20
	v_dot4c_i32_i8_e32 v112, v56, v69
	v_dot4c_i32_i8_e32 v111, v20, v69
	v_lshlrev_b32_e32 v243, 4, v57
	v_lshlrev_b32_e32 v254, 4, v21
	v_and_b32_e32 v243, s42, v243
	v_and_b32_e32 v254, s42, v254
	v_dot4c_i32_i8_e32 v112, v243, v70
	v_dot4c_i32_i8_e32 v111, v254, v70
	v_and_b32_e32 v57, s42, v57
	v_and_b32_e32 v21, s42, v21
	v_dot4c_i32_i8_e32 v112, v57, v71
	v_dot4c_i32_i8_e32 v111, v21, v71
	v_lshlrev_b32_e32 v243, 4, v58
	v_lshlrev_b32_e32 v254, 4, v22
	v_and_b32_e32 v243, s42, v243
	v_and_b32_e32 v254, s42, v254
	v_dot4c_i32_i8_e32 v112, v243, v64
	v_dot4c_i32_i8_e32 v111, v254, v64
	v_and_b32_e32 v58, s42, v58
	v_and_b32_e32 v22, s42, v22
	v_dot4c_i32_i8_e32 v112, v58, v65
	v_dot4c_i32_i8_e32 v111, v22, v65
	v_lshlrev_b32_e32 v243, 4, v59
	v_lshlrev_b32_e32 v254, 4, v23
	v_and_b32_e32 v243, s42, v243
	v_and_b32_e32 v254, s42, v254
	v_dot4c_i32_i8_e32 v112, v243, v66
	v_dot4c_i32_i8_e32 v111, v254, v66
	v_and_b32_e32 v59, s42, v59
	v_and_b32_e32 v23, s42, v23
	v_dot4c_i32_i8_e32 v112, v59, v67
	v_dot4c_i32_i8_e32 v111, v23, v67
	s_waitcnt lgkmcnt(0)
	v_add_u32_e32 v56, v72, v242
	v_add_u32_e32 v20, v73, v242
	global_load_dwordx4 v[56:59], v56, s[4:5]
	global_load_dwordx4 v[20:23], v20, s[4:5]
	s_waitcnt vmcnt(14)
	v_lshlrev_b32_e32 v243, 4, v60
	v_lshlrev_b32_e32 v254, 4, v24
	v_and_b32_e32 v243, s42, v243
	v_and_b32_e32 v254, s42, v254
	v_dot4c_i32_i8_e32 v110, v243, v68
	v_dot4c_i32_i8_e32 v109, v254, v68
	v_and_b32_e32 v60, s42, v60
	v_and_b32_e32 v24, s42, v24
	v_dot4c_i32_i8_e32 v110, v60, v69
	v_dot4c_i32_i8_e32 v109, v24, v69
	v_lshlrev_b32_e32 v243, 4, v61
	v_lshlrev_b32_e32 v254, 4, v25
	v_and_b32_e32 v243, s42, v243
	v_and_b32_e32 v254, s42, v254
	v_dot4c_i32_i8_e32 v110, v243, v70
	v_dot4c_i32_i8_e32 v109, v254, v70
	v_and_b32_e32 v61, s42, v61
	v_and_b32_e32 v25, s42, v25
	v_dot4c_i32_i8_e32 v110, v61, v71
	v_dot4c_i32_i8_e32 v109, v25, v71
	v_lshlrev_b32_e32 v243, 4, v62
	v_lshlrev_b32_e32 v254, 4, v26
	v_and_b32_e32 v243, s42, v243
	v_and_b32_e32 v254, s42, v254
	v_dot4c_i32_i8_e32 v110, v243, v64
	v_dot4c_i32_i8_e32 v109, v254, v64
	v_and_b32_e32 v62, s42, v62
	v_and_b32_e32 v26, s42, v26
	v_dot4c_i32_i8_e32 v110, v62, v65
	v_dot4c_i32_i8_e32 v109, v26, v65
	v_lshlrev_b32_e32 v243, 4, v63
	v_lshlrev_b32_e32 v254, 4, v27
	v_and_b32_e32 v243, s42, v243
	v_and_b32_e32 v254, s42, v254
	v_dot4c_i32_i8_e32 v110, v243, v66
	v_dot4c_i32_i8_e32 v109, v254, v66
	v_and_b32_e32 v63, s42, v63
	v_and_b32_e32 v27, s42, v27
	v_dot4c_i32_i8_e32 v110, v63, v67
	v_dot4c_i32_i8_e32 v109, v27, v67
	v_add_u32_e32 v60, v74, v242
	v_add_u32_e32 v24, v75, v242
	global_load_dwordx4 v[60:63], v60, s[4:5]
	global_load_dwordx4 v[24:27], v24, s[4:5]
	s_andn2_b64 vcc, exec, s[30:31]
	s_cbranch_vccnz .Lu_skip8
; __device__ __forceinline__ void p8_peer_gather(Frame& F) {
;     ...
;         for (int q = 0; q < 9; ++q) { const int j = q < 8 ? wave + 8 * q : 64;
;             if (q < 8 ? (wave + 8 * q < 65) : ((s & 7) == wave)) {
;                 const bool v8 = (s & 7) == wave, nsame = (q < 7) || (q == 7 && v8), nlast = !nsame && !(s_ + 1 < 16 * NREP_U);
;                 const int nj = nsame ? (q + 1 < 8 ? wave + 8 * (q + 1) : 64) : (nlast ? j : wave);
;                 const unsigned noff = (nsame || nlast) ? uoff : ((s + 1) & 15) * 128 + sub * 16;
;                 const v4u xr0 = *(const v4u*)(xs_w + q * 256 + 32 * sub), xr1 = *(const v4u*)(xs_w + q * 256 + 32 * sub + 16);
;                 const int xg[8] = {(int)xr0.x, (int)xr0.y, (int)xr0.z, (int)xr0.w, (int)xr1.x, (int)xr1.y, (int)xr1.z, (int)xr1.w};
; #pragma unroll
;                 for (int i = 0; i < 16; ++i) { int a = acc[q][i];
; #pragma unroll
;                     for (int g = 0; g < 4; ++g) { const unsigned w = d[i][g];
;                         a = __builtin_amdgcn_sdot4((int)((w << 4) & 0xf0f0f0f0u), xg[2 * g], a, false);
;                         a = __builtin_amdgcn_sdot4((int)(w & 0xf0f0f0f0u), xg[2 * g + 1], a, false); }
;                     acc[q][i] = a;
;                     d[i] = *(const v4u*)(UQ + (size_t)(idx_s[nj * 128 + pg * 16 + i] + noff)); }
;             }
	ds_read_b128 v[68:71], v241 offset:2048
	ds_read_b128 v[64:67], v241 offset:2064
	s_and_b64 s[28:29], exec, s[28:29]
	s_cselect_b32 s2, 0x780, s2
	v_or_b32_e32 v242, s2, v93
	s_cselect_b32 s2, 0x2000, s35
	v_lshl_add_u32 v252, s2, 2, v94
	ds_read_b128 v[244:247], v252
	ds_read_b128 v[248:251], v252 offset:16
	ds_read_b128 v[76:79], v252 offset:32
	ds_read_b128 v[72:75], v252 offset:48
	s_waitcnt vmcnt(14) lgkmcnt(4)
	v_lshlrev_b32_e32 v243, 4, v44
	v_lshlrev_b32_e32 v254, 4, v28
	v_and_b32_e32 v243, s42, v243
	v_and_b32_e32 v254, s42, v254
	v_dot4c_i32_i8_e32 v108, v243, v68
	v_dot4c_i32_i8_e32 v107, v254, v68
	v_and_b32_e32 v44, s42, v44
	v_and_b32_e32 v28, s42, v28
	v_dot4c_i32_i8_e32 v108, v44, v69
	v_dot4c_i32_i8_e32 v107, v28, v69
	v_lshlrev_b32_e32 v243, 4, v45
	v_lshlrev_b32_e32 v254, 4, v29
	v_and_b32_e32 v243, s42, v243
	v_and_b32_e32 v254, s42, v254
	v_dot4c_i32_i8_e32 v108, v243, v70
	v_dot4c_i32_i8_e32 v107, v254, v70
	v_and_b32_e32 v45, s42, v45
	v_and_b32_e32 v29, s42, v29
	v_dot4c_i32_i8_e32 v108, v45, v71
	v_dot4c_i32_i8_e32 v107, v29, v71
	v_lshlrev_b32_e32 v243, 4, v46
	v_lshlrev_b32_e32 v254, 4, v30
	v_and_b32_e32 v243, s42, v243
	v_and_b32_e32 v254, s42, v254
	v_dot4c_i32_i8_e32 v108, v243, v64
	v_dot4c_i32_i8_e32 v107, v254, v64
	v_and_b32_e32 v46, s42, v46
	v_and_b32_e32 v30, s42, v30
	v_dot4c_i32_i8_e32 v108, v46, v65
	v_dot4c_i32_i8_e32 v107, v30, v65
	v_lshlrev_b32_e32 v243, 4, v47
	v_lshlrev_b32_e32 v254, 4, v31
	v_and_b32_e32 v243, s42, v243
	v_and_b32_e32 v254, s42, v254
	v_dot4c_i32_i8_e32 v108, v243, v66
	v_dot4c_i32_i8_e32 v107, v254, v66
	v_and_b32_e32 v47, s42, v47
	v_and_b32_e32 v31, s42, v31
	v_dot4c_i32_i8_e32 v108, v47, v67
	v_dot4c_i32_i8_e32 v107, v31, v67
	s_waitcnt lgkmcnt(3)
	v_add_u32_e32 v44, v244, v242
	v_add_u32_e32 v28, v245, v242
	global_load_dwordx4 v[44:47], v44, s[4:5]
	global_load_dwordx4 v[28:31], v28, s[4:5]
	s_waitcnt vmcnt(14)
	v_lshlrev_b32_e32 v243, 4, v32
	v_lshlrev_b32_e32 v254, 4, v0
	v_and_b32_e32 v243, s42, v243
	v_and_b32_e32 v254, s42, v254
	v_dot4c_i32_i8_e32 v106, v243, v68
	v_dot4c_i32_i8_e32 v105, v254, v68
	v_and_b32_e32 v32, s42, v32
	v_and_b32_e32 v0, s42, v0
	v_dot4c_i32_i8_e32 v106, v32, v69
	v_dot4c_i32_i8_e32 v105, v0, v69
	v_lshlrev_b32_e32 v243, 4, v33
	v_lshlrev_b32_e32 v254, 4, v1
	v_and_b32_e32 v243, s42, v243
	v_and_b32_e32 v254, s42, v254
	v_dot4c_i32_i8_e32 v106, v243, v70
	v_dot4c_i32_i8_e32 v105, v254, v70
	v_and_b32_e32 v33, s42, v33
	v_and_b32_e32 v1, s42, v1
	v_dot4c_i32_i8_e32 v106, v33, v71
	v_dot4c_i32_i8_e32 v105, v1, v71
	v_lshlrev_b32_e32 v243, 4, v34
	v_lshlrev_b32_e32 v254, 4, v2
	v_and_b32_e32 v243, s42, v243
	v_and_b32_e32 v254, s42, v254
	v_dot4c_i32_i8_e32 v106, v243, v64
	v_dot4c_i32_i8_e32 v105, v254, v64
	v_and_b32_e32 v34, s42, v34
	v_and_b32_e32 v2, s42, v2
	v_dot4c_i32_i8_e32 v106, v34, v65
	v_dot4c_i32_i8_e32 v105, v2, v65
	v_lshlrev_b32_e32 v243, 4, v35
	v_lshlrev_b32_e32 v254, 4, v3
	v_and_b32_e32 v243, s42, v243
	v_and_b32_e32 v254, s42, v254
	v_dot4c_i32_i8_e32 v106, v243, v66
	v_dot4c_i32_i8_e32 v105, v254, v66
	v_and_b32_e32 v35, s42, v35
	v_and_b32_e32 v3, s42, v3
	v_dot4c_i32_i8_e32 v106, v35, v67
	v_dot4c_i32_i8_e32 v105, v3, v67
	v_add_u32_e32 v32, v246, v242
	v_add_u32_e32 v0, v247, v242
	global_load_dwordx4 v[32:35], v32, s[4:5]
	global_load_dwordx4 v[0:3], v0, s[4:5]
	s_waitcnt vmcnt(14)
	v_lshlrev_b32_e32 v243, 4, v36
	v_lshlrev_b32_e32 v254, 4, v4
	v_and_b32_e32 v243, s42, v243
	v_and_b32_e32 v254, s42, v254
	v_dot4c_i32_i8_e32 v104, v243, v68
	v_dot4c_i32_i8_e32 v103, v254, v68
	v_and_b32_e32 v36, s42, v36
	v_and_b32_e32 v4, s42, v4
	v_dot4c_i32_i8_e32 v104, v36, v69
	v_dot4c_i32_i8_e32 v103, v4, v69
	v_lshlrev_b32_e32 v243, 4, v37
	v_lshlrev_b32_e32 v254, 4, v5
	v_and_b32_e32 v243, s42, v243
	v_and_b32_e32 v254, s42, v254
	v_dot4c_i32_i8_e32 v104, v243, v70
	v_dot4c_i32_i8_e32 v103, v254, v70
	v_and_b32_e32 v37, s42, v37
	v_and_b32_e32 v5, s42, v5
	v_dot4c_i32_i8_e32 v104, v37, v71
	v_dot4c_i32_i8_e32 v103, v5, v71
	v_lshlrev_b32_e32 v243, 4, v38
	v_lshlrev_b32_e32 v254, 4, v6
	v_and_b32_e32 v243, s42, v243
	v_and_b32_e32 v254, s42, v254
	v_dot4c_i32_i8_e32 v104, v243, v64
	v_dot4c_i32_i8_e32 v103, v254, v64
	v_and_b32_e32 v38, s42, v38
	v_and_b32_e32 v6, s42, v6
	v_dot4c_i32_i8_e32 v104, v38, v65
	v_dot4c_i32_i8_e32 v103, v6, v65
	v_lshlrev_b32_e32 v243, 4, v39
	v_lshlrev_b32_e32 v254, 4, v7
	v_and_b32_e32 v243, s42, v243
	v_and_b32_e32 v254, s42, v254
	v_dot4c_i32_i8_e32 v104, v243, v66
	v_dot4c_i32_i8_e32 v103, v254, v66
	v_and_b32_e32 v39, s42, v39
	v_and_b32_e32 v7, s42, v7
	v_dot4c_i32_i8_e32 v104, v39, v67
	v_dot4c_i32_i8_e32 v103, v7, v67
	s_waitcnt lgkmcnt(2)
	v_add_u32_e32 v36, v248, v242
	v_add_u32_e32 v4, v249, v242
	global_load_dwordx4 v[36:39], v36, s[4:5]
	global_load_dwordx4 v[4:7], v4, s[4:5]
	s_waitcnt vmcnt(14)
	v_lshlrev_b32_e32 v243, 4, v40
	v_lshlrev_b32_e32 v254, 4, v8
	v_and_b32_e32 v243, s42, v243
	v_and_b32_e32 v254, s42, v254
	v_dot4c_i32_i8_e32 v102, v243, v68
	v_dot4c_i32_i8_e32 v101, v254, v68
	v_and_b32_e32 v40, s42, v40
	v_and_b32_e32 v8, s42, v8
	v_dot4c_i32_i8_e32 v102, v40, v69
	v_dot4c_i32_i8_e32 v101, v8, v69
	v_lshlrev_b32_e32 v243, 4, v41
	v_lshlrev_b32_e32 v254, 4, v9
	v_and_b32_e32 v243, s42, v243
	v_and_b32_e32 v254, s42, v254
	v_dot4c_i32_i8_e32 v102, v243, v70
	v_dot4c_i32_i8_e32 v101, v254, v70
	v_and_b32_e32 v41, s42, v41
	v_and_b32_e32 v9, s42, v9
	v_dot4c_i32_i8_e32 v102, v41, v71
	v_dot4c_i32_i8_e32 v101, v9, v71
	v_lshlrev_b32_e32 v243, 4, v42
	v_lshlrev_b32_e32 v254, 4, v10
	v_and_b32_e32 v243, s42, v243
	v_and_b32_e32 v254, s42, v254
	v_dot4c_i32_i8_e32 v102, v243, v64
	v_dot4c_i32_i8_e32 v101, v254, v64
	v_and_b32_e32 v42, s42, v42
	v_and_b32_e32 v10, s42, v10
	v_dot4c_i32_i8_e32 v102, v42, v65
	v_dot4c_i32_i8_e32 v101, v10, v65
	v_lshlrev_b32_e32 v243, 4, v43
	v_lshlrev_b32_e32 v254, 4, v11
	v_and_b32_e32 v243, s42, v243
	v_and_b32_e32 v254, s42, v254
	v_dot4c_i32_i8_e32 v102, v243, v66
	v_dot4c_i32_i8_e32 v101, v254, v66
	v_and_b32_e32 v43, s42, v43
	v_and_b32_e32 v11, s42, v11
	v_dot4c_i32_i8_e32 v102, v43, v67
	v_dot4c_i32_i8_e32 v101, v11, v67
	v_add_u32_e32 v40, v250, v242
	v_add_u32_e32 v8, v251, v242
	global_load_dwordx4 v[40:43], v40, s[4:5]
	global_load_dwordx4 v[8:11], v8, s[4:5]
	s_waitcnt vmcnt(14)
; __device__ __forceinline__ void p8_peer_gather(Frame& F) {
;     ...
;         for (int q = 0; q < 9; ++q) { const int j = q < 8 ? wave + 8 * q : 64;
;             if (q < 8 ? (wave + 8 * q < 65) : ((s & 7) == wave)) {
;                 const bool v8 = (s & 7) == wave, nsame = (q < 7) || (q == 7 && v8), nlast = !nsame && !(s_ + 1 < 16 * NREP_U);
;                 const int nj = nsame ? (q + 1 < 8 ? wave + 8 * (q + 1) : 64) : (nlast ? j : wave);
;                 const unsigned noff = (nsame || nlast) ? uoff : ((s + 1) & 15) * 128 + sub * 16;
;                 const v4u xr0 = *(const v4u*)(xs_w + q * 256 + 32 * sub), xr1 = *(const v4u*)(xs_w + q * 256 + 32 * sub + 16);
;                 const int xg[8] = {(int)xr0.x, (int)xr0.y, (int)xr0.z, (int)xr0.w, (int)xr1.x, (int)xr1.y, (int)xr1.z, (int)xr1.w};
; #pragma unroll
;                 for (int i = 0; i < 16; ++i) { int a = acc[q][i];
; #pragma unroll
;                     for (int g = 0; g < 4; ++g) { const unsigned w = d[i][g];
;                         a = __builtin_amdgcn_sdot4((int)((w << 4) & 0xf0f0f0f0u), xg[2 * g], a, false);
;                         a = __builtin_amdgcn_sdot4((int)(w & 0xf0f0f0f0u), xg[2 * g + 1], a, false); }
;                     acc[q][i] = a;
;                     d[i] = *(const v4u*)(UQ + (size_t)(idx_s[nj * 128 + pg * 16 + i] + noff)); }
;             }
;         }
;     }
	v_lshlrev_b32_e32 v243, 4, v48
	v_lshlrev_b32_e32 v254, 4, v12
	v_and_b32_e32 v243, s42, v243
	v_and_b32_e32 v254, s42, v254
	v_dot4c_i32_i8_e32 v100, v243, v68
	v_dot4c_i32_i8_e32 v99, v254, v68
	v_and_b32_e32 v48, s42, v48
	v_and_b32_e32 v12, s42, v12
	v_dot4c_i32_i8_e32 v100, v48, v69
	v_dot4c_i32_i8_e32 v99, v12, v69
	v_lshlrev_b32_e32 v243, 4, v49
	v_lshlrev_b32_e32 v254, 4, v13
	v_and_b32_e32 v243, s42, v243
	v_and_b32_e32 v254, s42, v254
	v_dot4c_i32_i8_e32 v100, v243, v70
	v_dot4c_i32_i8_e32 v99, v254, v70
	v_and_b32_e32 v49, s42, v49
	v_and_b32_e32 v13, s42, v13
	v_dot4c_i32_i8_e32 v100, v49, v71
	v_dot4c_i32_i8_e32 v99, v13, v71
	v_lshlrev_b32_e32 v243, 4, v50
	v_lshlrev_b32_e32 v254, 4, v14
	v_and_b32_e32 v243, s42, v243
	v_and_b32_e32 v254, s42, v254
	v_dot4c_i32_i8_e32 v100, v243, v64
	v_dot4c_i32_i8_e32 v99, v254, v64
	v_and_b32_e32 v50, s42, v50
	v_and_b32_e32 v14, s42, v14
	v_dot4c_i32_i8_e32 v100, v50, v65
	v_dot4c_i32_i8_e32 v99, v14, v65
	v_lshlrev_b32_e32 v243, 4, v51
	v_lshlrev_b32_e32 v254, 4, v15
	v_and_b32_e32 v243, s42, v243
	v_and_b32_e32 v254, s42, v254
	v_dot4c_i32_i8_e32 v100, v243, v66
	v_dot4c_i32_i8_e32 v99, v254, v66
	v_and_b32_e32 v51, s42, v51
	v_and_b32_e32 v15, s42, v15
	v_dot4c_i32_i8_e32 v100, v51, v67
	v_dot4c_i32_i8_e32 v99, v15, v67
	s_waitcnt lgkmcnt(1)
	v_add_u32_e32 v48, v76, v242
	v_add_u32_e32 v12, v77, v242
	global_load_dwordx4 v[48:51], v48, s[4:5]
	global_load_dwordx4 v[12:15], v12, s[4:5]
	s_waitcnt vmcnt(14)
	v_lshlrev_b32_e32 v243, 4, v52
	v_lshlrev_b32_e32 v254, 4, v16
	v_and_b32_e32 v243, s42, v243
	v_and_b32_e32 v254, s42, v254
	v_dot4c_i32_i8_e32 v98, v243, v68
	v_dot4c_i32_i8_e32 v97, v254, v68
	v_and_b32_e32 v52, s42, v52
	v_and_b32_e32 v16, s42, v16
	v_dot4c_i32_i8_e32 v98, v52, v69
	v_dot4c_i32_i8_e32 v97, v16, v69
	v_lshlrev_b32_e32 v243, 4, v53
	v_lshlrev_b32_e32 v254, 4, v17
	v_and_b32_e32 v243, s42, v243
	v_and_b32_e32 v254, s42, v254
	v_dot4c_i32_i8_e32 v98, v243, v70
	v_dot4c_i32_i8_e32 v97, v254, v70
	v_and_b32_e32 v53, s42, v53
	v_and_b32_e32 v17, s42, v17
	v_dot4c_i32_i8_e32 v98, v53, v71
	v_dot4c_i32_i8_e32 v97, v17, v71
	v_lshlrev_b32_e32 v243, 4, v54
	v_lshlrev_b32_e32 v254, 4, v18
	v_and_b32_e32 v243, s42, v243
	v_and_b32_e32 v254, s42, v254
	v_dot4c_i32_i8_e32 v98, v243, v64
	v_dot4c_i32_i8_e32 v97, v254, v64
	v_and_b32_e32 v54, s42, v54
	v_and_b32_e32 v18, s42, v18
	v_dot4c_i32_i8_e32 v98, v54, v65
	v_dot4c_i32_i8_e32 v97, v18, v65
	v_lshlrev_b32_e32 v243, 4, v55
	v_lshlrev_b32_e32 v254, 4, v19
	v_and_b32_e32 v243, s42, v243
	v_and_b32_e32 v254, s42, v254
	v_dot4c_i32_i8_e32 v98, v243, v66
	v_dot4c_i32_i8_e32 v97, v254, v66
	v_and_b32_e32 v55, s42, v55
	v_and_b32_e32 v19, s42, v19
	v_dot4c_i32_i8_e32 v98, v55, v67
	v_dot4c_i32_i8_e32 v97, v19, v67
	v_add_u32_e32 v52, v78, v242
	v_add_u32_e32 v16, v79, v242
	global_load_dwordx4 v[52:55], v52, s[4:5]
	global_load_dwordx4 v[16:19], v16, s[4:5]
	s_waitcnt vmcnt(14)
	v_lshlrev_b32_e32 v243, 4, v56
	v_lshlrev_b32_e32 v254, 4, v20
	v_and_b32_e32 v243, s42, v243
	v_and_b32_e32 v254, s42, v254
	v_dot4c_i32_i8_e32 v96, v243, v68
	v_dot4c_i32_i8_e32 v95, v254, v68
	v_and_b32_e32 v56, s42, v56
	v_and_b32_e32 v20, s42, v20
	v_dot4c_i32_i8_e32 v96, v56, v69
	v_dot4c_i32_i8_e32 v95, v20, v69
	v_lshlrev_b32_e32 v243, 4, v57
	v_lshlrev_b32_e32 v254, 4, v21
	v_and_b32_e32 v243, s42, v243
	v_and_b32_e32 v254, s42, v254
	v_dot4c_i32_i8_e32 v96, v243, v70
	v_dot4c_i32_i8_e32 v95, v254, v70
	v_and_b32_e32 v57, s42, v57
	v_and_b32_e32 v21, s42, v21
	v_dot4c_i32_i8_e32 v96, v57, v71
	v_dot4c_i32_i8_e32 v95, v21, v71
	v_lshlrev_b32_e32 v243, 4, v58
	v_lshlrev_b32_e32 v254, 4, v22
	v_and_b32_e32 v243, s42, v243
	v_and_b32_e32 v254, s42, v254
	v_dot4c_i32_i8_e32 v96, v243, v64
	v_dot4c_i32_i8_e32 v95, v254, v64
	v_and_b32_e32 v58, s42, v58
	v_and_b32_e32 v22, s42, v22
	v_dot4c_i32_i8_e32 v96, v58, v65
	v_dot4c_i32_i8_e32 v95, v22, v65
	v_lshlrev_b32_e32 v243, 4, v59
	v_lshlrev_b32_e32 v254, 4, v23
	v_and_b32_e32 v243, s42, v243
	v_and_b32_e32 v254, s42, v254
	v_dot4c_i32_i8_e32 v96, v243, v66
	v_dot4c_i32_i8_e32 v95, v254, v66
	v_and_b32_e32 v59, s42, v59
	v_and_b32_e32 v23, s42, v23
	v_dot4c_i32_i8_e32 v96, v59, v67
	v_dot4c_i32_i8_e32 v95, v23, v67
	s_waitcnt lgkmcnt(0)
	v_add_u32_e32 v56, v72, v242
	v_add_u32_e32 v20, v73, v242
	global_load_dwordx4 v[56:59], v56, s[4:5]
	global_load_dwordx4 v[20:23], v20, s[4:5]
	s_waitcnt vmcnt(14)
	v_lshlrev_b32_e32 v243, 4, v60
	v_lshlrev_b32_e32 v254, 4, v24
	v_and_b32_e32 v243, s42, v243
	v_and_b32_e32 v254, s42, v254
	v_dot4c_i32_i8_e32 v91, v243, v68
	v_dot4c_i32_i8_e32 v81, v254, v68
	v_and_b32_e32 v60, s42, v60
	v_and_b32_e32 v24, s42, v24
	v_dot4c_i32_i8_e32 v91, v60, v69
	v_dot4c_i32_i8_e32 v81, v24, v69
	v_lshlrev_b32_e32 v243, 4, v61
	v_lshlrev_b32_e32 v254, 4, v25
	v_and_b32_e32 v243, s42, v243
	v_and_b32_e32 v254, s42, v254
	v_dot4c_i32_i8_e32 v91, v243, v70
	v_dot4c_i32_i8_e32 v81, v254, v70
	v_and_b32_e32 v61, s42, v61
	v_and_b32_e32 v25, s42, v25
	v_dot4c_i32_i8_e32 v91, v61, v71
	v_dot4c_i32_i8_e32 v81, v25, v71
	v_lshlrev_b32_e32 v243, 4, v62
	v_lshlrev_b32_e32 v254, 4, v26
	v_and_b32_e32 v243, s42, v243
	v_and_b32_e32 v254, s42, v254
	v_dot4c_i32_i8_e32 v91, v243, v64
	v_dot4c_i32_i8_e32 v81, v254, v64
	v_and_b32_e32 v62, s42, v62
	v_and_b32_e32 v26, s42, v26
	v_dot4c_i32_i8_e32 v91, v62, v65
	v_dot4c_i32_i8_e32 v81, v26, v65
	v_lshlrev_b32_e32 v243, 4, v63
	v_lshlrev_b32_e32 v254, 4, v27
	v_and_b32_e32 v243, s42, v243
	v_and_b32_e32 v254, s42, v254
	v_dot4c_i32_i8_e32 v91, v243, v66
	v_dot4c_i32_i8_e32 v81, v254, v66
	v_and_b32_e32 v63, s42, v63
	v_and_b32_e32 v27, s42, v27
	v_dot4c_i32_i8_e32 v91, v63, v67
	v_dot4c_i32_i8_e32 v81, v27, v67
	v_add_u32_e32 v60, v74, v242
	v_add_u32_e32 v24, v75, v242
	global_load_dwordx4 v[60:63], v60, s[4:5]
	global_load_dwordx4 v[24:27], v24, s[4:5]
.Lu_skip8:
	s_addk_i32 s37, 0x100
	s_cmpk_eq_i32 s6, 0x800
	s_cbranch_scc1 .LBB0_1775
	s_mov_b32 s39, s6
	s_mov_b32 s30, s38
	s_branch .Lu_loop
